# peeled first K-iteration: P1 counted wait relaxed to vmcnt(8+S) (S = epilogue stores, which are younger than the DMA pieces P1 guards) so the previous unit's store drain overlaps the first MFMA slot
# baseline (speedup 1.0000x reference)
;     __device__ bool next(int i, Unit& u) const { if (r0 + i >= r1) return false; return base.next(r0 + i, u); }
;     __device__ bool next(int i, Unit& u) const { const int L = i * G + c; if (L >= 256) return false; u.pm = L; u.pn = L >> 3; return true; }
; #define PG8_STAGE(bufoff, gbase, voff) do { _Pragma("unroll") for (int _i = 0; _i < 2; ++_i) \
;         __builtin_amdgcn_global_load_lds((const unsigned*)((const char*)(gbase) + (voff)[_i]), (LAS unsigned*)(lds + (bufoff) + ldsw + _i * 8192), 16, 0, 0); } while (0)
; #define PG8_LDA(dst, b, h) do { _Pragma("unroll") for (int m = 0; m < 4; ++m) _Pragma("unroll") for (int k = 0; k < 2; ++k) dst[m][k] = *(const LAS bf16x8*)(lds + PG8_SA(b, h) + aoff + m * 2048 + k * 1024); } while (0)
; #define PG8_LDB(dst, b, h) do { _Pragma("unroll") for (int n = 0; n < 2; ++n) _Pragma("unroll") for (int k = 0; k < 2; ++k) dst[n][k] = *(const LAS bf16x8*)(lds + PG8_SB(b, h) + boff + n * 2048 + k * 1024); } while (0)
; #define PG8_WAIT_V(n) asm volatile("s_waitcnt vmcnt(" #n ")" ::: "memory")
; #define PG8_WAIT_L(n) asm volatile("s_waitcnt lgkmcnt(" #n ")" ::: "memory")
; template <class Epi, class Sched>
; __device__ __forceinline__ void gemm_phase(LAS unsigned char* lds, const Gemm g, const Sched& S, const Epi& E, int wave_id) {
;     ...
;         const bool has_next = S.next(ui + 1, nxt);
;         const char* nA = has_next ? (const char*)g.A + (size_t)nxt.pm * tstepA : cA; const char* nB = has_next ? (const char*)g.Bt + (size_t)nxt.pn * tstepB : cB;
;         for (int t = 0; t < nt; t += 2) {
;             const bool last = (t == nt - 2);
;             const char* a1 = cA + (size_t)(t + 1) * kstep;
;             const char* a2 = last ? nA : cA + (size_t)(t + 2) * kstep; const char* b2 = last ? nB : cB + (size_t)(t + 2) * kstep;
;             const char* a3 = a2 + kstep; const char* b3 = b2 + kstep;
;             PG8_LDB(B0, 0, 0); PG8_LDB(B1, 0, 1); PG8_SCHED; PG8_LDA(At, 0, 0); PG8_STAGE(PG8_SA(1, 1), a1 + hstepA, voffA);
;             PG8_WAIT_V(8); PG8_WAIT_L(0); PG8_BAR; PG8_MMA(0, 0, At, B0); PG8_MMA(0, 1, At, B1); PG8_BAR; PG8_SCHED;
;             PG8_LDA(At, 0, 1); PG8_STAGE(PG8_SB(0, 0), b2, voffB); PG8_STAGE(PG8_SB(0, 1), b2 + hstepB, voffB); PG8_STAGE(PG8_SA(0, 0), a2, voffA);
;             PG8_WAIT_V(8); PG8_WAIT_L(0); PG8_BAR; PG8_MMA(1, 0, At, B0); PG8_MMA(1, 1, At, B1); PG8_BAR; PG8_SCHED;
.LBB0_251:
	s_ashr_i32 s45, s44, 31
	s_lshl_b64 s[14:15], s[44:45], 19
	s_add_u32 s46, s52, s14
	s_addc_u32 s47, s53, s15
	s_and_b64 s[14:15], s[4:5], exec
	s_cselect_b32 s2, s47, s11
	s_cselect_b32 s7, s46, s10
	s_ashr_i32 s39, s38, 31
	s_lshl_b64 s[14:15], s[38:39], 19
	s_add_u32 s48, s92, s14
	s_addc_u32 s49, s93, s15
	s_and_b64 s[14:15], s[4:5], exec
	s_cselect_b32 s9, s49, s13
	s_cselect_b32 s18, s48, s12
	s_add_u32 s10, s10, 0x40080
	s_addc_u32 s11, s11, 0
	s_add_u32 s33, s12, 0x100
	s_addc_u32 s39, s13, 0
	s_mov_b32 s45, -2
	ds_read_b128 v[16:19], v183
	ds_read_b128 v[20:23], v183 offset:1024
	ds_read_b128 v[32:35], v183 offset:2048
	ds_read_b128 v[36:39], v183 offset:3072
	ds_read_b128 v[184:187], v190
	ds_read_b128 v[194:197], v190 offset:1024
	ds_read_b128 v[198:201], v190 offset:2048
	ds_read_b128 v[202:205], v190 offset:3072
	s_add_u32 s12, s10, 0xfffc0080
	s_addc_u32 s13, s11, -1
	s_cmp_eq_u32 s45, 12
	s_cselect_b32 s15, s2, s13
	s_cselect_b32 s14, s7, s12
	s_cselect_b32 s13, s9, s39
	s_cselect_b32 s12, s18, s33
	v_lshl_add_u64 v[168:169], s[10:11], 0, v[158:159]
	s_add_i32 m0, s55, 0xc000
	ds_read_b128 v[206:209], v191
	ds_read_b128 v[210:213], v191 offset:1024
	ds_read_b128 v[214:217], v191 offset:2048
	ds_read_b128 v[218:221], v191 offset:3072
	ds_read_b128 v[222:225], v191 offset:4096
	ds_read_b128 v[226:229], v191 offset:5120
	ds_read_b128 v[230:233], v191 offset:6144
	ds_read_b128 v[234:237], v191 offset:7168
	global_load_lds_dwordx4 v[168:169], off
	v_lshl_add_u64 v[168:169], s[10:11], 0, v[160:161]
	s_add_i32 m0, s55, 0xe000
	s_nop 0
	global_load_lds_dwordx4 v[168:169], off
	s_waitcnt vmcnt(24)
	s_waitcnt lgkmcnt(0)
	s_barrier
	s_setprio 1
	s_waitcnt lgkmcnt(0)
	v_mfma_f32_16x16x32_bf16 v[140:143], v[16:19], v[206:209], 0
	v_mfma_f32_16x16x32_bf16 v[136:139], v[32:35], v[206:209], 0
	v_mfma_f32_16x16x32_bf16 v[124:127], v[16:19], v[214:217], 0
	v_mfma_f32_16x16x32_bf16 v[120:123], v[32:35], v[214:217], 0
	v_mfma_f32_16x16x32_bf16 v[108:111], v[16:19], v[222:225], 0
	v_mfma_f32_16x16x32_bf16 v[104:107], v[32:35], v[222:225], 0
	v_mfma_f32_16x16x32_bf16 v[92:95], v[16:19], v[230:233], 0
	v_mfma_f32_16x16x32_bf16 v[88:91], v[32:35], v[230:233], 0
	v_mfma_f32_16x16x32_bf16 v[140:143], v[20:23], v[210:213], v[140:143]
	v_mfma_f32_16x16x32_bf16 v[136:139], v[36:39], v[210:213], v[136:139]
	v_mfma_f32_16x16x32_bf16 v[124:127], v[20:23], v[218:221], v[124:127]
	v_mfma_f32_16x16x32_bf16 v[120:123], v[36:39], v[218:221], v[120:123]
	v_mfma_f32_16x16x32_bf16 v[108:111], v[20:23], v[226:229], v[108:111]
	v_mfma_f32_16x16x32_bf16 v[104:107], v[36:39], v[226:229], v[104:107]
	v_mfma_f32_16x16x32_bf16 v[92:95], v[20:23], v[234:237], v[92:95]
	v_mfma_f32_16x16x32_bf16 v[88:91], v[36:39], v[234:237], v[88:91]
	s_setprio 0
	s_setprio 1
	v_mfma_f32_16x16x32_bf16 v[132:135], v[184:187], v[206:209], 0
	v_mfma_f32_16x16x32_bf16 v[128:131], v[198:201], v[206:209], 0
	v_mfma_f32_16x16x32_bf16 v[116:119], v[184:187], v[214:217], 0
	v_mfma_f32_16x16x32_bf16 v[112:115], v[198:201], v[214:217], 0
	v_mfma_f32_16x16x32_bf16 v[100:103], v[184:187], v[222:225], 0
	v_mfma_f32_16x16x32_bf16 v[96:99], v[198:201], v[222:225], 0
	v_mfma_f32_16x16x32_bf16 v[84:87], v[184:187], v[230:233], 0
	v_mfma_f32_16x16x32_bf16 v[80:83], v[198:201], v[230:233], 0
	v_mfma_f32_16x16x32_bf16 v[132:135], v[194:197], v[210:213], v[132:135]
	v_mfma_f32_16x16x32_bf16 v[128:131], v[202:205], v[210:213], v[128:131]
	v_mfma_f32_16x16x32_bf16 v[116:119], v[194:197], v[218:221], v[116:119]
	v_mfma_f32_16x16x32_bf16 v[112:115], v[202:205], v[218:221], v[112:115]
	v_mfma_f32_16x16x32_bf16 v[100:103], v[194:197], v[226:229], v[100:103]
	v_mfma_f32_16x16x32_bf16 v[96:99], v[202:205], v[226:229], v[96:99]
	v_mfma_f32_16x16x32_bf16 v[84:87], v[194:197], v[234:237], v[84:87]
	v_mfma_f32_16x16x32_bf16 v[80:83], v[202:205], v[234:237], v[80:83]
	s_setprio 0
	s_barrier
	s_add_i32 s50, s67, s54
	v_lshl_add_u64 v[168:169], s[12:13], 0, v[146:147]
	s_mov_b32 m0, s50
	ds_read_b128 v[206:209], v191 offset:16384
	ds_read_b128 v[210:213], v191 offset:17408
	ds_read_b128 v[214:217], v191 offset:18432
	ds_read_b128 v[218:221], v191 offset:19456
	ds_read_b128 v[222:225], v191 offset:20480
	ds_read_b128 v[226:229], v191 offset:21504
	ds_read_b128 v[230:233], v191 offset:22528
	ds_read_b128 v[234:237], v191 offset:23552
	global_load_lds_dwordx4 v[168:169], off
	s_add_i32 m0, s50, 0x2000
	s_add_u32 s50, s12, 0x40000
	v_lshl_add_u64 v[188:189], s[12:13], 0, v[150:151]
	s_addc_u32 s51, s13, 0
	s_add_i32 s78, s72, s54
	global_load_lds_dwordx4 v[188:189], off
	v_lshl_add_u64 v[238:239], s[50:51], 0, v[146:147]
	s_mov_b32 m0, s78
	v_lshl_add_u64 v[240:241], s[14:15], 0, v[148:149]
	global_load_lds_dwordx4 v[238:239], off
	v_lshl_add_u64 v[238:239], s[50:51], 0, v[150:151]
	s_add_i32 m0, s78, 0x2000
	s_nop 0
	global_load_lds_dwordx4 v[238:239], off
	v_lshl_add_u64 v[238:239], s[14:15], 0, v[144:145]
	s_mov_b32 m0, s55
	s_nop 0
	global_load_lds_dwordx4 v[238:239], off
	s_mov_b32 m0, s58
	s_nop 0
	global_load_lds_dwordx4 v[240:241], off
	s_waitcnt vmcnt(8)
	s_waitcnt lgkmcnt(0)
	s_barrier
; #define PG8_STAGE(bufoff, gbase, voff) do { _Pragma("unroll") for (int _i = 0; _i < 2; ++_i) \
;         __builtin_amdgcn_global_load_lds((const unsigned*)((const char*)(gbase) + (voff)[_i]), (LAS unsigned*)(lds + (bufoff) + ldsw + _i * 8192), 16, 0, 0); } while (0)
; #define PG8_LDA(dst, b, h) do { _Pragma("unroll") for (int m = 0; m < 4; ++m) _Pragma("unroll") for (int k = 0; k < 2; ++k) dst[m][k] = *(const LAS bf16x8*)(lds + PG8_SA(b, h) + aoff + m * 2048 + k * 1024); } while (0)
; #define PG8_LDB(dst, b, h) do { _Pragma("unroll") for (int n = 0; n < 2; ++n) _Pragma("unroll") for (int k = 0; k < 2; ++k) dst[n][k] = *(const LAS bf16x8*)(lds + PG8_SB(b, h) + boff + n * 2048 + k * 1024); } while (0)
; #define PG8_MMA(ai, bj, At, Bt) do { __builtin_amdgcn_s_setprio(1); _Pragma("unroll") for (int m = 0; m < 4; ++m) _Pragma("unroll") for (int n = 0; n < 2; ++n) _Pragma("unroll") for (int k = 0; k < 2; ++k) \
;         acc[ai][bj][m][n] = __builtin_amdgcn_mfma_f32_16x16x32_bf16(Bt[n][k], At[m][k], acc[ai][bj][m][n], 0, 0, 0); __builtin_amdgcn_s_setprio(0); } while (0)
; #define PG8_WAIT_V(n) asm volatile("s_waitcnt vmcnt(" #n ")" ::: "memory")
; #define PG8_WAIT_L(n) asm volatile("s_waitcnt lgkmcnt(" #n ")" ::: "memory")
; #define PG8_BAR __builtin_amdgcn_s_barrier()
; #define PG8_SCHED __builtin_amdgcn_sched_barrier(0)
; template <class Epi, class Sched>
; __device__ __forceinline__ void gemm_phase(LAS unsigned char* lds, const Gemm g, const Sched& S, const Epi& E, int wave_id) {
;     ...
;             PG8_WAIT_V(8); PG8_WAIT_L(0); PG8_BAR; PG8_MMA(1, 0, At, B0); PG8_MMA(1, 1, At, B1); PG8_BAR; PG8_SCHED;
;             PG8_LDB(B0, 1, 0); PG8_LDB(B1, 1, 1); PG8_SCHED; PG8_LDA(At, 1, 0); PG8_STAGE(PG8_SA(0, 1), a2 + hstepA, voffA);
;             PG8_WAIT_V(8); PG8_WAIT_L(0); PG8_BAR; PG8_MMA(0, 0, At, B0); PG8_MMA(0, 1, At, B1); PG8_BAR; PG8_SCHED;
;             PG8_LDA(At, 1, 1); PG8_STAGE(PG8_SB(1, 0), b3, voffB); PG8_STAGE(PG8_SB(1, 1), b3 + hstepB, voffB); PG8_STAGE(PG8_SA(1, 0), a3, voffA);
	s_setprio 1
	s_waitcnt lgkmcnt(0)
	v_mfma_f32_16x16x32_bf16 v[76:79], v[16:19], v[206:209], 0
	v_mfma_f32_16x16x32_bf16 v[72:75], v[32:35], v[206:209], 0
	v_mfma_f32_16x16x32_bf16 v[60:63], v[16:19], v[214:217], 0
	v_mfma_f32_16x16x32_bf16 v[56:59], v[32:35], v[214:217], 0
	v_mfma_f32_16x16x32_bf16 v[44:47], v[16:19], v[222:225], 0
	v_mfma_f32_16x16x32_bf16 v[40:43], v[32:35], v[222:225], 0
	v_mfma_f32_16x16x32_bf16 v[12:15], v[16:19], v[230:233], 0
	v_mfma_f32_16x16x32_bf16 v[8:11], v[32:35], v[230:233], 0
	v_mfma_f32_16x16x32_bf16 v[76:79], v[20:23], v[210:213], v[76:79]
	v_mfma_f32_16x16x32_bf16 v[72:75], v[36:39], v[210:213], v[72:75]
	v_mfma_f32_16x16x32_bf16 v[60:63], v[20:23], v[218:221], v[60:63]
	v_mfma_f32_16x16x32_bf16 v[56:59], v[36:39], v[218:221], v[56:59]
	v_mfma_f32_16x16x32_bf16 v[44:47], v[20:23], v[226:229], v[44:47]
	v_mfma_f32_16x16x32_bf16 v[40:43], v[36:39], v[226:229], v[40:43]
	v_mfma_f32_16x16x32_bf16 v[12:15], v[20:23], v[234:237], v[12:15]
	v_mfma_f32_16x16x32_bf16 v[8:11], v[36:39], v[234:237], v[8:11]
	s_setprio 0
	s_setprio 1
	v_mfma_f32_16x16x32_bf16 v[28:31], v[184:187], v[222:225], 0
	v_mfma_f32_16x16x32_bf16 v[24:27], v[198:201], v[222:225], 0
	v_mfma_f32_16x16x32_bf16 v[4:7], v[184:187], v[230:233], 0
	v_mfma_f32_16x16x32_bf16 v[0:3], v[198:201], v[230:233], 0
	v_mfma_f32_16x16x32_bf16 v[16:19], v[184:187], v[206:209], 0
	v_mfma_f32_16x16x32_bf16 v[20:23], v[198:201], v[206:209], 0
	v_mfma_f32_16x16x32_bf16 v[32:35], v[184:187], v[214:217], 0
	v_mfma_f32_16x16x32_bf16 v[36:39], v[198:201], v[214:217], 0
	v_mfma_f32_16x16x32_bf16 v[28:31], v[194:197], v[226:229], v[28:31]
	v_mfma_f32_16x16x32_bf16 v[24:27], v[202:205], v[226:229], v[24:27]
	v_mfma_f32_16x16x32_bf16 v[4:7], v[194:197], v[234:237], v[4:7]
	v_mfma_f32_16x16x32_bf16 v[0:3], v[202:205], v[234:237], v[0:3]
	v_mfma_f32_16x16x32_bf16 v[16:19], v[194:197], v[210:213], v[16:19]
	v_mfma_f32_16x16x32_bf16 v[20:23], v[202:205], v[210:213], v[20:23]
	v_mfma_f32_16x16x32_bf16 v[32:35], v[194:197], v[218:221], v[32:35]
	v_mfma_f32_16x16x32_bf16 v[36:39], v[202:205], v[218:221], v[36:39]
	s_setprio 0
	s_barrier
	s_add_i32 s50, 0, 0x18000
	s_add_i32 s51, 0, 0x1c000
	v_add_u32_e32 v68, s50, v171
	v_add_u32_e32 v152, s51, v171
	ds_read_b128 v[48:51], v68
	ds_read_b128 v[52:55], v68 offset:1024
	ds_read_b128 v[64:67], v68 offset:2048
	ds_read_b128 v[68:71], v68 offset:3072
	ds_read_b128 v[184:187], v152
	ds_read_b128 v[194:197], v152 offset:1024
	ds_read_b128 v[198:201], v152 offset:2048
	ds_read_b128 v[202:205], v152 offset:3072
	s_add_u32 s14, s14, 0x40000
	s_addc_u32 s15, s15, 0
	s_mov_b32 m0, s59
	v_lshl_add_u64 v[242:243], s[14:15], 0, v[144:145]
	ds_read_b128 v[206:209], v191 offset:32768
	ds_read_b128 v[210:213], v191 offset:33792
	ds_read_b128 v[214:217], v191 offset:34816
	ds_read_b128 v[218:221], v191 offset:35840
	ds_read_b128 v[222:225], v191 offset:36864
	ds_read_b128 v[226:229], v191 offset:37888
	ds_read_b128 v[230:233], v191 offset:38912
	ds_read_b128 v[234:237], v191 offset:39936
	global_load_lds_dwordx4 v[242:243], off
	v_lshl_add_u64 v[242:243], s[14:15], 0, v[148:149]
	s_mov_b32 m0, s60
	s_nop 0
	global_load_lds_dwordx4 v[242:243], off
	s_waitcnt vmcnt(8)
	s_waitcnt lgkmcnt(0)
	s_barrier
	s_setprio 1
	s_waitcnt lgkmcnt(0)
	v_mfma_f32_16x16x32_bf16 v[140:143], v[48:51], v[206:209], v[140:143]
	v_mfma_f32_16x16x32_bf16 v[136:139], v[64:67], v[206:209], v[136:139]
	v_mfma_f32_16x16x32_bf16 v[124:127], v[48:51], v[214:217], v[124:127]
	v_mfma_f32_16x16x32_bf16 v[120:123], v[64:67], v[214:217], v[120:123]
	v_mfma_f32_16x16x32_bf16 v[108:111], v[48:51], v[222:225], v[108:111]
	v_mfma_f32_16x16x32_bf16 v[104:107], v[64:67], v[222:225], v[104:107]
	v_mfma_f32_16x16x32_bf16 v[92:95], v[48:51], v[230:233], v[92:95]
	v_mfma_f32_16x16x32_bf16 v[88:91], v[64:67], v[230:233], v[88:91]
	v_mfma_f32_16x16x32_bf16 v[140:143], v[52:55], v[210:213], v[140:143]
	v_mfma_f32_16x16x32_bf16 v[136:139], v[68:71], v[210:213], v[136:139]
	v_mfma_f32_16x16x32_bf16 v[124:127], v[52:55], v[218:221], v[124:127]
	v_mfma_f32_16x16x32_bf16 v[120:123], v[68:71], v[218:221], v[120:123]
	v_mfma_f32_16x16x32_bf16 v[108:111], v[52:55], v[226:229], v[108:111]
	v_mfma_f32_16x16x32_bf16 v[104:107], v[68:71], v[226:229], v[104:107]
	v_mfma_f32_16x16x32_bf16 v[92:95], v[52:55], v[234:237], v[92:95]
	v_mfma_f32_16x16x32_bf16 v[88:91], v[68:71], v[234:237], v[88:91]
	s_setprio 0
	s_setprio 1
	v_mfma_f32_16x16x32_bf16 v[132:135], v[184:187], v[206:209], v[132:135]
	v_mfma_f32_16x16x32_bf16 v[128:131], v[198:201], v[206:209], v[128:131]
	v_mfma_f32_16x16x32_bf16 v[116:119], v[184:187], v[214:217], v[116:119]
	v_mfma_f32_16x16x32_bf16 v[112:115], v[198:201], v[214:217], v[112:115]
	v_mfma_f32_16x16x32_bf16 v[100:103], v[184:187], v[222:225], v[100:103]
	v_mfma_f32_16x16x32_bf16 v[96:99], v[198:201], v[222:225], v[96:99]
	v_mfma_f32_16x16x32_bf16 v[84:87], v[184:187], v[230:233], v[84:87]
	v_mfma_f32_16x16x32_bf16 v[80:83], v[198:201], v[230:233], v[80:83]
	v_mfma_f32_16x16x32_bf16 v[132:135], v[194:197], v[210:213], v[132:135]
	v_mfma_f32_16x16x32_bf16 v[128:131], v[202:205], v[210:213], v[128:131]
	v_mfma_f32_16x16x32_bf16 v[116:119], v[194:197], v[218:221], v[116:119]
	v_mfma_f32_16x16x32_bf16 v[112:115], v[202:205], v[218:221], v[112:115]
	v_mfma_f32_16x16x32_bf16 v[100:103], v[194:197], v[226:229], v[100:103]
	v_mfma_f32_16x16x32_bf16 v[96:99], v[202:205], v[226:229], v[96:99]
	v_mfma_f32_16x16x32_bf16 v[84:87], v[194:197], v[234:237], v[84:87]
	v_mfma_f32_16x16x32_bf16 v[80:83], v[202:205], v[234:237], v[80:83]
	s_setprio 0
	s_barrier
; #define PG8_STAGE(bufoff, gbase, voff) do { _Pragma("unroll") for (int _i = 0; _i < 2; ++_i) \
;         __builtin_amdgcn_global_load_lds((const unsigned*)((const char*)(gbase) + (voff)[_i]), (LAS unsigned*)(lds + (bufoff) + ldsw + _i * 8192), 16, 0, 0); } while (0)
; #define PG8_LDA(dst, b, h) do { _Pragma("unroll") for (int m = 0; m < 4; ++m) _Pragma("unroll") for (int k = 0; k < 2; ++k) dst[m][k] = *(const LAS bf16x8*)(lds + PG8_SA(b, h) + aoff + m * 2048 + k * 1024); } while (0)
; #define PG8_MMA(ai, bj, At, Bt) do { __builtin_amdgcn_s_setprio(1); _Pragma("unroll") for (int m = 0; m < 4; ++m) _Pragma("unroll") for (int n = 0; n < 2; ++n) _Pragma("unroll") for (int k = 0; k < 2; ++k) \
;         acc[ai][bj][m][n] = __builtin_amdgcn_mfma_f32_16x16x32_bf16(Bt[n][k], At[m][k], acc[ai][bj][m][n], 0, 0, 0); __builtin_amdgcn_s_setprio(0); } while (0)
; #define PG8_WAIT_V(n) asm volatile("s_waitcnt vmcnt(" #n ")" ::: "memory")
; #define PG8_WAIT_L(n) asm volatile("s_waitcnt lgkmcnt(" #n ")" ::: "memory")
; #define PG8_BAR __builtin_amdgcn_s_barrier()
; #define PG8_SCHED __builtin_amdgcn_sched_barrier(0)
; template <class Epi, class Sched>
; __device__ __forceinline__ void gemm_phase(LAS unsigned char* lds, const Gemm g, const Sched& S, const Epi& E, int wave_id) {
;     ...
;             PG8_LDA(At, 1, 1); PG8_STAGE(PG8_SB(1, 0), b3, voffB); PG8_STAGE(PG8_SB(1, 1), b3 + hstepB, voffB); PG8_STAGE(PG8_SA(1, 0), a3, voffA);
;             PG8_WAIT_V(8); PG8_WAIT_L(0); PG8_BAR; PG8_MMA(1, 0, At, B0); PG8_MMA(1, 1, At, B1); PG8_BAR; PG8_SCHED;
	s_add_i32 s14, s50, s54
	v_lshl_add_u64 v[168:169], v[168:169], 0, s[22:23]
	s_mov_b32 m0, s14
	ds_read_b128 v[206:209], v191 offset:49152
	ds_read_b128 v[210:213], v191 offset:50176
	ds_read_b128 v[214:217], v191 offset:51200
	ds_read_b128 v[218:221], v191 offset:52224
	ds_read_b128 v[222:225], v191 offset:53248
	ds_read_b128 v[226:229], v191 offset:54272
	ds_read_b128 v[230:233], v191 offset:55296
	ds_read_b128 v[234:237], v191 offset:56320
	global_load_lds_dwordx4 v[168:169], off
	s_add_i32 m0, s14, 0x2000
	s_add_u32 s12, s12, 0x40080
	v_lshl_add_u64 v[168:169], v[188:189], 0, s[22:23]
	s_addc_u32 s13, s13, 0
	s_add_i32 s14, s51, s54
	global_load_lds_dwordx4 v[168:169], off
	v_lshl_add_u64 v[168:169], s[12:13], 0, v[146:147]
	s_mov_b32 m0, s14
	s_nop 0
	global_load_lds_dwordx4 v[168:169], off
	v_lshl_add_u64 v[168:169], s[12:13], 0, v[150:151]
	s_add_i32 m0, s14, 0x2000
	s_nop 0
	global_load_lds_dwordx4 v[168:169], off
	v_lshl_add_u64 v[168:169], v[238:239], 0, s[22:23]
	s_mov_b32 m0, s62
	s_nop 0
	global_load_lds_dwordx4 v[168:169], off
	v_lshl_add_u64 v[168:169], v[240:241], 0, s[22:23]
	s_mov_b32 m0, s63
	s_nop 0
	global_load_lds_dwordx4 v[168:169], off
	s_waitcnt vmcnt(8)
	s_waitcnt lgkmcnt(0)
	s_barrier
	s_setprio 1
	s_waitcnt lgkmcnt(0)
	v_mfma_f32_16x16x32_bf16 v[76:79], v[48:51], v[206:209], v[76:79]
	v_mfma_f32_16x16x32_bf16 v[72:75], v[64:67], v[206:209], v[72:75]
	v_mfma_f32_16x16x32_bf16 v[60:63], v[48:51], v[214:217], v[60:63]
	v_mfma_f32_16x16x32_bf16 v[56:59], v[64:67], v[214:217], v[56:59]
	v_mfma_f32_16x16x32_bf16 v[44:47], v[48:51], v[222:225], v[44:47]
	v_mfma_f32_16x16x32_bf16 v[40:43], v[64:67], v[222:225], v[40:43]
	v_mfma_f32_16x16x32_bf16 v[12:15], v[48:51], v[230:233], v[12:15]
	v_mfma_f32_16x16x32_bf16 v[8:11], v[64:67], v[230:233], v[8:11]
	v_mfma_f32_16x16x32_bf16 v[76:79], v[52:55], v[210:213], v[76:79]
	v_mfma_f32_16x16x32_bf16 v[72:75], v[68:71], v[210:213], v[72:75]
	v_mfma_f32_16x16x32_bf16 v[60:63], v[52:55], v[218:221], v[60:63]
	v_mfma_f32_16x16x32_bf16 v[56:59], v[68:71], v[218:221], v[56:59]
	v_mfma_f32_16x16x32_bf16 v[44:47], v[52:55], v[226:229], v[44:47]
	v_mfma_f32_16x16x32_bf16 v[40:43], v[68:71], v[226:229], v[40:43]
	v_mfma_f32_16x16x32_bf16 v[12:15], v[52:55], v[234:237], v[12:15]
	v_mfma_f32_16x16x32_bf16 v[8:11], v[68:71], v[234:237], v[8:11]
	s_setprio 0
	s_setprio 1
	v_mfma_f32_16x16x32_bf16 v[16:19], v[184:187], v[206:209], v[16:19]
	v_mfma_f32_16x16x32_bf16 v[68:71], v[194:197], v[210:213], v[16:19]
	v_mfma_f32_16x16x32_bf16 v[16:19], v[198:201], v[206:209], v[20:23]
	v_mfma_f32_16x16x32_bf16 v[64:67], v[202:205], v[210:213], v[16:19]
	v_mfma_f32_16x16x32_bf16 v[16:19], v[184:187], v[214:217], v[32:35]
	v_mfma_f32_16x16x32_bf16 v[52:55], v[194:197], v[218:221], v[16:19]
	v_mfma_f32_16x16x32_bf16 v[16:19], v[198:201], v[214:217], v[36:39]
	v_mfma_f32_16x16x32_bf16 v[48:51], v[202:205], v[218:221], v[16:19]
	v_mfma_f32_16x16x32_bf16 v[16:19], v[184:187], v[222:225], v[28:31]
	v_mfma_f32_16x16x32_bf16 v[28:31], v[194:197], v[226:229], v[16:19]
	v_mfma_f32_16x16x32_bf16 v[16:19], v[198:201], v[222:225], v[24:27]
	v_mfma_f32_16x16x32_bf16 v[4:7], v[184:187], v[230:233], v[4:7]
	v_mfma_f32_16x16x32_bf16 v[0:3], v[198:201], v[230:233], v[0:3]
	v_mfma_f32_16x16x32_bf16 v[24:27], v[202:205], v[226:229], v[16:19]
	v_mfma_f32_16x16x32_bf16 v[4:7], v[194:197], v[234:237], v[4:7]
	v_mfma_f32_16x16x32_bf16 v[0:3], v[202:205], v[234:237], v[0:3]
	s_setprio 0
	s_barrier
	s_add_i32 s45, s45, 2
	s_add_u32 s10, s10, 0x100
	s_addc_u32 s11, s11, 0
	s_add_u32 s33, s33, 0x100
	s_addc_u32 s39, s39, 0
	s_cmp_gt_u32 s45, 13

;     __device__ bool next(int i, Unit& u) const { if (r0 + i >= r1) return false; return base.next(r0 + i, u); }
;     __device__ bool next(int i, Unit& u) const { const int L = i * G + c; if (L >= 256) return false; u.pm = L; u.pn = L >> 3; return true; }
; #define PG8_STAGE(bufoff, gbase, voff) do { _Pragma("unroll") for (int _i = 0; _i < 2; ++_i) \
;         __builtin_amdgcn_global_load_lds((const unsigned*)((const char*)(gbase) + (voff)[_i]), (LAS unsigned*)(lds + (bufoff) + ldsw + _i * 8192), 16, 0, 0); } while (0)
; #define PG8_LDA(dst, b, h) do { _Pragma("unroll") for (int m = 0; m < 4; ++m) _Pragma("unroll") for (int k = 0; k < 2; ++k) dst[m][k] = *(const LAS bf16x8*)(lds + PG8_SA(b, h) + aoff + m * 2048 + k * 1024); } while (0)
; #define PG8_LDB(dst, b, h) do { _Pragma("unroll") for (int n = 0; n < 2; ++n) _Pragma("unroll") for (int k = 0; k < 2; ++k) dst[n][k] = *(const LAS bf16x8*)(lds + PG8_SB(b, h) + boff + n * 2048 + k * 1024); } while (0)
; #define PG8_WAIT_V(n) asm volatile("s_waitcnt vmcnt(" #n ")" ::: "memory")
; #define PG8_WAIT_L(n) asm volatile("s_waitcnt lgkmcnt(" #n ")" ::: "memory")
; template <class Epi, class Sched>
; __device__ __forceinline__ void gemm_phase(LAS unsigned char* lds, const Gemm g, const Sched& S, const Epi& E, int wave_id) {
;     ...
;         const bool has_next = S.next(ui + 1, nxt);
;         const char* nA = has_next ? (const char*)g.A + (size_t)nxt.pm * tstepA : cA; const char* nB = has_next ? (const char*)g.Bt + (size_t)nxt.pn * tstepB : cB;
;         for (int t = 0; t < nt; t += 2) {
;             const bool last = (t == nt - 2);
;             const char* a1 = cA + (size_t)(t + 1) * kstep;
;             const char* a2 = last ? nA : cA + (size_t)(t + 2) * kstep; const char* b2 = last ? nB : cB + (size_t)(t + 2) * kstep;
;             const char* a3 = a2 + kstep; const char* b3 = b2 + kstep;
;             PG8_LDB(B0, 0, 0); PG8_LDB(B1, 0, 1); PG8_SCHED; PG8_LDA(At, 0, 0); PG8_STAGE(PG8_SA(1, 1), a1 + hstepA, voffA);
;             PG8_WAIT_V(8); PG8_WAIT_L(0); PG8_BAR; PG8_MMA(0, 0, At, B0); PG8_MMA(0, 1, At, B1); PG8_BAR; PG8_SCHED;
;             PG8_LDA(At, 0, 1); PG8_STAGE(PG8_SB(0, 0), b2, voffB); PG8_STAGE(PG8_SB(0, 1), b2 + hstepB, voffB); PG8_STAGE(PG8_SA(0, 0), a2, voffA);
;             PG8_WAIT_V(8); PG8_WAIT_L(0); PG8_BAR; PG8_MMA(1, 0, At, B0); PG8_MMA(1, 1, At, B1); PG8_BAR; PG8_SCHED;
.LBB0_672:
	s_ashr_i32 s23, s22, 31
	s_lshl_b64 s[26:27], s[22:23], 19
	s_add_u32 s26, s15, s26
	s_addc_u32 s27, s33, s27
	s_and_b64 s[28:29], s[24:25], exec
	s_cselect_b32 s23, s27, s35
	s_cselect_b32 s61, s26, s34
	s_ashr_i32 s17, s16, 31
	s_lshl_b64 s[28:29], s[16:17], 19
	s_add_u32 s28, s44, s28
	s_addc_u32 s29, s45, s29
	s_and_b64 s[38:39], s[24:25], exec
	s_cselect_b32 s17, s29, s37
	s_cselect_b32 s62, s28, s36
	s_add_u32 s34, s34, 0x40080
	s_addc_u32 s35, s35, 0
	s_add_u32 s63, s36, 0x100
	s_addc_u32 s64, s37, 0
	s_mov_b32 s65, -2
	ds_read_b128 v[142:145], v161
	ds_read_b128 v[146:149], v161 offset:1024
	ds_read_b128 v[150:153], v161 offset:2048
	ds_read_b128 v[154:157], v161 offset:3072
	ds_read_b128 v[164:167], v162
	ds_read_b128 v[168:171], v162 offset:1024
	ds_read_b128 v[172:175], v162 offset:2048
	ds_read_b128 v[176:179], v162 offset:3072
	s_add_u32 s36, s34, 0xfffc0080
	s_addc_u32 s37, s35, -1
	s_cmp_eq_u32 s65, 12
	s_cselect_b32 s39, s23, s37
	s_cselect_b32 s38, s61, s36
	s_cselect_b32 s37, s17, s64
	s_cselect_b32 s36, s62, s63
	v_lshl_add_u64 v[212:213], s[34:35], 0, v[136:137]
	s_add_i32 m0, s31, 0xc000
	ds_read_b128 v[180:183], v163
	ds_read_b128 v[184:187], v163 offset:1024
	ds_read_b128 v[188:191], v163 offset:2048
	ds_read_b128 v[192:195], v163 offset:3072
	ds_read_b128 v[196:199], v163 offset:4096
	ds_read_b128 v[200:203], v163 offset:5120
	ds_read_b128 v[204:207], v163 offset:6144
	ds_read_b128 v[208:211], v163 offset:7168
	global_load_lds_dwordx4 v[212:213], off
	v_lshl_add_u64 v[212:213], s[34:35], 0, v[138:139]
	s_add_i32 m0, s31, 0xe000
	s_nop 0
	global_load_lds_dwordx4 v[212:213], off
	s_waitcnt vmcnt(24)
	s_waitcnt lgkmcnt(0)
	s_barrier
	s_setprio 1
	s_waitcnt lgkmcnt(0)
	v_mfma_f32_16x16x32_bf16 v[124:127], v[142:145], v[180:183], 0
	v_mfma_f32_16x16x32_bf16 v[120:123], v[150:153], v[180:183], 0
	v_mfma_f32_16x16x32_bf16 v[108:111], v[142:145], v[188:191], 0
	v_mfma_f32_16x16x32_bf16 v[104:107], v[150:153], v[188:191], 0
	v_mfma_f32_16x16x32_bf16 v[92:95], v[142:145], v[196:199], 0
	v_mfma_f32_16x16x32_bf16 v[88:91], v[150:153], v[196:199], 0
	v_mfma_f32_16x16x32_bf16 v[76:79], v[142:145], v[204:207], 0
	v_mfma_f32_16x16x32_bf16 v[72:75], v[150:153], v[204:207], 0
	v_mfma_f32_16x16x32_bf16 v[124:127], v[146:149], v[184:187], v[124:127]
	v_mfma_f32_16x16x32_bf16 v[120:123], v[154:157], v[184:187], v[120:123]
	v_mfma_f32_16x16x32_bf16 v[108:111], v[146:149], v[192:195], v[108:111]
	v_mfma_f32_16x16x32_bf16 v[104:107], v[154:157], v[192:195], v[104:107]
	v_mfma_f32_16x16x32_bf16 v[92:95], v[146:149], v[200:203], v[92:95]
	v_mfma_f32_16x16x32_bf16 v[88:91], v[154:157], v[200:203], v[88:91]
	v_mfma_f32_16x16x32_bf16 v[76:79], v[146:149], v[208:211], v[76:79]
	v_mfma_f32_16x16x32_bf16 v[72:75], v[154:157], v[208:211], v[72:75]
	s_setprio 0
	s_setprio 1
	v_mfma_f32_16x16x32_bf16 v[116:119], v[164:167], v[180:183], 0
	v_mfma_f32_16x16x32_bf16 v[112:115], v[172:175], v[180:183], 0
	v_mfma_f32_16x16x32_bf16 v[100:103], v[164:167], v[188:191], 0
	v_mfma_f32_16x16x32_bf16 v[96:99], v[172:175], v[188:191], 0
	v_mfma_f32_16x16x32_bf16 v[84:87], v[164:167], v[196:199], 0
	v_mfma_f32_16x16x32_bf16 v[80:83], v[172:175], v[196:199], 0
	v_mfma_f32_16x16x32_bf16 v[68:71], v[164:167], v[204:207], 0
	v_mfma_f32_16x16x32_bf16 v[64:67], v[172:175], v[204:207], 0
	v_mfma_f32_16x16x32_bf16 v[116:119], v[168:171], v[184:187], v[116:119]
	v_mfma_f32_16x16x32_bf16 v[112:115], v[176:179], v[184:187], v[112:115]
	v_mfma_f32_16x16x32_bf16 v[100:103], v[168:171], v[192:195], v[100:103]
	v_mfma_f32_16x16x32_bf16 v[96:99], v[176:179], v[192:195], v[96:99]
	v_mfma_f32_16x16x32_bf16 v[84:87], v[168:171], v[200:203], v[84:87]
	v_mfma_f32_16x16x32_bf16 v[80:83], v[176:179], v[200:203], v[80:83]
	v_mfma_f32_16x16x32_bf16 v[68:71], v[168:171], v[208:211], v[68:71]
	v_mfma_f32_16x16x32_bf16 v[64:67], v[176:179], v[208:211], v[64:67]
	s_setprio 0
	s_barrier
	s_add_i32 s66, s55, s46
	v_lshl_add_u64 v[212:213], s[36:37], 0, v[130:131]
	s_mov_b32 m0, s66
	ds_read_b128 v[180:183], v163 offset:16384
	ds_read_b128 v[184:187], v163 offset:17408
	ds_read_b128 v[188:191], v163 offset:18432
	ds_read_b128 v[192:195], v163 offset:19456
	ds_read_b128 v[196:199], v163 offset:20480
	ds_read_b128 v[200:203], v163 offset:21504
	ds_read_b128 v[204:207], v163 offset:22528
	ds_read_b128 v[208:211], v163 offset:23552
	global_load_lds_dwordx4 v[212:213], off
	s_add_i32 m0, s66, 0x2000
	s_add_u32 s66, s36, 0x40000
	v_lshl_add_u64 v[214:215], s[36:37], 0, v[134:135]
	s_addc_u32 s67, s37, 0
	s_add_i32 s72, s58, s46
	global_load_lds_dwordx4 v[214:215], off
	v_lshl_add_u64 v[216:217], s[66:67], 0, v[130:131]
	s_mov_b32 m0, s72
	v_lshl_add_u64 v[218:219], s[38:39], 0, v[132:133]
	global_load_lds_dwordx4 v[216:217], off
	v_lshl_add_u64 v[216:217], s[66:67], 0, v[134:135]
	s_add_i32 m0, s72, 0x2000
	s_nop 0
	global_load_lds_dwordx4 v[216:217], off
	v_lshl_add_u64 v[216:217], s[38:39], 0, v[128:129]
	s_mov_b32 m0, s31
	s_nop 0
	global_load_lds_dwordx4 v[216:217], off
	s_mov_b32 m0, s47
	s_nop 0
	global_load_lds_dwordx4 v[218:219], off
	s_waitcnt vmcnt(8)
	s_waitcnt lgkmcnt(0)
	s_barrier
; #define PG8_STAGE(bufoff, gbase, voff) do { _Pragma("unroll") for (int _i = 0; _i < 2; ++_i) \
;         __builtin_amdgcn_global_load_lds((const unsigned*)((const char*)(gbase) + (voff)[_i]), (LAS unsigned*)(lds + (bufoff) + ldsw + _i * 8192), 16, 0, 0); } while (0)
; #define PG8_LDA(dst, b, h) do { _Pragma("unroll") for (int m = 0; m < 4; ++m) _Pragma("unroll") for (int k = 0; k < 2; ++k) dst[m][k] = *(const LAS bf16x8*)(lds + PG8_SA(b, h) + aoff + m * 2048 + k * 1024); } while (0)
; #define PG8_LDB(dst, b, h) do { _Pragma("unroll") for (int n = 0; n < 2; ++n) _Pragma("unroll") for (int k = 0; k < 2; ++k) dst[n][k] = *(const LAS bf16x8*)(lds + PG8_SB(b, h) + boff + n * 2048 + k * 1024); } while (0)
; #define PG8_MMA(ai, bj, At, Bt) do { __builtin_amdgcn_s_setprio(1); _Pragma("unroll") for (int m = 0; m < 4; ++m) _Pragma("unroll") for (int n = 0; n < 2; ++n) _Pragma("unroll") for (int k = 0; k < 2; ++k) \
;         acc[ai][bj][m][n] = __builtin_amdgcn_mfma_f32_16x16x32_bf16(Bt[n][k], At[m][k], acc[ai][bj][m][n], 0, 0, 0); __builtin_amdgcn_s_setprio(0); } while (0)
; #define PG8_WAIT_V(n) asm volatile("s_waitcnt vmcnt(" #n ")" ::: "memory")
; #define PG8_WAIT_L(n) asm volatile("s_waitcnt lgkmcnt(" #n ")" ::: "memory")
; #define PG8_BAR __builtin_amdgcn_s_barrier()
; #define PG8_SCHED __builtin_amdgcn_sched_barrier(0)
; template <class Epi, class Sched>
; __device__ __forceinline__ void gemm_phase(LAS unsigned char* lds, const Gemm g, const Sched& S, const Epi& E, int wave_id) {
;     ...
;             PG8_WAIT_V(8); PG8_WAIT_L(0); PG8_BAR; PG8_MMA(1, 0, At, B0); PG8_MMA(1, 1, At, B1); PG8_BAR; PG8_SCHED;
;             PG8_LDB(B0, 1, 0); PG8_LDB(B1, 1, 1); PG8_SCHED; PG8_LDA(At, 1, 0); PG8_STAGE(PG8_SA(0, 1), a2 + hstepA, voffA);
;             PG8_WAIT_V(8); PG8_WAIT_L(0); PG8_BAR; PG8_MMA(0, 0, At, B0); PG8_MMA(0, 1, At, B1); PG8_BAR; PG8_SCHED;
;             PG8_LDA(At, 1, 1); PG8_STAGE(PG8_SB(1, 0), b3, voffB); PG8_STAGE(PG8_SB(1, 1), b3 + hstepB, voffB); PG8_STAGE(PG8_SA(1, 0), a3, voffA);
	s_setprio 1
	s_waitcnt lgkmcnt(0)
	v_mfma_f32_16x16x32_bf16 v[60:63], v[142:145], v[180:183], 0
	v_mfma_f32_16x16x32_bf16 v[56:59], v[150:153], v[180:183], 0
	v_mfma_f32_16x16x32_bf16 v[44:47], v[142:145], v[188:191], 0
	v_mfma_f32_16x16x32_bf16 v[40:43], v[150:153], v[188:191], 0
	v_mfma_f32_16x16x32_bf16 v[28:31], v[142:145], v[196:199], 0
	v_mfma_f32_16x16x32_bf16 v[24:27], v[150:153], v[196:199], 0
	v_mfma_f32_16x16x32_bf16 v[12:15], v[142:145], v[204:207], 0
	v_mfma_f32_16x16x32_bf16 v[8:11], v[150:153], v[204:207], 0
	v_mfma_f32_16x16x32_bf16 v[60:63], v[146:149], v[184:187], v[60:63]
	v_mfma_f32_16x16x32_bf16 v[56:59], v[154:157], v[184:187], v[56:59]
	v_mfma_f32_16x16x32_bf16 v[44:47], v[146:149], v[192:195], v[44:47]
	v_mfma_f32_16x16x32_bf16 v[40:43], v[154:157], v[192:195], v[40:43]
	v_mfma_f32_16x16x32_bf16 v[28:31], v[146:149], v[200:203], v[28:31]
	v_mfma_f32_16x16x32_bf16 v[24:27], v[154:157], v[200:203], v[24:27]
	v_mfma_f32_16x16x32_bf16 v[12:15], v[146:149], v[208:211], v[12:15]
	v_mfma_f32_16x16x32_bf16 v[8:11], v[154:157], v[208:211], v[8:11]
	s_setprio 0
	s_setprio 1
	v_mfma_f32_16x16x32_bf16 v[52:55], v[164:167], v[180:183], 0
	v_mfma_f32_16x16x32_bf16 v[48:51], v[172:175], v[180:183], 0
	v_mfma_f32_16x16x32_bf16 v[36:39], v[164:167], v[188:191], 0
	v_mfma_f32_16x16x32_bf16 v[32:35], v[172:175], v[188:191], 0
	v_mfma_f32_16x16x32_bf16 v[20:23], v[164:167], v[196:199], 0
	v_mfma_f32_16x16x32_bf16 v[16:19], v[172:175], v[196:199], 0
	v_mfma_f32_16x16x32_bf16 v[4:7], v[164:167], v[204:207], 0
	v_mfma_f32_16x16x32_bf16 v[0:3], v[172:175], v[204:207], 0
	v_mfma_f32_16x16x32_bf16 v[52:55], v[168:171], v[184:187], v[52:55]
	v_mfma_f32_16x16x32_bf16 v[48:51], v[176:179], v[184:187], v[48:51]
	v_mfma_f32_16x16x32_bf16 v[36:39], v[168:171], v[192:195], v[36:39]
	v_mfma_f32_16x16x32_bf16 v[32:35], v[176:179], v[192:195], v[32:35]
	v_mfma_f32_16x16x32_bf16 v[20:23], v[168:171], v[200:203], v[20:23]
	v_mfma_f32_16x16x32_bf16 v[16:19], v[176:179], v[200:203], v[16:19]
	v_mfma_f32_16x16x32_bf16 v[4:7], v[168:171], v[208:211], v[4:7]
	v_mfma_f32_16x16x32_bf16 v[0:3], v[176:179], v[208:211], v[0:3]
	s_setprio 0
	s_barrier
	s_add_i32 s66, 0, 0x18000
	s_add_i32 s67, 0, 0x1c000
	v_add_u32_e32 v154, s66, v159
	v_add_u32_e32 v176, s67, v159
	ds_read_b128 v[142:145], v154
	ds_read_b128 v[146:149], v154 offset:1024
	ds_read_b128 v[150:153], v154 offset:2048
	ds_read_b128 v[154:157], v154 offset:3072
	ds_read_b128 v[164:167], v176
	ds_read_b128 v[168:171], v176 offset:1024
	ds_read_b128 v[172:175], v176 offset:2048
	ds_read_b128 v[176:179], v176 offset:3072
	s_add_u32 s38, s38, 0x40000
	s_addc_u32 s39, s39, 0
	s_mov_b32 m0, s48
	v_lshl_add_u64 v[220:221], s[38:39], 0, v[128:129]
	ds_read_b128 v[180:183], v163 offset:32768
	ds_read_b128 v[184:187], v163 offset:33792
	ds_read_b128 v[188:191], v163 offset:34816
	ds_read_b128 v[192:195], v163 offset:35840
	ds_read_b128 v[196:199], v163 offset:36864
	ds_read_b128 v[200:203], v163 offset:37888
	ds_read_b128 v[204:207], v163 offset:38912
	ds_read_b128 v[208:211], v163 offset:39936
	global_load_lds_dwordx4 v[220:221], off
	v_lshl_add_u64 v[220:221], s[38:39], 0, v[132:133]
	s_mov_b32 m0, s49
	s_nop 0
	global_load_lds_dwordx4 v[220:221], off
	s_waitcnt vmcnt(8)
	s_waitcnt lgkmcnt(0)
	s_barrier
	s_setprio 1
	s_waitcnt lgkmcnt(0)
	v_mfma_f32_16x16x32_bf16 v[124:127], v[142:145], v[180:183], v[124:127]
	v_mfma_f32_16x16x32_bf16 v[120:123], v[150:153], v[180:183], v[120:123]
	v_mfma_f32_16x16x32_bf16 v[108:111], v[142:145], v[188:191], v[108:111]
	v_mfma_f32_16x16x32_bf16 v[104:107], v[150:153], v[188:191], v[104:107]
	v_mfma_f32_16x16x32_bf16 v[92:95], v[142:145], v[196:199], v[92:95]
	v_mfma_f32_16x16x32_bf16 v[88:91], v[150:153], v[196:199], v[88:91]
	v_mfma_f32_16x16x32_bf16 v[76:79], v[142:145], v[204:207], v[76:79]
	v_mfma_f32_16x16x32_bf16 v[72:75], v[150:153], v[204:207], v[72:75]
	v_mfma_f32_16x16x32_bf16 v[124:127], v[146:149], v[184:187], v[124:127]
	v_mfma_f32_16x16x32_bf16 v[120:123], v[154:157], v[184:187], v[120:123]
	v_mfma_f32_16x16x32_bf16 v[108:111], v[146:149], v[192:195], v[108:111]
	v_mfma_f32_16x16x32_bf16 v[104:107], v[154:157], v[192:195], v[104:107]
	v_mfma_f32_16x16x32_bf16 v[92:95], v[146:149], v[200:203], v[92:95]
	v_mfma_f32_16x16x32_bf16 v[88:91], v[154:157], v[200:203], v[88:91]
	v_mfma_f32_16x16x32_bf16 v[76:79], v[146:149], v[208:211], v[76:79]
	v_mfma_f32_16x16x32_bf16 v[72:75], v[154:157], v[208:211], v[72:75]
	s_setprio 0
	s_setprio 1
	v_mfma_f32_16x16x32_bf16 v[116:119], v[164:167], v[180:183], v[116:119]
	v_mfma_f32_16x16x32_bf16 v[112:115], v[172:175], v[180:183], v[112:115]
	v_mfma_f32_16x16x32_bf16 v[100:103], v[164:167], v[188:191], v[100:103]
	v_mfma_f32_16x16x32_bf16 v[96:99], v[172:175], v[188:191], v[96:99]
	v_mfma_f32_16x16x32_bf16 v[84:87], v[164:167], v[196:199], v[84:87]
	v_mfma_f32_16x16x32_bf16 v[80:83], v[172:175], v[196:199], v[80:83]
	v_mfma_f32_16x16x32_bf16 v[68:71], v[164:167], v[204:207], v[68:71]
	v_mfma_f32_16x16x32_bf16 v[64:67], v[172:175], v[204:207], v[64:67]
	v_mfma_f32_16x16x32_bf16 v[116:119], v[168:171], v[184:187], v[116:119]
	v_mfma_f32_16x16x32_bf16 v[112:115], v[176:179], v[184:187], v[112:115]
	v_mfma_f32_16x16x32_bf16 v[100:103], v[168:171], v[192:195], v[100:103]
	v_mfma_f32_16x16x32_bf16 v[96:99], v[176:179], v[192:195], v[96:99]
	v_mfma_f32_16x16x32_bf16 v[84:87], v[168:171], v[200:203], v[84:87]
	v_mfma_f32_16x16x32_bf16 v[80:83], v[176:179], v[200:203], v[80:83]
	v_mfma_f32_16x16x32_bf16 v[68:71], v[168:171], v[208:211], v[68:71]
	v_mfma_f32_16x16x32_bf16 v[64:67], v[176:179], v[208:211], v[64:67]
	s_setprio 0
	s_barrier
; #define PG8_STAGE(bufoff, gbase, voff) do { _Pragma("unroll") for (int _i = 0; _i < 2; ++_i) \
;         __builtin_amdgcn_global_load_lds((const unsigned*)((const char*)(gbase) + (voff)[_i]), (LAS unsigned*)(lds + (bufoff) + ldsw + _i * 8192), 16, 0, 0); } while (0)
; #define PG8_LDA(dst, b, h) do { _Pragma("unroll") for (int m = 0; m < 4; ++m) _Pragma("unroll") for (int k = 0; k < 2; ++k) dst[m][k] = *(const LAS bf16x8*)(lds + PG8_SA(b, h) + aoff + m * 2048 + k * 1024); } while (0)
; #define PG8_MMA(ai, bj, At, Bt) do { __builtin_amdgcn_s_setprio(1); _Pragma("unroll") for (int m = 0; m < 4; ++m) _Pragma("unroll") for (int n = 0; n < 2; ++n) _Pragma("unroll") for (int k = 0; k < 2; ++k) \
;         acc[ai][bj][m][n] = __builtin_amdgcn_mfma_f32_16x16x32_bf16(Bt[n][k], At[m][k], acc[ai][bj][m][n], 0, 0, 0); __builtin_amdgcn_s_setprio(0); } while (0)
; #define PG8_WAIT_V(n) asm volatile("s_waitcnt vmcnt(" #n ")" ::: "memory")
; #define PG8_WAIT_L(n) asm volatile("s_waitcnt lgkmcnt(" #n ")" ::: "memory")
; #define PG8_BAR __builtin_amdgcn_s_barrier()
; #define PG8_SCHED __builtin_amdgcn_sched_barrier(0)
; template <class Epi, class Sched>
; __device__ __forceinline__ void gemm_phase(LAS unsigned char* lds, const Gemm g, const Sched& S, const Epi& E, int wave_id) {
;     ...
;             PG8_LDA(At, 1, 1); PG8_STAGE(PG8_SB(1, 0), b3, voffB); PG8_STAGE(PG8_SB(1, 1), b3 + hstepB, voffB); PG8_STAGE(PG8_SA(1, 0), a3, voffA);
;             PG8_WAIT_V(8); PG8_WAIT_L(0); PG8_BAR; PG8_MMA(1, 0, At, B0); PG8_MMA(1, 1, At, B1); PG8_BAR; PG8_SCHED;
	s_add_i32 s38, s66, s46
	v_lshl_add_u64 v[212:213], v[212:213], 0, s[6:7]
	s_mov_b32 m0, s38
	ds_read_b128 v[180:183], v163 offset:49152
	ds_read_b128 v[184:187], v163 offset:50176
	ds_read_b128 v[188:191], v163 offset:51200
	ds_read_b128 v[192:195], v163 offset:52224
	ds_read_b128 v[196:199], v163 offset:53248
	ds_read_b128 v[200:203], v163 offset:54272
	ds_read_b128 v[204:207], v163 offset:55296
	ds_read_b128 v[208:211], v163 offset:56320
	global_load_lds_dwordx4 v[212:213], off
	s_add_i32 m0, s38, 0x2000
	s_add_u32 s36, s36, 0x40080
	v_lshl_add_u64 v[212:213], v[214:215], 0, s[6:7]
	s_addc_u32 s37, s37, 0
	s_add_i32 s38, s67, s46
	global_load_lds_dwordx4 v[212:213], off
	v_lshl_add_u64 v[212:213], s[36:37], 0, v[130:131]
	s_mov_b32 m0, s38
	s_nop 0
	global_load_lds_dwordx4 v[212:213], off
	v_lshl_add_u64 v[212:213], s[36:37], 0, v[134:135]
	s_add_i32 m0, s38, 0x2000
	s_nop 0
	global_load_lds_dwordx4 v[212:213], off
	v_lshl_add_u64 v[212:213], v[216:217], 0, s[6:7]
	s_mov_b32 m0, s52
	s_nop 0
	global_load_lds_dwordx4 v[212:213], off
	v_lshl_add_u64 v[212:213], v[218:219], 0, s[6:7]
	s_mov_b32 m0, s53
	s_nop 0
	global_load_lds_dwordx4 v[212:213], off
	s_waitcnt vmcnt(8)
	s_waitcnt lgkmcnt(0)
	s_barrier
	s_setprio 1
	s_waitcnt lgkmcnt(0)
	v_mfma_f32_16x16x32_bf16 v[60:63], v[142:145], v[180:183], v[60:63]
	v_mfma_f32_16x16x32_bf16 v[56:59], v[150:153], v[180:183], v[56:59]
	v_mfma_f32_16x16x32_bf16 v[44:47], v[142:145], v[188:191], v[44:47]
	v_mfma_f32_16x16x32_bf16 v[40:43], v[150:153], v[188:191], v[40:43]
	v_mfma_f32_16x16x32_bf16 v[28:31], v[142:145], v[196:199], v[28:31]
	v_mfma_f32_16x16x32_bf16 v[24:27], v[150:153], v[196:199], v[24:27]
	v_mfma_f32_16x16x32_bf16 v[12:15], v[142:145], v[204:207], v[12:15]
	v_mfma_f32_16x16x32_bf16 v[8:11], v[150:153], v[204:207], v[8:11]
	v_mfma_f32_16x16x32_bf16 v[60:63], v[146:149], v[184:187], v[60:63]
	v_mfma_f32_16x16x32_bf16 v[56:59], v[154:157], v[184:187], v[56:59]
	v_mfma_f32_16x16x32_bf16 v[44:47], v[146:149], v[192:195], v[44:47]
	v_mfma_f32_16x16x32_bf16 v[40:43], v[154:157], v[192:195], v[40:43]
	v_mfma_f32_16x16x32_bf16 v[28:31], v[146:149], v[200:203], v[28:31]
	v_mfma_f32_16x16x32_bf16 v[24:27], v[154:157], v[200:203], v[24:27]
	v_mfma_f32_16x16x32_bf16 v[12:15], v[146:149], v[208:211], v[12:15]
	v_mfma_f32_16x16x32_bf16 v[8:11], v[154:157], v[208:211], v[8:11]
	s_setprio 0
	s_setprio 1
	v_mfma_f32_16x16x32_bf16 v[52:55], v[164:167], v[180:183], v[52:55]
	v_mfma_f32_16x16x32_bf16 v[48:51], v[172:175], v[180:183], v[48:51]
	v_mfma_f32_16x16x32_bf16 v[36:39], v[164:167], v[188:191], v[36:39]
	v_mfma_f32_16x16x32_bf16 v[32:35], v[172:175], v[188:191], v[32:35]
	v_mfma_f32_16x16x32_bf16 v[20:23], v[164:167], v[196:199], v[20:23]
	v_mfma_f32_16x16x32_bf16 v[16:19], v[172:175], v[196:199], v[16:19]
	v_mfma_f32_16x16x32_bf16 v[4:7], v[164:167], v[204:207], v[4:7]
	v_mfma_f32_16x16x32_bf16 v[0:3], v[172:175], v[204:207], v[0:3]
	v_mfma_f32_16x16x32_bf16 v[52:55], v[168:171], v[184:187], v[52:55]
	v_mfma_f32_16x16x32_bf16 v[48:51], v[176:179], v[184:187], v[48:51]
	v_mfma_f32_16x16x32_bf16 v[36:39], v[168:171], v[192:195], v[36:39]
	v_mfma_f32_16x16x32_bf16 v[32:35], v[176:179], v[192:195], v[32:35]
	v_mfma_f32_16x16x32_bf16 v[20:23], v[168:171], v[200:203], v[20:23]
	v_mfma_f32_16x16x32_bf16 v[16:19], v[176:179], v[200:203], v[16:19]
	v_mfma_f32_16x16x32_bf16 v[4:7], v[168:171], v[208:211], v[4:7]
	v_mfma_f32_16x16x32_bf16 v[0:3], v[176:179], v[208:211], v[0:3]
	s_setprio 0
	s_barrier
	s_add_i32 s65, s65, 2
	s_add_u32 s34, s34, 0x100
	s_addc_u32 s35, s35, 0
	s_add_u32 s63, s63, 0x100
	s_addc_u32 s64, s64, 0
	s_cmp_gt_u32 s65, 13

;     __device__ bool next(int i, Unit& u) const { if (r0 + i >= r1) return false; return base.next(r0 + i, u); }
;     __device__ bool next(int i, Unit& u) const { const int L = i * G + c; if (L >= 256) return false; u.pm = L; u.pn = L >> 3; return true; }
; #define PG8_STAGE(bufoff, gbase, voff) do { _Pragma("unroll") for (int _i = 0; _i < 2; ++_i) \
;         __builtin_amdgcn_global_load_lds((const unsigned*)((const char*)(gbase) + (voff)[_i]), (LAS unsigned*)(lds + (bufoff) + ldsw + _i * 8192), 16, 0, 0); } while (0)
; #define PG8_LDA(dst, b, h) do { _Pragma("unroll") for (int m = 0; m < 4; ++m) _Pragma("unroll") for (int k = 0; k < 2; ++k) dst[m][k] = *(const LAS bf16x8*)(lds + PG8_SA(b, h) + aoff + m * 2048 + k * 1024); } while (0)
; #define PG8_LDB(dst, b, h) do { _Pragma("unroll") for (int n = 0; n < 2; ++n) _Pragma("unroll") for (int k = 0; k < 2; ++k) dst[n][k] = *(const LAS bf16x8*)(lds + PG8_SB(b, h) + boff + n * 2048 + k * 1024); } while (0)
; #define PG8_WAIT_V(n) asm volatile("s_waitcnt vmcnt(" #n ")" ::: "memory")
; #define PG8_WAIT_L(n) asm volatile("s_waitcnt lgkmcnt(" #n ")" ::: "memory")
; template <class Epi, class Sched>
; __device__ __forceinline__ void gemm_phase(LAS unsigned char* lds, const Gemm g, const Sched& S, const Epi& E, int wave_id) {
;     ...
;         const bool has_next = S.next(ui + 1, nxt);
;         const char* nA = has_next ? (const char*)g.A + (size_t)nxt.pm * tstepA : cA; const char* nB = has_next ? (const char*)g.Bt + (size_t)nxt.pn * tstepB : cB;
;         for (int t = 0; t < nt; t += 2) {
;             const bool last = (t == nt - 2);
;             const char* a1 = cA + (size_t)(t + 1) * kstep;
;             const char* a2 = last ? nA : cA + (size_t)(t + 2) * kstep; const char* b2 = last ? nB : cB + (size_t)(t + 2) * kstep;
;             const char* a3 = a2 + kstep; const char* b3 = b2 + kstep;
;             PG8_LDB(B0, 0, 0); PG8_LDB(B1, 0, 1); PG8_SCHED; PG8_LDA(At, 0, 0); PG8_STAGE(PG8_SA(1, 1), a1 + hstepA, voffA);
;             PG8_WAIT_V(8); PG8_WAIT_L(0); PG8_BAR; PG8_MMA(0, 0, At, B0); PG8_MMA(0, 1, At, B1); PG8_BAR; PG8_SCHED;
;             PG8_LDA(At, 0, 1); PG8_STAGE(PG8_SB(0, 0), b2, voffB); PG8_STAGE(PG8_SB(0, 1), b2 + hstepB, voffB); PG8_STAGE(PG8_SA(0, 0), a2, voffA);
;             PG8_WAIT_V(8); PG8_WAIT_L(0); PG8_BAR; PG8_MMA(1, 0, At, B0); PG8_MMA(1, 1, At, B1); PG8_BAR; PG8_SCHED;
.LBB0_727:
	s_ashr_i32 s21, s20, 31
	s_lshl_b64 s[24:25], s[20:21], 19
	s_add_u32 s24, s15, s24
	s_addc_u32 s25, s33, s25
	s_and_b64 s[26:27], s[22:23], exec
	s_cselect_b32 s21, s25, s31
	s_cselect_b32 s59, s24, s30
	s_ashr_i32 s17, s16, 31
	s_lshl_b64 s[26:27], s[16:17], 19
	s_add_u32 s26, s38, s26
	s_addc_u32 s27, s39, s27
	s_and_b64 s[36:37], s[22:23], exec
	s_cselect_b32 s17, s27, s35
	s_cselect_b32 s60, s26, s34
	s_add_u32 s30, s30, 0x40080
	s_addc_u32 s31, s31, 0
	s_add_u32 s61, s34, 0x100
	s_addc_u32 s62, s35, 0
	s_mov_b32 s63, -2
	s_waitcnt vmcnt(0)
	ds_read_b128 v[142:145], v161
	ds_read_b128 v[146:149], v161 offset:1024
	ds_read_b128 v[150:153], v161 offset:2048
	ds_read_b128 v[154:157], v161 offset:3072
	ds_read_b128 v[164:167], v162
	ds_read_b128 v[168:171], v162 offset:1024
	ds_read_b128 v[172:175], v162 offset:2048
	ds_read_b128 v[176:179], v162 offset:3072
	s_add_u32 s34, s30, 0xfffc0080
	s_addc_u32 s35, s31, -1
	s_cmp_eq_u32 s63, 12
	s_cselect_b32 s37, s21, s35
	s_cselect_b32 s36, s59, s34
	s_cselect_b32 s35, s17, s62
	s_cselect_b32 s34, s60, s61
	v_lshl_add_u64 v[212:213], s[30:31], 0, v[136:137]
	s_add_i32 m0, s29, 0xc000
	ds_read_b128 v[180:183], v163
	ds_read_b128 v[184:187], v163 offset:1024
	ds_read_b128 v[188:191], v163 offset:2048
	ds_read_b128 v[192:195], v163 offset:3072
	ds_read_b128 v[196:199], v163 offset:4096
	ds_read_b128 v[200:203], v163 offset:5120
	ds_read_b128 v[204:207], v163 offset:6144
	ds_read_b128 v[208:211], v163 offset:7168
	global_load_lds_dwordx4 v[212:213], off
	v_lshl_add_u64 v[212:213], s[30:31], 0, v[138:139]
	s_add_i32 m0, s29, 0xe000
	s_nop 0
	global_load_lds_dwordx4 v[212:213], off
	s_waitcnt vmcnt(24)
	s_waitcnt lgkmcnt(0)
	s_barrier
	s_setprio 1
	s_waitcnt lgkmcnt(0)
	v_mfma_f32_16x16x32_bf16 v[124:127], v[142:145], v[180:183], 0
	v_mfma_f32_16x16x32_bf16 v[120:123], v[150:153], v[180:183], 0
	v_mfma_f32_16x16x32_bf16 v[108:111], v[142:145], v[188:191], 0
	v_mfma_f32_16x16x32_bf16 v[104:107], v[150:153], v[188:191], 0
	v_mfma_f32_16x16x32_bf16 v[92:95], v[142:145], v[196:199], 0
	v_mfma_f32_16x16x32_bf16 v[88:91], v[150:153], v[196:199], 0
	v_mfma_f32_16x16x32_bf16 v[76:79], v[142:145], v[204:207], 0
	v_mfma_f32_16x16x32_bf16 v[72:75], v[150:153], v[204:207], 0
	v_mfma_f32_16x16x32_bf16 v[124:127], v[146:149], v[184:187], v[124:127]
	v_mfma_f32_16x16x32_bf16 v[120:123], v[154:157], v[184:187], v[120:123]
	v_mfma_f32_16x16x32_bf16 v[108:111], v[146:149], v[192:195], v[108:111]
	v_mfma_f32_16x16x32_bf16 v[104:107], v[154:157], v[192:195], v[104:107]
	v_mfma_f32_16x16x32_bf16 v[92:95], v[146:149], v[200:203], v[92:95]
	v_mfma_f32_16x16x32_bf16 v[88:91], v[154:157], v[200:203], v[88:91]
	v_mfma_f32_16x16x32_bf16 v[76:79], v[146:149], v[208:211], v[76:79]
	v_mfma_f32_16x16x32_bf16 v[72:75], v[154:157], v[208:211], v[72:75]
	s_setprio 0
	s_setprio 1
	v_mfma_f32_16x16x32_bf16 v[116:119], v[164:167], v[180:183], 0
	v_mfma_f32_16x16x32_bf16 v[112:115], v[172:175], v[180:183], 0
	v_mfma_f32_16x16x32_bf16 v[100:103], v[164:167], v[188:191], 0
	v_mfma_f32_16x16x32_bf16 v[96:99], v[172:175], v[188:191], 0
	v_mfma_f32_16x16x32_bf16 v[84:87], v[164:167], v[196:199], 0
	v_mfma_f32_16x16x32_bf16 v[80:83], v[172:175], v[196:199], 0
	v_mfma_f32_16x16x32_bf16 v[68:71], v[164:167], v[204:207], 0
	v_mfma_f32_16x16x32_bf16 v[64:67], v[172:175], v[204:207], 0
	v_mfma_f32_16x16x32_bf16 v[116:119], v[168:171], v[184:187], v[116:119]
	v_mfma_f32_16x16x32_bf16 v[112:115], v[176:179], v[184:187], v[112:115]
	v_mfma_f32_16x16x32_bf16 v[100:103], v[168:171], v[192:195], v[100:103]
	v_mfma_f32_16x16x32_bf16 v[96:99], v[176:179], v[192:195], v[96:99]
	v_mfma_f32_16x16x32_bf16 v[84:87], v[168:171], v[200:203], v[84:87]
	v_mfma_f32_16x16x32_bf16 v[80:83], v[176:179], v[200:203], v[80:83]
	v_mfma_f32_16x16x32_bf16 v[68:71], v[168:171], v[208:211], v[68:71]
	v_mfma_f32_16x16x32_bf16 v[64:67], v[176:179], v[208:211], v[64:67]
	s_setprio 0
	s_barrier
	s_add_i32 s64, s53, s44
	v_lshl_add_u64 v[212:213], s[34:35], 0, v[130:131]
	s_mov_b32 m0, s64
	ds_read_b128 v[180:183], v163 offset:16384
	ds_read_b128 v[184:187], v163 offset:17408
	ds_read_b128 v[188:191], v163 offset:18432
	ds_read_b128 v[192:195], v163 offset:19456
	ds_read_b128 v[196:199], v163 offset:20480
	ds_read_b128 v[200:203], v163 offset:21504
	ds_read_b128 v[204:207], v163 offset:22528
	ds_read_b128 v[208:211], v163 offset:23552
	global_load_lds_dwordx4 v[212:213], off
	s_add_i32 m0, s64, 0x2000
	s_add_u32 s64, s34, 0x40000
	v_lshl_add_u64 v[214:215], s[34:35], 0, v[134:135]
	s_addc_u32 s65, s35, 0
	s_add_i32 s66, s54, s44
	global_load_lds_dwordx4 v[214:215], off
	v_lshl_add_u64 v[216:217], s[64:65], 0, v[130:131]
	s_mov_b32 m0, s66
	v_lshl_add_u64 v[218:219], s[36:37], 0, v[132:133]
	global_load_lds_dwordx4 v[216:217], off
	v_lshl_add_u64 v[216:217], s[64:65], 0, v[134:135]
	s_add_i32 m0, s66, 0x2000
	s_nop 0
	global_load_lds_dwordx4 v[216:217], off
	v_lshl_add_u64 v[216:217], s[36:37], 0, v[128:129]
	s_mov_b32 m0, s29
	s_nop 0
	global_load_lds_dwordx4 v[216:217], off
	s_mov_b32 m0, s45
	s_nop 0
	global_load_lds_dwordx4 v[218:219], off
	s_waitcnt vmcnt(8)
	s_waitcnt lgkmcnt(0)
	s_barrier
; #define PG8_STAGE(bufoff, gbase, voff) do { _Pragma("unroll") for (int _i = 0; _i < 2; ++_i) \
;         __builtin_amdgcn_global_load_lds((const unsigned*)((const char*)(gbase) + (voff)[_i]), (LAS unsigned*)(lds + (bufoff) + ldsw + _i * 8192), 16, 0, 0); } while (0)
; #define PG8_LDA(dst, b, h) do { _Pragma("unroll") for (int m = 0; m < 4; ++m) _Pragma("unroll") for (int k = 0; k < 2; ++k) dst[m][k] = *(const LAS bf16x8*)(lds + PG8_SA(b, h) + aoff + m * 2048 + k * 1024); } while (0)
; #define PG8_LDB(dst, b, h) do { _Pragma("unroll") for (int n = 0; n < 2; ++n) _Pragma("unroll") for (int k = 0; k < 2; ++k) dst[n][k] = *(const LAS bf16x8*)(lds + PG8_SB(b, h) + boff + n * 2048 + k * 1024); } while (0)
; #define PG8_MMA(ai, bj, At, Bt) do { __builtin_amdgcn_s_setprio(1); _Pragma("unroll") for (int m = 0; m < 4; ++m) _Pragma("unroll") for (int n = 0; n < 2; ++n) _Pragma("unroll") for (int k = 0; k < 2; ++k) \
;         acc[ai][bj][m][n] = __builtin_amdgcn_mfma_f32_16x16x32_bf16(Bt[n][k], At[m][k], acc[ai][bj][m][n], 0, 0, 0); __builtin_amdgcn_s_setprio(0); } while (0)
; #define PG8_WAIT_V(n) asm volatile("s_waitcnt vmcnt(" #n ")" ::: "memory")
; #define PG8_WAIT_L(n) asm volatile("s_waitcnt lgkmcnt(" #n ")" ::: "memory")
; #define PG8_BAR __builtin_amdgcn_s_barrier()
; #define PG8_SCHED __builtin_amdgcn_sched_barrier(0)
; template <class Epi, class Sched>
; __device__ __forceinline__ void gemm_phase(LAS unsigned char* lds, const Gemm g, const Sched& S, const Epi& E, int wave_id) {
;     ...
;             PG8_WAIT_V(8); PG8_WAIT_L(0); PG8_BAR; PG8_MMA(1, 0, At, B0); PG8_MMA(1, 1, At, B1); PG8_BAR; PG8_SCHED;
;             PG8_LDB(B0, 1, 0); PG8_LDB(B1, 1, 1); PG8_SCHED; PG8_LDA(At, 1, 0); PG8_STAGE(PG8_SA(0, 1), a2 + hstepA, voffA);
;             PG8_WAIT_V(8); PG8_WAIT_L(0); PG8_BAR; PG8_MMA(0, 0, At, B0); PG8_MMA(0, 1, At, B1); PG8_BAR; PG8_SCHED;
;             PG8_LDA(At, 1, 1); PG8_STAGE(PG8_SB(1, 0), b3, voffB); PG8_STAGE(PG8_SB(1, 1), b3 + hstepB, voffB); PG8_STAGE(PG8_SA(1, 0), a3, voffA);
	s_setprio 1
	s_waitcnt lgkmcnt(0)
	v_mfma_f32_16x16x32_bf16 v[60:63], v[142:145], v[180:183], 0
	v_mfma_f32_16x16x32_bf16 v[56:59], v[150:153], v[180:183], 0
	v_mfma_f32_16x16x32_bf16 v[44:47], v[142:145], v[188:191], 0
	v_mfma_f32_16x16x32_bf16 v[40:43], v[150:153], v[188:191], 0
	v_mfma_f32_16x16x32_bf16 v[28:31], v[142:145], v[196:199], 0
	v_mfma_f32_16x16x32_bf16 v[24:27], v[150:153], v[196:199], 0
	v_mfma_f32_16x16x32_bf16 v[12:15], v[142:145], v[204:207], 0
	v_mfma_f32_16x16x32_bf16 v[8:11], v[150:153], v[204:207], 0
	v_mfma_f32_16x16x32_bf16 v[60:63], v[146:149], v[184:187], v[60:63]
	v_mfma_f32_16x16x32_bf16 v[56:59], v[154:157], v[184:187], v[56:59]
	v_mfma_f32_16x16x32_bf16 v[44:47], v[146:149], v[192:195], v[44:47]
	v_mfma_f32_16x16x32_bf16 v[40:43], v[154:157], v[192:195], v[40:43]
	v_mfma_f32_16x16x32_bf16 v[28:31], v[146:149], v[200:203], v[28:31]
	v_mfma_f32_16x16x32_bf16 v[24:27], v[154:157], v[200:203], v[24:27]
	v_mfma_f32_16x16x32_bf16 v[12:15], v[146:149], v[208:211], v[12:15]
	v_mfma_f32_16x16x32_bf16 v[8:11], v[154:157], v[208:211], v[8:11]
	s_setprio 0
	s_setprio 1
	v_mfma_f32_16x16x32_bf16 v[52:55], v[164:167], v[180:183], 0
	v_mfma_f32_16x16x32_bf16 v[48:51], v[172:175], v[180:183], 0
	v_mfma_f32_16x16x32_bf16 v[36:39], v[164:167], v[188:191], 0
	v_mfma_f32_16x16x32_bf16 v[32:35], v[172:175], v[188:191], 0
	v_mfma_f32_16x16x32_bf16 v[20:23], v[164:167], v[196:199], 0
	v_mfma_f32_16x16x32_bf16 v[16:19], v[172:175], v[196:199], 0
	v_mfma_f32_16x16x32_bf16 v[4:7], v[164:167], v[204:207], 0
	v_mfma_f32_16x16x32_bf16 v[0:3], v[172:175], v[204:207], 0
	v_mfma_f32_16x16x32_bf16 v[52:55], v[168:171], v[184:187], v[52:55]
	v_mfma_f32_16x16x32_bf16 v[48:51], v[176:179], v[184:187], v[48:51]
	v_mfma_f32_16x16x32_bf16 v[36:39], v[168:171], v[192:195], v[36:39]
	v_mfma_f32_16x16x32_bf16 v[32:35], v[176:179], v[192:195], v[32:35]
	v_mfma_f32_16x16x32_bf16 v[20:23], v[168:171], v[200:203], v[20:23]
	v_mfma_f32_16x16x32_bf16 v[16:19], v[176:179], v[200:203], v[16:19]
	v_mfma_f32_16x16x32_bf16 v[4:7], v[168:171], v[208:211], v[4:7]
	v_mfma_f32_16x16x32_bf16 v[0:3], v[176:179], v[208:211], v[0:3]
	s_setprio 0
	s_barrier
	s_add_i32 s64, 0, 0x18000
	s_add_i32 s65, 0, 0x1c000
	v_add_u32_e32 v154, s64, v159
	v_add_u32_e32 v176, s65, v159
	ds_read_b128 v[142:145], v154
	ds_read_b128 v[146:149], v154 offset:1024
	ds_read_b128 v[150:153], v154 offset:2048
	ds_read_b128 v[154:157], v154 offset:3072
	ds_read_b128 v[164:167], v176
	ds_read_b128 v[168:171], v176 offset:1024
	ds_read_b128 v[172:175], v176 offset:2048
	ds_read_b128 v[176:179], v176 offset:3072
	s_add_u32 s36, s36, 0x40000
	s_addc_u32 s37, s37, 0
	s_mov_b32 m0, s46
	v_lshl_add_u64 v[220:221], s[36:37], 0, v[128:129]
	ds_read_b128 v[180:183], v163 offset:32768
	ds_read_b128 v[184:187], v163 offset:33792
	ds_read_b128 v[188:191], v163 offset:34816
	ds_read_b128 v[192:195], v163 offset:35840
	ds_read_b128 v[196:199], v163 offset:36864
	ds_read_b128 v[200:203], v163 offset:37888
	ds_read_b128 v[204:207], v163 offset:38912
	ds_read_b128 v[208:211], v163 offset:39936
	global_load_lds_dwordx4 v[220:221], off
	v_lshl_add_u64 v[220:221], s[36:37], 0, v[132:133]
	s_mov_b32 m0, s47
	s_nop 0
	global_load_lds_dwordx4 v[220:221], off
	s_waitcnt vmcnt(8)
	s_waitcnt lgkmcnt(0)
	s_barrier
	s_setprio 1
	s_waitcnt lgkmcnt(0)
	v_mfma_f32_16x16x32_bf16 v[124:127], v[142:145], v[180:183], v[124:127]
	v_mfma_f32_16x16x32_bf16 v[120:123], v[150:153], v[180:183], v[120:123]
	v_mfma_f32_16x16x32_bf16 v[108:111], v[142:145], v[188:191], v[108:111]
	v_mfma_f32_16x16x32_bf16 v[104:107], v[150:153], v[188:191], v[104:107]
	v_mfma_f32_16x16x32_bf16 v[92:95], v[142:145], v[196:199], v[92:95]
	v_mfma_f32_16x16x32_bf16 v[88:91], v[150:153], v[196:199], v[88:91]
	v_mfma_f32_16x16x32_bf16 v[76:79], v[142:145], v[204:207], v[76:79]
	v_mfma_f32_16x16x32_bf16 v[72:75], v[150:153], v[204:207], v[72:75]
	v_mfma_f32_16x16x32_bf16 v[124:127], v[146:149], v[184:187], v[124:127]
	v_mfma_f32_16x16x32_bf16 v[120:123], v[154:157], v[184:187], v[120:123]
	v_mfma_f32_16x16x32_bf16 v[108:111], v[146:149], v[192:195], v[108:111]
	v_mfma_f32_16x16x32_bf16 v[104:107], v[154:157], v[192:195], v[104:107]
	v_mfma_f32_16x16x32_bf16 v[92:95], v[146:149], v[200:203], v[92:95]
	v_mfma_f32_16x16x32_bf16 v[88:91], v[154:157], v[200:203], v[88:91]
	v_mfma_f32_16x16x32_bf16 v[76:79], v[146:149], v[208:211], v[76:79]
	v_mfma_f32_16x16x32_bf16 v[72:75], v[154:157], v[208:211], v[72:75]
	s_setprio 0
	s_setprio 1
	v_mfma_f32_16x16x32_bf16 v[116:119], v[164:167], v[180:183], v[116:119]
	v_mfma_f32_16x16x32_bf16 v[112:115], v[172:175], v[180:183], v[112:115]
	v_mfma_f32_16x16x32_bf16 v[100:103], v[164:167], v[188:191], v[100:103]
	v_mfma_f32_16x16x32_bf16 v[96:99], v[172:175], v[188:191], v[96:99]
	v_mfma_f32_16x16x32_bf16 v[84:87], v[164:167], v[196:199], v[84:87]
	v_mfma_f32_16x16x32_bf16 v[80:83], v[172:175], v[196:199], v[80:83]
	v_mfma_f32_16x16x32_bf16 v[68:71], v[164:167], v[204:207], v[68:71]
	v_mfma_f32_16x16x32_bf16 v[64:67], v[172:175], v[204:207], v[64:67]
	v_mfma_f32_16x16x32_bf16 v[116:119], v[168:171], v[184:187], v[116:119]
	v_mfma_f32_16x16x32_bf16 v[112:115], v[176:179], v[184:187], v[112:115]
	v_mfma_f32_16x16x32_bf16 v[100:103], v[168:171], v[192:195], v[100:103]
	v_mfma_f32_16x16x32_bf16 v[96:99], v[176:179], v[192:195], v[96:99]
	v_mfma_f32_16x16x32_bf16 v[84:87], v[168:171], v[200:203], v[84:87]
	v_mfma_f32_16x16x32_bf16 v[80:83], v[176:179], v[200:203], v[80:83]
	v_mfma_f32_16x16x32_bf16 v[68:71], v[168:171], v[208:211], v[68:71]
	v_mfma_f32_16x16x32_bf16 v[64:67], v[176:179], v[208:211], v[64:67]
	s_setprio 0
	s_barrier
; #define PG8_STAGE(bufoff, gbase, voff) do { _Pragma("unroll") for (int _i = 0; _i < 2; ++_i) \
;         __builtin_amdgcn_global_load_lds((const unsigned*)((const char*)(gbase) + (voff)[_i]), (LAS unsigned*)(lds + (bufoff) + ldsw + _i * 8192), 16, 0, 0); } while (0)
; #define PG8_LDA(dst, b, h) do { _Pragma("unroll") for (int m = 0; m < 4; ++m) _Pragma("unroll") for (int k = 0; k < 2; ++k) dst[m][k] = *(const LAS bf16x8*)(lds + PG8_SA(b, h) + aoff + m * 2048 + k * 1024); } while (0)
; #define PG8_MMA(ai, bj, At, Bt) do { __builtin_amdgcn_s_setprio(1); _Pragma("unroll") for (int m = 0; m < 4; ++m) _Pragma("unroll") for (int n = 0; n < 2; ++n) _Pragma("unroll") for (int k = 0; k < 2; ++k) \
;         acc[ai][bj][m][n] = __builtin_amdgcn_mfma_f32_16x16x32_bf16(Bt[n][k], At[m][k], acc[ai][bj][m][n], 0, 0, 0); __builtin_amdgcn_s_setprio(0); } while (0)
; #define PG8_WAIT_V(n) asm volatile("s_waitcnt vmcnt(" #n ")" ::: "memory")
; #define PG8_WAIT_L(n) asm volatile("s_waitcnt lgkmcnt(" #n ")" ::: "memory")
; #define PG8_BAR __builtin_amdgcn_s_barrier()
; #define PG8_SCHED __builtin_amdgcn_sched_barrier(0)
; template <class Epi, class Sched>
; __device__ __forceinline__ void gemm_phase(LAS unsigned char* lds, const Gemm g, const Sched& S, const Epi& E, int wave_id) {
;     ...
;             PG8_LDA(At, 1, 1); PG8_STAGE(PG8_SB(1, 0), b3, voffB); PG8_STAGE(PG8_SB(1, 1), b3 + hstepB, voffB); PG8_STAGE(PG8_SA(1, 0), a3, voffA);
;             PG8_WAIT_V(8); PG8_WAIT_L(0); PG8_BAR; PG8_MMA(1, 0, At, B0); PG8_MMA(1, 1, At, B1); PG8_BAR; PG8_SCHED;
	s_add_i32 s36, s64, s44
	v_lshl_add_u64 v[212:213], v[212:213], 0, s[6:7]
	s_mov_b32 m0, s36
	ds_read_b128 v[180:183], v163 offset:49152
	ds_read_b128 v[184:187], v163 offset:50176
	ds_read_b128 v[188:191], v163 offset:51200
	ds_read_b128 v[192:195], v163 offset:52224
	ds_read_b128 v[196:199], v163 offset:53248
	ds_read_b128 v[200:203], v163 offset:54272
	ds_read_b128 v[204:207], v163 offset:55296
	ds_read_b128 v[208:211], v163 offset:56320
	global_load_lds_dwordx4 v[212:213], off
	s_add_i32 m0, s36, 0x2000
	s_add_u32 s34, s34, 0x40080
	v_lshl_add_u64 v[212:213], v[214:215], 0, s[6:7]
	s_addc_u32 s35, s35, 0
	s_add_i32 s36, s65, s44
	global_load_lds_dwordx4 v[212:213], off
	v_lshl_add_u64 v[212:213], s[34:35], 0, v[130:131]
	s_mov_b32 m0, s36
	s_nop 0
	global_load_lds_dwordx4 v[212:213], off
	v_lshl_add_u64 v[212:213], s[34:35], 0, v[134:135]
	s_add_i32 m0, s36, 0x2000
	s_nop 0
	global_load_lds_dwordx4 v[212:213], off
	v_lshl_add_u64 v[212:213], v[216:217], 0, s[6:7]
	s_mov_b32 m0, s50
	s_nop 0
	global_load_lds_dwordx4 v[212:213], off
	v_lshl_add_u64 v[212:213], v[218:219], 0, s[6:7]
	s_mov_b32 m0, s51
	s_nop 0
	global_load_lds_dwordx4 v[212:213], off
	s_waitcnt vmcnt(8)
	s_waitcnt lgkmcnt(0)
	s_barrier
	s_setprio 1
	s_waitcnt lgkmcnt(0)
	v_mfma_f32_16x16x32_bf16 v[60:63], v[142:145], v[180:183], v[60:63]
	v_mfma_f32_16x16x32_bf16 v[56:59], v[150:153], v[180:183], v[56:59]
	v_mfma_f32_16x16x32_bf16 v[44:47], v[142:145], v[188:191], v[44:47]
	v_mfma_f32_16x16x32_bf16 v[40:43], v[150:153], v[188:191], v[40:43]
	v_mfma_f32_16x16x32_bf16 v[28:31], v[142:145], v[196:199], v[28:31]
	v_mfma_f32_16x16x32_bf16 v[24:27], v[150:153], v[196:199], v[24:27]
	v_mfma_f32_16x16x32_bf16 v[12:15], v[142:145], v[204:207], v[12:15]
	v_mfma_f32_16x16x32_bf16 v[8:11], v[150:153], v[204:207], v[8:11]
	v_mfma_f32_16x16x32_bf16 v[60:63], v[146:149], v[184:187], v[60:63]
	v_mfma_f32_16x16x32_bf16 v[56:59], v[154:157], v[184:187], v[56:59]
	v_mfma_f32_16x16x32_bf16 v[44:47], v[146:149], v[192:195], v[44:47]
	v_mfma_f32_16x16x32_bf16 v[40:43], v[154:157], v[192:195], v[40:43]
	v_mfma_f32_16x16x32_bf16 v[28:31], v[146:149], v[200:203], v[28:31]
	v_mfma_f32_16x16x32_bf16 v[24:27], v[154:157], v[200:203], v[24:27]
	v_mfma_f32_16x16x32_bf16 v[12:15], v[146:149], v[208:211], v[12:15]
	v_mfma_f32_16x16x32_bf16 v[8:11], v[154:157], v[208:211], v[8:11]
	s_setprio 0
	s_setprio 1
	v_mfma_f32_16x16x32_bf16 v[52:55], v[164:167], v[180:183], v[52:55]
	v_mfma_f32_16x16x32_bf16 v[48:51], v[172:175], v[180:183], v[48:51]
	v_mfma_f32_16x16x32_bf16 v[36:39], v[164:167], v[188:191], v[36:39]
	v_mfma_f32_16x16x32_bf16 v[32:35], v[172:175], v[188:191], v[32:35]
	v_mfma_f32_16x16x32_bf16 v[20:23], v[164:167], v[196:199], v[20:23]
	v_mfma_f32_16x16x32_bf16 v[16:19], v[172:175], v[196:199], v[16:19]
	v_mfma_f32_16x16x32_bf16 v[4:7], v[164:167], v[204:207], v[4:7]
	v_mfma_f32_16x16x32_bf16 v[0:3], v[172:175], v[204:207], v[0:3]
	v_mfma_f32_16x16x32_bf16 v[52:55], v[168:171], v[184:187], v[52:55]
	v_mfma_f32_16x16x32_bf16 v[48:51], v[176:179], v[184:187], v[48:51]
	v_mfma_f32_16x16x32_bf16 v[36:39], v[168:171], v[192:195], v[36:39]
	v_mfma_f32_16x16x32_bf16 v[32:35], v[176:179], v[192:195], v[32:35]
	v_mfma_f32_16x16x32_bf16 v[20:23], v[168:171], v[200:203], v[20:23]
	v_mfma_f32_16x16x32_bf16 v[16:19], v[176:179], v[200:203], v[16:19]
	v_mfma_f32_16x16x32_bf16 v[4:7], v[168:171], v[208:211], v[4:7]
	v_mfma_f32_16x16x32_bf16 v[0:3], v[176:179], v[208:211], v[0:3]
	s_setprio 0
	s_barrier
	s_add_i32 s63, s63, 2
	s_add_u32 s30, s30, 0x100
	s_addc_u32 s31, s31, 0
	s_add_u32 s61, s61, 0x100
	s_addc_u32 s62, s62, 0
	s_cmp_gt_u32 s63, 13

;     __device__ bool next(int i, Unit& u) const { if (r0 + i >= r1) return false; return base.next(r0 + i, u); }
;     __device__ bool next(int i, Unit& u) const { const int L = i * G + c; if (L >= 256) return false; u.pm = L; u.pn = L >> 3; return true; }
; #define PG8_STAGE(bufoff, gbase, voff) do { _Pragma("unroll") for (int _i = 0; _i < 2; ++_i) \
;         __builtin_amdgcn_global_load_lds((const unsigned*)((const char*)(gbase) + (voff)[_i]), (LAS unsigned*)(lds + (bufoff) + ldsw + _i * 8192), 16, 0, 0); } while (0)
; #define PG8_LDA(dst, b, h) do { _Pragma("unroll") for (int m = 0; m < 4; ++m) _Pragma("unroll") for (int k = 0; k < 2; ++k) dst[m][k] = *(const LAS bf16x8*)(lds + PG8_SA(b, h) + aoff + m * 2048 + k * 1024); } while (0)
; #define PG8_LDB(dst, b, h) do { _Pragma("unroll") for (int n = 0; n < 2; ++n) _Pragma("unroll") for (int k = 0; k < 2; ++k) dst[n][k] = *(const LAS bf16x8*)(lds + PG8_SB(b, h) + boff + n * 2048 + k * 1024); } while (0)
; #define PG8_WAIT_V(n) asm volatile("s_waitcnt vmcnt(" #n ")" ::: "memory")
; #define PG8_WAIT_L(n) asm volatile("s_waitcnt lgkmcnt(" #n ")" ::: "memory")
; template <class Epi, class Sched>
; __device__ __forceinline__ void gemm_phase(LAS unsigned char* lds, const Gemm g, const Sched& S, const Epi& E, int wave_id) {
;     ...
;         const bool has_next = S.next(ui + 1, nxt);
;         const char* nA = has_next ? (const char*)g.A + (size_t)nxt.pm * tstepA : cA; const char* nB = has_next ? (const char*)g.Bt + (size_t)nxt.pn * tstepB : cB;
;         for (int t = 0; t < nt; t += 2) {
;             const bool last = (t == nt - 2);
;             const char* a1 = cA + (size_t)(t + 1) * kstep;
;             const char* a2 = last ? nA : cA + (size_t)(t + 2) * kstep; const char* b2 = last ? nB : cB + (size_t)(t + 2) * kstep;
;             const char* a3 = a2 + kstep; const char* b3 = b2 + kstep;
;             PG8_LDB(B0, 0, 0); PG8_LDB(B1, 0, 1); PG8_SCHED; PG8_LDA(At, 0, 0); PG8_STAGE(PG8_SA(1, 1), a1 + hstepA, voffA);
;             PG8_WAIT_V(8); PG8_WAIT_L(0); PG8_BAR; PG8_MMA(0, 0, At, B0); PG8_MMA(0, 1, At, B1); PG8_BAR; PG8_SCHED;
;             PG8_LDA(At, 0, 1); PG8_STAGE(PG8_SB(0, 0), b2, voffB); PG8_STAGE(PG8_SB(0, 1), b2 + hstepB, voffB); PG8_STAGE(PG8_SA(0, 0), a2, voffA);
;             PG8_WAIT_V(8); PG8_WAIT_L(0); PG8_BAR; PG8_MMA(1, 0, At, B0); PG8_MMA(1, 1, At, B1); PG8_BAR; PG8_SCHED;
.LBB0_803:
	s_ashr_i32 s19, s18, 31
	s_andn2_b64 vcc, exec, s[36:37]
	s_lshl_b64 s[22:23], s[18:19], 19
	s_add_u32 s22, s2, s22
	s_addc_u32 s23, s21, s23
	s_and_b64 s[24:25], s[36:37], exec
	s_cselect_b32 s19, s23, s31
	s_cselect_b32 s51, s22, s30
	s_ashr_i32 s17, s16, 31
	s_lshl_b64 s[24:25], s[16:17], 19
	s_add_u32 s24, s33, s24
	s_addc_u32 s25, s38, s25
	v_cndmask_b32_e64 v0, 0, 1, s[36:37]
	s_and_b64 s[36:37], s[36:37], exec
	s_cselect_b32 s17, s25, s35
	s_cselect_b32 s52, s24, s34
	s_add_u32 s30, s30, 0x40080
	s_addc_u32 s31, s31, 0
	v_cmp_ne_u32_e64 s[4:5], 1, v0
	s_add_u32 s53, s34, 0x100
	s_addc_u32 s54, s35, 0
	s_mov_b32 s55, -2
	s_waitcnt vmcnt(0)
	ds_read_b128 v[140:143], v159
	ds_read_b128 v[144:147], v159 offset:1024
	ds_read_b128 v[148:151], v159 offset:2048
	ds_read_b128 v[152:155], v159 offset:3072
	ds_read_b128 v[162:165], v160
	ds_read_b128 v[166:169], v160 offset:1024
	ds_read_b128 v[170:173], v160 offset:2048
	ds_read_b128 v[174:177], v160 offset:3072
	s_add_u32 s34, s30, 0xfffc0080
	s_addc_u32 s35, s31, -1
	s_cmp_eq_u32 s55, 12
	s_cselect_b32 s37, s19, s35
	s_cselect_b32 s36, s51, s34
	s_cselect_b32 s35, s17, s54
	s_cselect_b32 s34, s52, s53
	v_lshl_add_u64 v[210:211], s[30:31], 0, v[136:137]
	s_add_i32 m0, s27, 0xc000
	ds_read_b128 v[178:181], v161
	ds_read_b128 v[182:185], v161 offset:1024
	ds_read_b128 v[186:189], v161 offset:2048
	ds_read_b128 v[190:193], v161 offset:3072
	ds_read_b128 v[194:197], v161 offset:4096
	ds_read_b128 v[198:201], v161 offset:5120
	ds_read_b128 v[202:205], v161 offset:6144
	ds_read_b128 v[206:209], v161 offset:7168
	global_load_lds_dwordx4 v[210:211], off
	v_lshl_add_u64 v[210:211], s[30:31], 0, v[138:139]
	s_add_i32 m0, s27, 0xe000
	s_nop 0
	global_load_lds_dwordx4 v[210:211], off
	s_waitcnt vmcnt(24)
	s_waitcnt lgkmcnt(0)
	s_barrier
	s_setprio 1
	s_waitcnt lgkmcnt(0)
	v_mfma_f32_16x16x32_bf16 v[124:127], v[140:143], v[178:181], 0
	v_mfma_f32_16x16x32_bf16 v[120:123], v[148:151], v[178:181], 0
	v_mfma_f32_16x16x32_bf16 v[108:111], v[140:143], v[186:189], 0
	v_mfma_f32_16x16x32_bf16 v[104:107], v[148:151], v[186:189], 0
	v_mfma_f32_16x16x32_bf16 v[92:95], v[140:143], v[194:197], 0
	v_mfma_f32_16x16x32_bf16 v[88:91], v[148:151], v[194:197], 0
	v_mfma_f32_16x16x32_bf16 v[76:79], v[140:143], v[202:205], 0
	v_mfma_f32_16x16x32_bf16 v[72:75], v[148:151], v[202:205], 0
	v_mfma_f32_16x16x32_bf16 v[124:127], v[144:147], v[182:185], v[124:127]
	v_mfma_f32_16x16x32_bf16 v[120:123], v[152:155], v[182:185], v[120:123]
	v_mfma_f32_16x16x32_bf16 v[108:111], v[144:147], v[190:193], v[108:111]
	v_mfma_f32_16x16x32_bf16 v[104:107], v[152:155], v[190:193], v[104:107]
	v_mfma_f32_16x16x32_bf16 v[92:95], v[144:147], v[198:201], v[92:95]
	v_mfma_f32_16x16x32_bf16 v[88:91], v[152:155], v[198:201], v[88:91]
	v_mfma_f32_16x16x32_bf16 v[76:79], v[144:147], v[206:209], v[76:79]
	v_mfma_f32_16x16x32_bf16 v[72:75], v[152:155], v[206:209], v[72:75]
	s_setprio 0
	s_setprio 1
	v_mfma_f32_16x16x32_bf16 v[116:119], v[162:165], v[178:181], 0
	v_mfma_f32_16x16x32_bf16 v[112:115], v[170:173], v[178:181], 0
	v_mfma_f32_16x16x32_bf16 v[100:103], v[162:165], v[186:189], 0
	v_mfma_f32_16x16x32_bf16 v[96:99], v[170:173], v[186:189], 0
	v_mfma_f32_16x16x32_bf16 v[84:87], v[162:165], v[194:197], 0
	v_mfma_f32_16x16x32_bf16 v[80:83], v[170:173], v[194:197], 0
	v_mfma_f32_16x16x32_bf16 v[68:71], v[162:165], v[202:205], 0
	v_mfma_f32_16x16x32_bf16 v[64:67], v[170:173], v[202:205], 0
	v_mfma_f32_16x16x32_bf16 v[116:119], v[166:169], v[182:185], v[116:119]
	v_mfma_f32_16x16x32_bf16 v[112:115], v[174:177], v[182:185], v[112:115]
	v_mfma_f32_16x16x32_bf16 v[100:103], v[166:169], v[190:193], v[100:103]
	v_mfma_f32_16x16x32_bf16 v[96:99], v[174:177], v[190:193], v[96:99]
	v_mfma_f32_16x16x32_bf16 v[84:87], v[166:169], v[198:201], v[84:87]
	v_mfma_f32_16x16x32_bf16 v[80:83], v[174:177], v[198:201], v[80:83]
	v_mfma_f32_16x16x32_bf16 v[68:71], v[166:169], v[206:209], v[68:71]
	v_mfma_f32_16x16x32_bf16 v[64:67], v[174:177], v[206:209], v[64:67]
	s_setprio 0
	s_barrier
	s_add_i32 s58, s48, s39
	v_lshl_add_u64 v[210:211], s[34:35], 0, v[130:131]
	s_mov_b32 m0, s58
	ds_read_b128 v[178:181], v161 offset:16384
	ds_read_b128 v[182:185], v161 offset:17408
	ds_read_b128 v[186:189], v161 offset:18432
	ds_read_b128 v[190:193], v161 offset:19456
	ds_read_b128 v[194:197], v161 offset:20480
	ds_read_b128 v[198:201], v161 offset:21504
	ds_read_b128 v[202:205], v161 offset:22528
	ds_read_b128 v[206:209], v161 offset:23552
	global_load_lds_dwordx4 v[210:211], off
	s_add_i32 m0, s58, 0x2000
	s_add_u32 s58, s34, 0x40000
	v_lshl_add_u64 v[212:213], s[34:35], 0, v[134:135]
	s_addc_u32 s59, s35, 0
	s_add_i32 s60, s49, s39
	global_load_lds_dwordx4 v[212:213], off
	v_lshl_add_u64 v[214:215], s[58:59], 0, v[130:131]
	s_mov_b32 m0, s60
	v_lshl_add_u64 v[216:217], s[36:37], 0, v[132:133]
	global_load_lds_dwordx4 v[214:215], off
	v_lshl_add_u64 v[214:215], s[58:59], 0, v[134:135]
	s_add_i32 m0, s60, 0x2000
	s_nop 0
	global_load_lds_dwordx4 v[214:215], off
	v_lshl_add_u64 v[214:215], s[36:37], 0, v[128:129]
	s_mov_b32 m0, s27
	s_nop 0
	global_load_lds_dwordx4 v[214:215], off
	s_mov_b32 m0, s29
	s_nop 0
	global_load_lds_dwordx4 v[216:217], off
	s_waitcnt vmcnt(8)
	s_waitcnt lgkmcnt(0)
	s_barrier
; #define PG8_STAGE(bufoff, gbase, voff) do { _Pragma("unroll") for (int _i = 0; _i < 2; ++_i) \
;         __builtin_amdgcn_global_load_lds((const unsigned*)((const char*)(gbase) + (voff)[_i]), (LAS unsigned*)(lds + (bufoff) + ldsw + _i * 8192), 16, 0, 0); } while (0)
; #define PG8_LDA(dst, b, h) do { _Pragma("unroll") for (int m = 0; m < 4; ++m) _Pragma("unroll") for (int k = 0; k < 2; ++k) dst[m][k] = *(const LAS bf16x8*)(lds + PG8_SA(b, h) + aoff + m * 2048 + k * 1024); } while (0)
; #define PG8_LDB(dst, b, h) do { _Pragma("unroll") for (int n = 0; n < 2; ++n) _Pragma("unroll") for (int k = 0; k < 2; ++k) dst[n][k] = *(const LAS bf16x8*)(lds + PG8_SB(b, h) + boff + n * 2048 + k * 1024); } while (0)
; #define PG8_MMA(ai, bj, At, Bt) do { __builtin_amdgcn_s_setprio(1); _Pragma("unroll") for (int m = 0; m < 4; ++m) _Pragma("unroll") for (int n = 0; n < 2; ++n) _Pragma("unroll") for (int k = 0; k < 2; ++k) \
;         acc[ai][bj][m][n] = __builtin_amdgcn_mfma_f32_16x16x32_bf16(Bt[n][k], At[m][k], acc[ai][bj][m][n], 0, 0, 0); __builtin_amdgcn_s_setprio(0); } while (0)
; #define PG8_WAIT_V(n) asm volatile("s_waitcnt vmcnt(" #n ")" ::: "memory")
; #define PG8_WAIT_L(n) asm volatile("s_waitcnt lgkmcnt(" #n ")" ::: "memory")
; #define PG8_BAR __builtin_amdgcn_s_barrier()
; #define PG8_SCHED __builtin_amdgcn_sched_barrier(0)
; template <class Epi, class Sched>
; __device__ __forceinline__ void gemm_phase(LAS unsigned char* lds, const Gemm g, const Sched& S, const Epi& E, int wave_id) {
;     ...
;             PG8_WAIT_V(8); PG8_WAIT_L(0); PG8_BAR; PG8_MMA(1, 0, At, B0); PG8_MMA(1, 1, At, B1); PG8_BAR; PG8_SCHED;
;             PG8_LDB(B0, 1, 0); PG8_LDB(B1, 1, 1); PG8_SCHED; PG8_LDA(At, 1, 0); PG8_STAGE(PG8_SA(0, 1), a2 + hstepA, voffA);
;             PG8_WAIT_V(8); PG8_WAIT_L(0); PG8_BAR; PG8_MMA(0, 0, At, B0); PG8_MMA(0, 1, At, B1); PG8_BAR; PG8_SCHED;
;             PG8_LDA(At, 1, 1); PG8_STAGE(PG8_SB(1, 0), b3, voffB); PG8_STAGE(PG8_SB(1, 1), b3 + hstepB, voffB); PG8_STAGE(PG8_SA(1, 0), a3, voffA);
	s_setprio 1
	s_waitcnt lgkmcnt(0)
	v_mfma_f32_16x16x32_bf16 v[60:63], v[140:143], v[178:181], 0
	v_mfma_f32_16x16x32_bf16 v[56:59], v[148:151], v[178:181], 0
	v_mfma_f32_16x16x32_bf16 v[44:47], v[140:143], v[186:189], 0
	v_mfma_f32_16x16x32_bf16 v[40:43], v[148:151], v[186:189], 0
	v_mfma_f32_16x16x32_bf16 v[28:31], v[140:143], v[194:197], 0
	v_mfma_f32_16x16x32_bf16 v[24:27], v[148:151], v[194:197], 0
	v_mfma_f32_16x16x32_bf16 v[12:15], v[140:143], v[202:205], 0
	v_mfma_f32_16x16x32_bf16 v[8:11], v[148:151], v[202:205], 0
	v_mfma_f32_16x16x32_bf16 v[60:63], v[144:147], v[182:185], v[60:63]
	v_mfma_f32_16x16x32_bf16 v[56:59], v[152:155], v[182:185], v[56:59]
	v_mfma_f32_16x16x32_bf16 v[44:47], v[144:147], v[190:193], v[44:47]
	v_mfma_f32_16x16x32_bf16 v[40:43], v[152:155], v[190:193], v[40:43]
	v_mfma_f32_16x16x32_bf16 v[28:31], v[144:147], v[198:201], v[28:31]
	v_mfma_f32_16x16x32_bf16 v[24:27], v[152:155], v[198:201], v[24:27]
	v_mfma_f32_16x16x32_bf16 v[12:15], v[144:147], v[206:209], v[12:15]
	v_mfma_f32_16x16x32_bf16 v[8:11], v[152:155], v[206:209], v[8:11]
	s_setprio 0
	s_setprio 1
	v_mfma_f32_16x16x32_bf16 v[52:55], v[162:165], v[178:181], 0
	v_mfma_f32_16x16x32_bf16 v[48:51], v[170:173], v[178:181], 0
	v_mfma_f32_16x16x32_bf16 v[36:39], v[162:165], v[186:189], 0
	v_mfma_f32_16x16x32_bf16 v[32:35], v[170:173], v[186:189], 0
	v_mfma_f32_16x16x32_bf16 v[20:23], v[162:165], v[194:197], 0
	v_mfma_f32_16x16x32_bf16 v[16:19], v[170:173], v[194:197], 0
	v_mfma_f32_16x16x32_bf16 v[4:7], v[162:165], v[202:205], 0
	v_mfma_f32_16x16x32_bf16 v[0:3], v[170:173], v[202:205], 0
	v_mfma_f32_16x16x32_bf16 v[52:55], v[166:169], v[182:185], v[52:55]
	v_mfma_f32_16x16x32_bf16 v[48:51], v[174:177], v[182:185], v[48:51]
	v_mfma_f32_16x16x32_bf16 v[36:39], v[166:169], v[190:193], v[36:39]
	v_mfma_f32_16x16x32_bf16 v[32:35], v[174:177], v[190:193], v[32:35]
	v_mfma_f32_16x16x32_bf16 v[20:23], v[166:169], v[198:201], v[20:23]
	v_mfma_f32_16x16x32_bf16 v[16:19], v[174:177], v[198:201], v[16:19]
	v_mfma_f32_16x16x32_bf16 v[4:7], v[166:169], v[206:209], v[4:7]
	v_mfma_f32_16x16x32_bf16 v[0:3], v[174:177], v[206:209], v[0:3]
	s_setprio 0
	s_barrier
	s_add_i32 s58, 0, 0x18000
	s_add_i32 s59, 0, 0x1c000
	v_add_u32_e32 v152, s58, v157
	v_add_u32_e32 v174, s59, v157
	ds_read_b128 v[140:143], v152
	ds_read_b128 v[144:147], v152 offset:1024
	ds_read_b128 v[148:151], v152 offset:2048
	ds_read_b128 v[152:155], v152 offset:3072
	ds_read_b128 v[162:165], v174
	ds_read_b128 v[166:169], v174 offset:1024
	ds_read_b128 v[170:173], v174 offset:2048
	ds_read_b128 v[174:177], v174 offset:3072
	s_add_u32 s36, s36, 0x40000
	s_addc_u32 s37, s37, 0
	s_mov_b32 m0, s44
	v_lshl_add_u64 v[218:219], s[36:37], 0, v[128:129]
	ds_read_b128 v[178:181], v161 offset:32768
	ds_read_b128 v[182:185], v161 offset:33792
	ds_read_b128 v[186:189], v161 offset:34816
	ds_read_b128 v[190:193], v161 offset:35840
	ds_read_b128 v[194:197], v161 offset:36864
	ds_read_b128 v[198:201], v161 offset:37888
	ds_read_b128 v[202:205], v161 offset:38912
	ds_read_b128 v[206:209], v161 offset:39936
	global_load_lds_dwordx4 v[218:219], off
	v_lshl_add_u64 v[218:219], s[36:37], 0, v[132:133]
	s_mov_b32 m0, s45
	s_nop 0
	global_load_lds_dwordx4 v[218:219], off
	s_waitcnt vmcnt(8)
	s_waitcnt lgkmcnt(0)
	s_barrier
	s_setprio 1
	s_waitcnt lgkmcnt(0)
	v_mfma_f32_16x16x32_bf16 v[124:127], v[140:143], v[178:181], v[124:127]
	v_mfma_f32_16x16x32_bf16 v[120:123], v[148:151], v[178:181], v[120:123]
	v_mfma_f32_16x16x32_bf16 v[108:111], v[140:143], v[186:189], v[108:111]
	v_mfma_f32_16x16x32_bf16 v[104:107], v[148:151], v[186:189], v[104:107]
	v_mfma_f32_16x16x32_bf16 v[92:95], v[140:143], v[194:197], v[92:95]
	v_mfma_f32_16x16x32_bf16 v[88:91], v[148:151], v[194:197], v[88:91]
	v_mfma_f32_16x16x32_bf16 v[76:79], v[140:143], v[202:205], v[76:79]
	v_mfma_f32_16x16x32_bf16 v[72:75], v[148:151], v[202:205], v[72:75]
	v_mfma_f32_16x16x32_bf16 v[124:127], v[144:147], v[182:185], v[124:127]
	v_mfma_f32_16x16x32_bf16 v[120:123], v[152:155], v[182:185], v[120:123]
	v_mfma_f32_16x16x32_bf16 v[108:111], v[144:147], v[190:193], v[108:111]
	v_mfma_f32_16x16x32_bf16 v[104:107], v[152:155], v[190:193], v[104:107]
	v_mfma_f32_16x16x32_bf16 v[92:95], v[144:147], v[198:201], v[92:95]
	v_mfma_f32_16x16x32_bf16 v[88:91], v[152:155], v[198:201], v[88:91]
	v_mfma_f32_16x16x32_bf16 v[76:79], v[144:147], v[206:209], v[76:79]
	v_mfma_f32_16x16x32_bf16 v[72:75], v[152:155], v[206:209], v[72:75]
	s_setprio 0
	s_setprio 1
	v_mfma_f32_16x16x32_bf16 v[116:119], v[162:165], v[178:181], v[116:119]
	v_mfma_f32_16x16x32_bf16 v[112:115], v[170:173], v[178:181], v[112:115]
	v_mfma_f32_16x16x32_bf16 v[100:103], v[162:165], v[186:189], v[100:103]
	v_mfma_f32_16x16x32_bf16 v[96:99], v[170:173], v[186:189], v[96:99]
	v_mfma_f32_16x16x32_bf16 v[84:87], v[162:165], v[194:197], v[84:87]
	v_mfma_f32_16x16x32_bf16 v[80:83], v[170:173], v[194:197], v[80:83]
	v_mfma_f32_16x16x32_bf16 v[68:71], v[162:165], v[202:205], v[68:71]
	v_mfma_f32_16x16x32_bf16 v[64:67], v[170:173], v[202:205], v[64:67]
	v_mfma_f32_16x16x32_bf16 v[116:119], v[166:169], v[182:185], v[116:119]
	v_mfma_f32_16x16x32_bf16 v[112:115], v[174:177], v[182:185], v[112:115]
	v_mfma_f32_16x16x32_bf16 v[100:103], v[166:169], v[190:193], v[100:103]
	v_mfma_f32_16x16x32_bf16 v[96:99], v[174:177], v[190:193], v[96:99]
	v_mfma_f32_16x16x32_bf16 v[84:87], v[166:169], v[198:201], v[84:87]
	v_mfma_f32_16x16x32_bf16 v[80:83], v[174:177], v[198:201], v[80:83]
	v_mfma_f32_16x16x32_bf16 v[68:71], v[166:169], v[206:209], v[68:71]
	v_mfma_f32_16x16x32_bf16 v[64:67], v[174:177], v[206:209], v[64:67]
	s_setprio 0
	s_barrier
; #define PG8_STAGE(bufoff, gbase, voff) do { _Pragma("unroll") for (int _i = 0; _i < 2; ++_i) \
;         __builtin_amdgcn_global_load_lds((const unsigned*)((const char*)(gbase) + (voff)[_i]), (LAS unsigned*)(lds + (bufoff) + ldsw + _i * 8192), 16, 0, 0); } while (0)
; #define PG8_LDA(dst, b, h) do { _Pragma("unroll") for (int m = 0; m < 4; ++m) _Pragma("unroll") for (int k = 0; k < 2; ++k) dst[m][k] = *(const LAS bf16x8*)(lds + PG8_SA(b, h) + aoff + m * 2048 + k * 1024); } while (0)
; #define PG8_MMA(ai, bj, At, Bt) do { __builtin_amdgcn_s_setprio(1); _Pragma("unroll") for (int m = 0; m < 4; ++m) _Pragma("unroll") for (int n = 0; n < 2; ++n) _Pragma("unroll") for (int k = 0; k < 2; ++k) \
;         acc[ai][bj][m][n] = __builtin_amdgcn_mfma_f32_16x16x32_bf16(Bt[n][k], At[m][k], acc[ai][bj][m][n], 0, 0, 0); __builtin_amdgcn_s_setprio(0); } while (0)
; #define PG8_WAIT_V(n) asm volatile("s_waitcnt vmcnt(" #n ")" ::: "memory")
; #define PG8_WAIT_L(n) asm volatile("s_waitcnt lgkmcnt(" #n ")" ::: "memory")
; #define PG8_BAR __builtin_amdgcn_s_barrier()
; #define PG8_SCHED __builtin_amdgcn_sched_barrier(0)
; template <class Epi, class Sched>
; __device__ __forceinline__ void gemm_phase(LAS unsigned char* lds, const Gemm g, const Sched& S, const Epi& E, int wave_id) {
;     ...
;             PG8_LDA(At, 1, 1); PG8_STAGE(PG8_SB(1, 0), b3, voffB); PG8_STAGE(PG8_SB(1, 1), b3 + hstepB, voffB); PG8_STAGE(PG8_SA(1, 0), a3, voffA);
;             PG8_WAIT_V(8); PG8_WAIT_L(0); PG8_BAR; PG8_MMA(1, 0, At, B0); PG8_MMA(1, 1, At, B1); PG8_BAR; PG8_SCHED;
	s_add_i32 s36, s58, s39
	v_lshl_add_u64 v[210:211], v[210:211], 0, s[8:9]
	s_mov_b32 m0, s36
	ds_read_b128 v[178:181], v161 offset:49152
	ds_read_b128 v[182:185], v161 offset:50176
	ds_read_b128 v[186:189], v161 offset:51200
	ds_read_b128 v[190:193], v161 offset:52224
	ds_read_b128 v[194:197], v161 offset:53248
	ds_read_b128 v[198:201], v161 offset:54272
	ds_read_b128 v[202:205], v161 offset:55296
	ds_read_b128 v[206:209], v161 offset:56320
	global_load_lds_dwordx4 v[210:211], off
	s_add_i32 m0, s36, 0x2000
	s_add_u32 s34, s34, 0x40080
	v_lshl_add_u64 v[210:211], v[212:213], 0, s[8:9]
	s_addc_u32 s35, s35, 0
	s_add_i32 s36, s59, s39
	global_load_lds_dwordx4 v[210:211], off
	v_lshl_add_u64 v[210:211], s[34:35], 0, v[130:131]
	s_mov_b32 m0, s36
	s_nop 0
	global_load_lds_dwordx4 v[210:211], off
	v_lshl_add_u64 v[210:211], s[34:35], 0, v[134:135]
	s_add_i32 m0, s36, 0x2000
	s_nop 0
	global_load_lds_dwordx4 v[210:211], off
	v_lshl_add_u64 v[210:211], v[214:215], 0, s[8:9]
	s_mov_b32 m0, s46
	s_nop 0
	global_load_lds_dwordx4 v[210:211], off
	v_lshl_add_u64 v[210:211], v[216:217], 0, s[8:9]
	s_mov_b32 m0, s47
	s_nop 0
	global_load_lds_dwordx4 v[210:211], off
	s_waitcnt vmcnt(8)
	s_waitcnt lgkmcnt(0)
	s_barrier
	s_setprio 1
	s_waitcnt lgkmcnt(0)
	v_mfma_f32_16x16x32_bf16 v[60:63], v[140:143], v[178:181], v[60:63]
	v_mfma_f32_16x16x32_bf16 v[56:59], v[148:151], v[178:181], v[56:59]
	v_mfma_f32_16x16x32_bf16 v[44:47], v[140:143], v[186:189], v[44:47]
	v_mfma_f32_16x16x32_bf16 v[40:43], v[148:151], v[186:189], v[40:43]
	v_mfma_f32_16x16x32_bf16 v[28:31], v[140:143], v[194:197], v[28:31]
	v_mfma_f32_16x16x32_bf16 v[24:27], v[148:151], v[194:197], v[24:27]
	v_mfma_f32_16x16x32_bf16 v[12:15], v[140:143], v[202:205], v[12:15]
	v_mfma_f32_16x16x32_bf16 v[8:11], v[148:151], v[202:205], v[8:11]
	v_mfma_f32_16x16x32_bf16 v[60:63], v[144:147], v[182:185], v[60:63]
	v_mfma_f32_16x16x32_bf16 v[56:59], v[152:155], v[182:185], v[56:59]
	v_mfma_f32_16x16x32_bf16 v[44:47], v[144:147], v[190:193], v[44:47]
	v_mfma_f32_16x16x32_bf16 v[40:43], v[152:155], v[190:193], v[40:43]
	v_mfma_f32_16x16x32_bf16 v[28:31], v[144:147], v[198:201], v[28:31]
	v_mfma_f32_16x16x32_bf16 v[24:27], v[152:155], v[198:201], v[24:27]
	v_mfma_f32_16x16x32_bf16 v[12:15], v[144:147], v[206:209], v[12:15]
	v_mfma_f32_16x16x32_bf16 v[8:11], v[152:155], v[206:209], v[8:11]
	s_setprio 0
	s_setprio 1
	v_mfma_f32_16x16x32_bf16 v[52:55], v[162:165], v[178:181], v[52:55]
	v_mfma_f32_16x16x32_bf16 v[48:51], v[170:173], v[178:181], v[48:51]
	v_mfma_f32_16x16x32_bf16 v[36:39], v[162:165], v[186:189], v[36:39]
	v_mfma_f32_16x16x32_bf16 v[32:35], v[170:173], v[186:189], v[32:35]
	v_mfma_f32_16x16x32_bf16 v[20:23], v[162:165], v[194:197], v[20:23]
	v_mfma_f32_16x16x32_bf16 v[16:19], v[170:173], v[194:197], v[16:19]
	v_mfma_f32_16x16x32_bf16 v[4:7], v[162:165], v[202:205], v[4:7]
	v_mfma_f32_16x16x32_bf16 v[0:3], v[170:173], v[202:205], v[0:3]
	v_mfma_f32_16x16x32_bf16 v[52:55], v[166:169], v[182:185], v[52:55]
	v_mfma_f32_16x16x32_bf16 v[48:51], v[174:177], v[182:185], v[48:51]
	v_mfma_f32_16x16x32_bf16 v[36:39], v[166:169], v[190:193], v[36:39]
	v_mfma_f32_16x16x32_bf16 v[32:35], v[174:177], v[190:193], v[32:35]
	v_mfma_f32_16x16x32_bf16 v[20:23], v[166:169], v[198:201], v[20:23]
	v_mfma_f32_16x16x32_bf16 v[16:19], v[174:177], v[198:201], v[16:19]
	v_mfma_f32_16x16x32_bf16 v[4:7], v[166:169], v[206:209], v[4:7]
	v_mfma_f32_16x16x32_bf16 v[0:3], v[174:177], v[206:209], v[0:3]
	s_setprio 0
	s_barrier
	s_add_i32 s55, s55, 2
	s_add_u32 s30, s30, 0x100
	s_addc_u32 s31, s31, 0
	s_add_u32 s53, s53, 0x100
	s_addc_u32 s54, s54, 0
	s_cmp_gt_u32 s55, 13

;     __device__ bool next(int i, Unit& u) const { if (r0 + i >= r1) return false; return base.next(r0 + i, u); }
;     __device__ bool next(int i, Unit& u) const { const int L = i * G + c; if (L >= 256) return false; u.pm = L; u.pn = L >> 3; return true; }
; #define PG8_STAGE(bufoff, gbase, voff) do { _Pragma("unroll") for (int _i = 0; _i < 2; ++_i) \
;         __builtin_amdgcn_global_load_lds((const unsigned*)((const char*)(gbase) + (voff)[_i]), (LAS unsigned*)(lds + (bufoff) + ldsw + _i * 8192), 16, 0, 0); } while (0)
; #define PG8_LDA(dst, b, h) do { _Pragma("unroll") for (int m = 0; m < 4; ++m) _Pragma("unroll") for (int k = 0; k < 2; ++k) dst[m][k] = *(const LAS bf16x8*)(lds + PG8_SA(b, h) + aoff + m * 2048 + k * 1024); } while (0)
; #define PG8_LDB(dst, b, h) do { _Pragma("unroll") for (int n = 0; n < 2; ++n) _Pragma("unroll") for (int k = 0; k < 2; ++k) dst[n][k] = *(const LAS bf16x8*)(lds + PG8_SB(b, h) + boff + n * 2048 + k * 1024); } while (0)
; #define PG8_WAIT_V(n) asm volatile("s_waitcnt vmcnt(" #n ")" ::: "memory")
; #define PG8_WAIT_L(n) asm volatile("s_waitcnt lgkmcnt(" #n ")" ::: "memory")
; template <class Epi, class Sched>
; __device__ __forceinline__ void gemm_phase(LAS unsigned char* lds, const Gemm g, const Sched& S, const Epi& E, int wave_id) {
;     ...
;         const bool has_next = S.next(ui + 1, nxt);
;         const char* nA = has_next ? (const char*)g.A + (size_t)nxt.pm * tstepA : cA; const char* nB = has_next ? (const char*)g.Bt + (size_t)nxt.pn * tstepB : cB;
;         for (int t = 0; t < nt; t += 2) {
;             const bool last = (t == nt - 2);
;             const char* a1 = cA + (size_t)(t + 1) * kstep;
;             const char* a2 = last ? nA : cA + (size_t)(t + 2) * kstep; const char* b2 = last ? nB : cB + (size_t)(t + 2) * kstep;
;             const char* a3 = a2 + kstep; const char* b3 = b2 + kstep;
;             PG8_LDB(B0, 0, 0); PG8_LDB(B1, 0, 1); PG8_SCHED; PG8_LDA(At, 0, 0); PG8_STAGE(PG8_SA(1, 1), a1 + hstepA, voffA);
;             PG8_WAIT_V(8); PG8_WAIT_L(0); PG8_BAR; PG8_MMA(0, 0, At, B0); PG8_MMA(0, 1, At, B1); PG8_BAR; PG8_SCHED;
;             PG8_LDA(At, 0, 1); PG8_STAGE(PG8_SB(0, 0), b2, voffB); PG8_STAGE(PG8_SB(0, 1), b2 + hstepB, voffB); PG8_STAGE(PG8_SA(0, 0), a2, voffA);
;             PG8_WAIT_V(8); PG8_WAIT_L(0); PG8_BAR; PG8_MMA(1, 0, At, B0); PG8_MMA(1, 1, At, B1); PG8_BAR; PG8_SCHED;
.LBB0_862:
	s_ashr_i32 s19, s18, 31
	s_andn2_b64 vcc, exec, s[36:37]
	s_lshl_b64 s[22:23], s[18:19], 19
	s_add_u32 s22, s2, s22
	s_addc_u32 s23, s3, s23
	s_and_b64 s[24:25], s[36:37], exec
	s_cselect_b32 s19, s23, s31
	s_cselect_b32 s46, s22, s30
	s_ashr_i32 s17, s16, 31
	s_lshl_b64 s[24:25], s[16:17], 19
	s_add_u32 s24, s21, s24
	s_addc_u32 s25, s33, s25
	v_cndmask_b32_e64 v0, 0, 1, s[36:37]
	s_and_b64 s[36:37], s[36:37], exec
	s_cselect_b32 s17, s25, s35
	s_cselect_b32 s47, s24, s34
	s_add_u32 s30, s30, 0x40080
	s_addc_u32 s31, s31, 0
	v_cmp_ne_u32_e64 s[4:5], 1, v0
	s_add_u32 s48, s34, 0x100
	s_addc_u32 s49, s35, 0
	s_mov_b32 s50, -2
	s_waitcnt vmcnt(0)
	ds_read_b128 v[140:143], v159
	ds_read_b128 v[144:147], v159 offset:1024
	ds_read_b128 v[148:151], v159 offset:2048
	ds_read_b128 v[152:155], v159 offset:3072
	ds_read_b128 v[162:165], v160
	ds_read_b128 v[166:169], v160 offset:1024
	ds_read_b128 v[170:173], v160 offset:2048
	ds_read_b128 v[174:177], v160 offset:3072
	s_add_u32 s34, s30, 0xfffc0080
	s_addc_u32 s35, s31, -1
	s_cmp_eq_u32 s50, 12
	s_cselect_b32 s37, s19, s35
	s_cselect_b32 s36, s46, s34
	s_cselect_b32 s35, s17, s49
	s_cselect_b32 s34, s47, s48
	v_lshl_add_u64 v[210:211], s[30:31], 0, v[136:137]
	s_add_i32 m0, s27, 0xc000
	ds_read_b128 v[178:181], v161
	ds_read_b128 v[182:185], v161 offset:1024
	ds_read_b128 v[186:189], v161 offset:2048
	ds_read_b128 v[190:193], v161 offset:3072
	ds_read_b128 v[194:197], v161 offset:4096
	ds_read_b128 v[198:201], v161 offset:5120
	ds_read_b128 v[202:205], v161 offset:6144
	ds_read_b128 v[206:209], v161 offset:7168
	global_load_lds_dwordx4 v[210:211], off
	v_lshl_add_u64 v[210:211], s[30:31], 0, v[138:139]
	s_add_i32 m0, s27, 0xe000
	s_nop 0
	global_load_lds_dwordx4 v[210:211], off
	s_waitcnt vmcnt(24)
	s_waitcnt lgkmcnt(0)
	s_barrier
	s_setprio 1
	s_waitcnt lgkmcnt(0)
	v_mfma_f32_16x16x32_bf16 v[124:127], v[140:143], v[178:181], 0
	v_mfma_f32_16x16x32_bf16 v[120:123], v[148:151], v[178:181], 0
	v_mfma_f32_16x16x32_bf16 v[108:111], v[140:143], v[186:189], 0
	v_mfma_f32_16x16x32_bf16 v[104:107], v[148:151], v[186:189], 0
	v_mfma_f32_16x16x32_bf16 v[92:95], v[140:143], v[194:197], 0
	v_mfma_f32_16x16x32_bf16 v[88:91], v[148:151], v[194:197], 0
	v_mfma_f32_16x16x32_bf16 v[76:79], v[140:143], v[202:205], 0
	v_mfma_f32_16x16x32_bf16 v[72:75], v[148:151], v[202:205], 0
	v_mfma_f32_16x16x32_bf16 v[124:127], v[144:147], v[182:185], v[124:127]
	v_mfma_f32_16x16x32_bf16 v[120:123], v[152:155], v[182:185], v[120:123]
	v_mfma_f32_16x16x32_bf16 v[108:111], v[144:147], v[190:193], v[108:111]
	v_mfma_f32_16x16x32_bf16 v[104:107], v[152:155], v[190:193], v[104:107]
	v_mfma_f32_16x16x32_bf16 v[92:95], v[144:147], v[198:201], v[92:95]
	v_mfma_f32_16x16x32_bf16 v[88:91], v[152:155], v[198:201], v[88:91]
	v_mfma_f32_16x16x32_bf16 v[76:79], v[144:147], v[206:209], v[76:79]
	v_mfma_f32_16x16x32_bf16 v[72:75], v[152:155], v[206:209], v[72:75]
	s_setprio 0
	s_setprio 1
	v_mfma_f32_16x16x32_bf16 v[116:119], v[162:165], v[178:181], 0
	v_mfma_f32_16x16x32_bf16 v[112:115], v[170:173], v[178:181], 0
	v_mfma_f32_16x16x32_bf16 v[100:103], v[162:165], v[186:189], 0
	v_mfma_f32_16x16x32_bf16 v[96:99], v[170:173], v[186:189], 0
	v_mfma_f32_16x16x32_bf16 v[84:87], v[162:165], v[194:197], 0
	v_mfma_f32_16x16x32_bf16 v[80:83], v[170:173], v[194:197], 0
	v_mfma_f32_16x16x32_bf16 v[68:71], v[162:165], v[202:205], 0
	v_mfma_f32_16x16x32_bf16 v[64:67], v[170:173], v[202:205], 0
	v_mfma_f32_16x16x32_bf16 v[116:119], v[166:169], v[182:185], v[116:119]
	v_mfma_f32_16x16x32_bf16 v[112:115], v[174:177], v[182:185], v[112:115]
	v_mfma_f32_16x16x32_bf16 v[100:103], v[166:169], v[190:193], v[100:103]
	v_mfma_f32_16x16x32_bf16 v[96:99], v[174:177], v[190:193], v[96:99]
	v_mfma_f32_16x16x32_bf16 v[84:87], v[166:169], v[198:201], v[84:87]
	v_mfma_f32_16x16x32_bf16 v[80:83], v[174:177], v[198:201], v[80:83]
	v_mfma_f32_16x16x32_bf16 v[68:71], v[166:169], v[206:209], v[68:71]
	v_mfma_f32_16x16x32_bf16 v[64:67], v[174:177], v[206:209], v[64:67]
	s_setprio 0
	s_barrier
	s_add_i32 s51, s43, s38
	v_lshl_add_u64 v[210:211], s[34:35], 0, v[130:131]
	s_mov_b32 m0, s51
	ds_read_b128 v[178:181], v161 offset:16384
	ds_read_b128 v[182:185], v161 offset:17408
	ds_read_b128 v[186:189], v161 offset:18432
	ds_read_b128 v[190:193], v161 offset:19456
	ds_read_b128 v[194:197], v161 offset:20480
	ds_read_b128 v[198:201], v161 offset:21504
	ds_read_b128 v[202:205], v161 offset:22528
	ds_read_b128 v[206:209], v161 offset:23552
	global_load_lds_dwordx4 v[210:211], off
	s_add_i32 m0, s51, 0x2000
	s_add_u32 s52, s34, 0x40000
	v_lshl_add_u64 v[212:213], s[34:35], 0, v[134:135]
	s_addc_u32 s53, s35, 0
	s_add_i32 s51, s44, s38
	global_load_lds_dwordx4 v[212:213], off
	v_lshl_add_u64 v[214:215], s[52:53], 0, v[130:131]
	s_mov_b32 m0, s51
	v_lshl_add_u64 v[216:217], s[36:37], 0, v[132:133]
	global_load_lds_dwordx4 v[214:215], off
	v_lshl_add_u64 v[214:215], s[52:53], 0, v[134:135]
	s_add_i32 m0, s51, 0x2000
	s_nop 0
	global_load_lds_dwordx4 v[214:215], off
	v_lshl_add_u64 v[214:215], s[36:37], 0, v[128:129]
	s_mov_b32 m0, s27
	s_nop 0
	global_load_lds_dwordx4 v[214:215], off
	s_mov_b32 m0, s29
	s_nop 0
	global_load_lds_dwordx4 v[216:217], off
	s_waitcnt vmcnt(8)
	s_waitcnt lgkmcnt(0)
	s_barrier
; #define PG8_STAGE(bufoff, gbase, voff) do { _Pragma("unroll") for (int _i = 0; _i < 2; ++_i) \
;         __builtin_amdgcn_global_load_lds((const unsigned*)((const char*)(gbase) + (voff)[_i]), (LAS unsigned*)(lds + (bufoff) + ldsw + _i * 8192), 16, 0, 0); } while (0)
; #define PG8_LDA(dst, b, h) do { _Pragma("unroll") for (int m = 0; m < 4; ++m) _Pragma("unroll") for (int k = 0; k < 2; ++k) dst[m][k] = *(const LAS bf16x8*)(lds + PG8_SA(b, h) + aoff + m * 2048 + k * 1024); } while (0)
; #define PG8_LDB(dst, b, h) do { _Pragma("unroll") for (int n = 0; n < 2; ++n) _Pragma("unroll") for (int k = 0; k < 2; ++k) dst[n][k] = *(const LAS bf16x8*)(lds + PG8_SB(b, h) + boff + n * 2048 + k * 1024); } while (0)
; #define PG8_MMA(ai, bj, At, Bt) do { __builtin_amdgcn_s_setprio(1); _Pragma("unroll") for (int m = 0; m < 4; ++m) _Pragma("unroll") for (int n = 0; n < 2; ++n) _Pragma("unroll") for (int k = 0; k < 2; ++k) \
;         acc[ai][bj][m][n] = __builtin_amdgcn_mfma_f32_16x16x32_bf16(Bt[n][k], At[m][k], acc[ai][bj][m][n], 0, 0, 0); __builtin_amdgcn_s_setprio(0); } while (0)
; #define PG8_WAIT_V(n) asm volatile("s_waitcnt vmcnt(" #n ")" ::: "memory")
; #define PG8_WAIT_L(n) asm volatile("s_waitcnt lgkmcnt(" #n ")" ::: "memory")
; #define PG8_BAR __builtin_amdgcn_s_barrier()
; #define PG8_SCHED __builtin_amdgcn_sched_barrier(0)
; template <class Epi, class Sched>
; __device__ __forceinline__ void gemm_phase(LAS unsigned char* lds, const Gemm g, const Sched& S, const Epi& E, int wave_id) {
;     ...
;             PG8_WAIT_V(8); PG8_WAIT_L(0); PG8_BAR; PG8_MMA(1, 0, At, B0); PG8_MMA(1, 1, At, B1); PG8_BAR; PG8_SCHED;
;             PG8_LDB(B0, 1, 0); PG8_LDB(B1, 1, 1); PG8_SCHED; PG8_LDA(At, 1, 0); PG8_STAGE(PG8_SA(0, 1), a2 + hstepA, voffA);
;             PG8_WAIT_V(8); PG8_WAIT_L(0); PG8_BAR; PG8_MMA(0, 0, At, B0); PG8_MMA(0, 1, At, B1); PG8_BAR; PG8_SCHED;
;             PG8_LDA(At, 1, 1); PG8_STAGE(PG8_SB(1, 0), b3, voffB); PG8_STAGE(PG8_SB(1, 1), b3 + hstepB, voffB); PG8_STAGE(PG8_SA(1, 0), a3, voffA);
	s_setprio 1
	s_waitcnt lgkmcnt(0)
	v_mfma_f32_16x16x32_bf16 v[60:63], v[140:143], v[178:181], 0
	v_mfma_f32_16x16x32_bf16 v[56:59], v[148:151], v[178:181], 0
	v_mfma_f32_16x16x32_bf16 v[44:47], v[140:143], v[186:189], 0
	v_mfma_f32_16x16x32_bf16 v[40:43], v[148:151], v[186:189], 0
	v_mfma_f32_16x16x32_bf16 v[28:31], v[140:143], v[194:197], 0
	v_mfma_f32_16x16x32_bf16 v[24:27], v[148:151], v[194:197], 0
	v_mfma_f32_16x16x32_bf16 v[12:15], v[140:143], v[202:205], 0
	v_mfma_f32_16x16x32_bf16 v[8:11], v[148:151], v[202:205], 0
	v_mfma_f32_16x16x32_bf16 v[60:63], v[144:147], v[182:185], v[60:63]
	v_mfma_f32_16x16x32_bf16 v[56:59], v[152:155], v[182:185], v[56:59]
	v_mfma_f32_16x16x32_bf16 v[44:47], v[144:147], v[190:193], v[44:47]
	v_mfma_f32_16x16x32_bf16 v[40:43], v[152:155], v[190:193], v[40:43]
	v_mfma_f32_16x16x32_bf16 v[28:31], v[144:147], v[198:201], v[28:31]
	v_mfma_f32_16x16x32_bf16 v[24:27], v[152:155], v[198:201], v[24:27]
	v_mfma_f32_16x16x32_bf16 v[12:15], v[144:147], v[206:209], v[12:15]
	v_mfma_f32_16x16x32_bf16 v[8:11], v[152:155], v[206:209], v[8:11]
	s_setprio 0
	s_setprio 1
	v_mfma_f32_16x16x32_bf16 v[52:55], v[162:165], v[178:181], 0
	v_mfma_f32_16x16x32_bf16 v[48:51], v[170:173], v[178:181], 0
	v_mfma_f32_16x16x32_bf16 v[36:39], v[162:165], v[186:189], 0
	v_mfma_f32_16x16x32_bf16 v[32:35], v[170:173], v[186:189], 0
	v_mfma_f32_16x16x32_bf16 v[20:23], v[162:165], v[194:197], 0
	v_mfma_f32_16x16x32_bf16 v[16:19], v[170:173], v[194:197], 0
	v_mfma_f32_16x16x32_bf16 v[4:7], v[162:165], v[202:205], 0
	v_mfma_f32_16x16x32_bf16 v[0:3], v[170:173], v[202:205], 0
	v_mfma_f32_16x16x32_bf16 v[52:55], v[166:169], v[182:185], v[52:55]
	v_mfma_f32_16x16x32_bf16 v[48:51], v[174:177], v[182:185], v[48:51]
	v_mfma_f32_16x16x32_bf16 v[36:39], v[166:169], v[190:193], v[36:39]
	v_mfma_f32_16x16x32_bf16 v[32:35], v[174:177], v[190:193], v[32:35]
	v_mfma_f32_16x16x32_bf16 v[20:23], v[166:169], v[198:201], v[20:23]
	v_mfma_f32_16x16x32_bf16 v[16:19], v[174:177], v[198:201], v[16:19]
	v_mfma_f32_16x16x32_bf16 v[4:7], v[166:169], v[206:209], v[4:7]
	v_mfma_f32_16x16x32_bf16 v[0:3], v[174:177], v[206:209], v[0:3]
	s_setprio 0
	s_barrier
	s_add_i32 s51, 0, 0x18000
	s_add_i32 s52, 0, 0x1c000
	v_add_u32_e32 v152, s51, v157
	v_add_u32_e32 v174, s52, v157
	ds_read_b128 v[140:143], v152
	ds_read_b128 v[144:147], v152 offset:1024
	ds_read_b128 v[148:151], v152 offset:2048
	ds_read_b128 v[152:155], v152 offset:3072
	ds_read_b128 v[162:165], v174
	ds_read_b128 v[166:169], v174 offset:1024
	ds_read_b128 v[170:173], v174 offset:2048
	ds_read_b128 v[174:177], v174 offset:3072
	s_add_u32 s36, s36, 0x40000
	s_addc_u32 s37, s37, 0
	s_mov_b32 m0, s39
	v_lshl_add_u64 v[218:219], s[36:37], 0, v[128:129]
	ds_read_b128 v[178:181], v161 offset:32768
	ds_read_b128 v[182:185], v161 offset:33792
	ds_read_b128 v[186:189], v161 offset:34816
	ds_read_b128 v[190:193], v161 offset:35840
	ds_read_b128 v[194:197], v161 offset:36864
	ds_read_b128 v[198:201], v161 offset:37888
	ds_read_b128 v[202:205], v161 offset:38912
	ds_read_b128 v[206:209], v161 offset:39936
	global_load_lds_dwordx4 v[218:219], off
	v_lshl_add_u64 v[218:219], s[36:37], 0, v[132:133]
	s_mov_b32 m0, s40
	s_nop 0
	global_load_lds_dwordx4 v[218:219], off
	s_waitcnt vmcnt(8)
	s_waitcnt lgkmcnt(0)
	s_barrier
	s_setprio 1
	s_waitcnt lgkmcnt(0)
	v_mfma_f32_16x16x32_bf16 v[124:127], v[140:143], v[178:181], v[124:127]
	v_mfma_f32_16x16x32_bf16 v[120:123], v[148:151], v[178:181], v[120:123]
	v_mfma_f32_16x16x32_bf16 v[108:111], v[140:143], v[186:189], v[108:111]
	v_mfma_f32_16x16x32_bf16 v[104:107], v[148:151], v[186:189], v[104:107]
	v_mfma_f32_16x16x32_bf16 v[92:95], v[140:143], v[194:197], v[92:95]
	v_mfma_f32_16x16x32_bf16 v[88:91], v[148:151], v[194:197], v[88:91]
	v_mfma_f32_16x16x32_bf16 v[76:79], v[140:143], v[202:205], v[76:79]
	v_mfma_f32_16x16x32_bf16 v[72:75], v[148:151], v[202:205], v[72:75]
	v_mfma_f32_16x16x32_bf16 v[124:127], v[144:147], v[182:185], v[124:127]
	v_mfma_f32_16x16x32_bf16 v[120:123], v[152:155], v[182:185], v[120:123]
	v_mfma_f32_16x16x32_bf16 v[108:111], v[144:147], v[190:193], v[108:111]
	v_mfma_f32_16x16x32_bf16 v[104:107], v[152:155], v[190:193], v[104:107]
	v_mfma_f32_16x16x32_bf16 v[92:95], v[144:147], v[198:201], v[92:95]
	v_mfma_f32_16x16x32_bf16 v[88:91], v[152:155], v[198:201], v[88:91]
	v_mfma_f32_16x16x32_bf16 v[76:79], v[144:147], v[206:209], v[76:79]
	v_mfma_f32_16x16x32_bf16 v[72:75], v[152:155], v[206:209], v[72:75]
	s_setprio 0
	s_setprio 1
	v_mfma_f32_16x16x32_bf16 v[116:119], v[162:165], v[178:181], v[116:119]
	v_mfma_f32_16x16x32_bf16 v[112:115], v[170:173], v[178:181], v[112:115]
	v_mfma_f32_16x16x32_bf16 v[100:103], v[162:165], v[186:189], v[100:103]
	v_mfma_f32_16x16x32_bf16 v[96:99], v[170:173], v[186:189], v[96:99]
	v_mfma_f32_16x16x32_bf16 v[84:87], v[162:165], v[194:197], v[84:87]
	v_mfma_f32_16x16x32_bf16 v[80:83], v[170:173], v[194:197], v[80:83]
	v_mfma_f32_16x16x32_bf16 v[68:71], v[162:165], v[202:205], v[68:71]
	v_mfma_f32_16x16x32_bf16 v[64:67], v[170:173], v[202:205], v[64:67]
	v_mfma_f32_16x16x32_bf16 v[116:119], v[166:169], v[182:185], v[116:119]
	v_mfma_f32_16x16x32_bf16 v[112:115], v[174:177], v[182:185], v[112:115]
	v_mfma_f32_16x16x32_bf16 v[100:103], v[166:169], v[190:193], v[100:103]
	v_mfma_f32_16x16x32_bf16 v[96:99], v[174:177], v[190:193], v[96:99]
	v_mfma_f32_16x16x32_bf16 v[84:87], v[166:169], v[198:201], v[84:87]
	v_mfma_f32_16x16x32_bf16 v[80:83], v[174:177], v[198:201], v[80:83]
	v_mfma_f32_16x16x32_bf16 v[68:71], v[166:169], v[206:209], v[68:71]
	v_mfma_f32_16x16x32_bf16 v[64:67], v[174:177], v[206:209], v[64:67]
	s_setprio 0
	s_barrier
; #define PG8_STAGE(bufoff, gbase, voff) do { _Pragma("unroll") for (int _i = 0; _i < 2; ++_i) \
;         __builtin_amdgcn_global_load_lds((const unsigned*)((const char*)(gbase) + (voff)[_i]), (LAS unsigned*)(lds + (bufoff) + ldsw + _i * 8192), 16, 0, 0); } while (0)
; #define PG8_LDA(dst, b, h) do { _Pragma("unroll") for (int m = 0; m < 4; ++m) _Pragma("unroll") for (int k = 0; k < 2; ++k) dst[m][k] = *(const LAS bf16x8*)(lds + PG8_SA(b, h) + aoff + m * 2048 + k * 1024); } while (0)
; #define PG8_MMA(ai, bj, At, Bt) do { __builtin_amdgcn_s_setprio(1); _Pragma("unroll") for (int m = 0; m < 4; ++m) _Pragma("unroll") for (int n = 0; n < 2; ++n) _Pragma("unroll") for (int k = 0; k < 2; ++k) \
;         acc[ai][bj][m][n] = __builtin_amdgcn_mfma_f32_16x16x32_bf16(Bt[n][k], At[m][k], acc[ai][bj][m][n], 0, 0, 0); __builtin_amdgcn_s_setprio(0); } while (0)
; #define PG8_WAIT_V(n) asm volatile("s_waitcnt vmcnt(" #n ")" ::: "memory")
; #define PG8_WAIT_L(n) asm volatile("s_waitcnt lgkmcnt(" #n ")" ::: "memory")
; #define PG8_BAR __builtin_amdgcn_s_barrier()
; #define PG8_SCHED __builtin_amdgcn_sched_barrier(0)
; template <class Epi, class Sched>
; __device__ __forceinline__ void gemm_phase(LAS unsigned char* lds, const Gemm g, const Sched& S, const Epi& E, int wave_id) {
;     ...
;             PG8_LDA(At, 1, 1); PG8_STAGE(PG8_SB(1, 0), b3, voffB); PG8_STAGE(PG8_SB(1, 1), b3 + hstepB, voffB); PG8_STAGE(PG8_SA(1, 0), a3, voffA);
;             PG8_WAIT_V(8); PG8_WAIT_L(0); PG8_BAR; PG8_MMA(1, 0, At, B0); PG8_MMA(1, 1, At, B1); PG8_BAR; PG8_SCHED;
	s_add_i32 s36, s51, s38
	v_lshl_add_u64 v[210:211], v[210:211], 0, s[8:9]
	s_mov_b32 m0, s36
	ds_read_b128 v[178:181], v161 offset:49152
	ds_read_b128 v[182:185], v161 offset:50176
	ds_read_b128 v[186:189], v161 offset:51200
	ds_read_b128 v[190:193], v161 offset:52224
	ds_read_b128 v[194:197], v161 offset:53248
	ds_read_b128 v[198:201], v161 offset:54272
	ds_read_b128 v[202:205], v161 offset:55296
	ds_read_b128 v[206:209], v161 offset:56320
	global_load_lds_dwordx4 v[210:211], off
	s_add_i32 m0, s36, 0x2000
	s_add_u32 s34, s34, 0x40080
	v_lshl_add_u64 v[210:211], v[212:213], 0, s[8:9]
	s_addc_u32 s35, s35, 0
	s_add_i32 s36, s52, s38
	global_load_lds_dwordx4 v[210:211], off
	v_lshl_add_u64 v[210:211], s[34:35], 0, v[130:131]
	s_mov_b32 m0, s36
	s_nop 0
	global_load_lds_dwordx4 v[210:211], off
	v_lshl_add_u64 v[210:211], s[34:35], 0, v[134:135]
	s_add_i32 m0, s36, 0x2000
	s_nop 0
	global_load_lds_dwordx4 v[210:211], off
	v_lshl_add_u64 v[210:211], v[214:215], 0, s[8:9]
	s_mov_b32 m0, s41
	s_nop 0
	global_load_lds_dwordx4 v[210:211], off
	v_lshl_add_u64 v[210:211], v[216:217], 0, s[8:9]
	s_mov_b32 m0, s42
	s_nop 0
	global_load_lds_dwordx4 v[210:211], off
	s_waitcnt vmcnt(8)
	s_waitcnt lgkmcnt(0)
	s_barrier
	s_setprio 1
	s_waitcnt lgkmcnt(0)
	v_mfma_f32_16x16x32_bf16 v[60:63], v[140:143], v[178:181], v[60:63]
	v_mfma_f32_16x16x32_bf16 v[56:59], v[148:151], v[178:181], v[56:59]
	v_mfma_f32_16x16x32_bf16 v[44:47], v[140:143], v[186:189], v[44:47]
	v_mfma_f32_16x16x32_bf16 v[40:43], v[148:151], v[186:189], v[40:43]
	v_mfma_f32_16x16x32_bf16 v[28:31], v[140:143], v[194:197], v[28:31]
	v_mfma_f32_16x16x32_bf16 v[24:27], v[148:151], v[194:197], v[24:27]
	v_mfma_f32_16x16x32_bf16 v[12:15], v[140:143], v[202:205], v[12:15]
	v_mfma_f32_16x16x32_bf16 v[8:11], v[148:151], v[202:205], v[8:11]
	v_mfma_f32_16x16x32_bf16 v[60:63], v[144:147], v[182:185], v[60:63]
	v_mfma_f32_16x16x32_bf16 v[56:59], v[152:155], v[182:185], v[56:59]
	v_mfma_f32_16x16x32_bf16 v[44:47], v[144:147], v[190:193], v[44:47]
	v_mfma_f32_16x16x32_bf16 v[40:43], v[152:155], v[190:193], v[40:43]
	v_mfma_f32_16x16x32_bf16 v[28:31], v[144:147], v[198:201], v[28:31]
	v_mfma_f32_16x16x32_bf16 v[24:27], v[152:155], v[198:201], v[24:27]
	v_mfma_f32_16x16x32_bf16 v[12:15], v[144:147], v[206:209], v[12:15]
	v_mfma_f32_16x16x32_bf16 v[8:11], v[152:155], v[206:209], v[8:11]
	s_setprio 0
	s_setprio 1
	v_mfma_f32_16x16x32_bf16 v[52:55], v[162:165], v[178:181], v[52:55]
	v_mfma_f32_16x16x32_bf16 v[48:51], v[170:173], v[178:181], v[48:51]
	v_mfma_f32_16x16x32_bf16 v[36:39], v[162:165], v[186:189], v[36:39]
	v_mfma_f32_16x16x32_bf16 v[32:35], v[170:173], v[186:189], v[32:35]
	v_mfma_f32_16x16x32_bf16 v[20:23], v[162:165], v[194:197], v[20:23]
	v_mfma_f32_16x16x32_bf16 v[16:19], v[170:173], v[194:197], v[16:19]
	v_mfma_f32_16x16x32_bf16 v[4:7], v[162:165], v[202:205], v[4:7]
	v_mfma_f32_16x16x32_bf16 v[0:3], v[170:173], v[202:205], v[0:3]
	v_mfma_f32_16x16x32_bf16 v[52:55], v[166:169], v[182:185], v[52:55]
	v_mfma_f32_16x16x32_bf16 v[48:51], v[174:177], v[182:185], v[48:51]
	v_mfma_f32_16x16x32_bf16 v[36:39], v[166:169], v[190:193], v[36:39]
	v_mfma_f32_16x16x32_bf16 v[32:35], v[174:177], v[190:193], v[32:35]
	v_mfma_f32_16x16x32_bf16 v[20:23], v[166:169], v[198:201], v[20:23]
	v_mfma_f32_16x16x32_bf16 v[16:19], v[174:177], v[198:201], v[16:19]
	v_mfma_f32_16x16x32_bf16 v[4:7], v[166:169], v[206:209], v[4:7]
	v_mfma_f32_16x16x32_bf16 v[0:3], v[174:177], v[206:209], v[0:3]
	s_setprio 0
	s_barrier
	s_add_i32 s50, s50, 2
	s_add_u32 s30, s30, 0x100
	s_addc_u32 s31, s31, 0
	s_add_u32 s48, s48, 0x100
	s_addc_u32 s49, s49, 0
	s_cmp_gt_u32 s50, 13

;     __device__ bool next(int i, Unit& u) const { if (r0 + i >= r1) return false; return base.next(r0 + i, u); }
;     __device__ bool next(int i, Unit& u) const { const int L = i * G + c; if (L >= 256) return false; u.pm = L; u.pn = L >> 3; return true; }
; #define PG8_STAGE(bufoff, gbase, voff) do { _Pragma("unroll") for (int _i = 0; _i < 2; ++_i) \
;         __builtin_amdgcn_global_load_lds((const unsigned*)((const char*)(gbase) + (voff)[_i]), (LAS unsigned*)(lds + (bufoff) + ldsw + _i * 8192), 16, 0, 0); } while (0)
; #define PG8_LDA(dst, b, h) do { _Pragma("unroll") for (int m = 0; m < 4; ++m) _Pragma("unroll") for (int k = 0; k < 2; ++k) dst[m][k] = *(const LAS bf16x8*)(lds + PG8_SA(b, h) + aoff + m * 2048 + k * 1024); } while (0)
; #define PG8_LDB(dst, b, h) do { _Pragma("unroll") for (int n = 0; n < 2; ++n) _Pragma("unroll") for (int k = 0; k < 2; ++k) dst[n][k] = *(const LAS bf16x8*)(lds + PG8_SB(b, h) + boff + n * 2048 + k * 1024); } while (0)
; #define PG8_WAIT_V(n) asm volatile("s_waitcnt vmcnt(" #n ")" ::: "memory")
; #define PG8_WAIT_L(n) asm volatile("s_waitcnt lgkmcnt(" #n ")" ::: "memory")
; template <class Epi, class Sched>
; __device__ __forceinline__ void gemm_phase(LAS unsigned char* lds, const Gemm g, const Sched& S, const Epi& E, int wave_id) {
;     ...
;         const bool has_next = S.next(ui + 1, nxt);
;         const char* nA = has_next ? (const char*)g.A + (size_t)nxt.pm * tstepA : cA; const char* nB = has_next ? (const char*)g.Bt + (size_t)nxt.pn * tstepB : cB;
;         for (int t = 0; t < nt; t += 2) {
;             const bool last = (t == nt - 2);
;             const char* a1 = cA + (size_t)(t + 1) * kstep;
;             const char* a2 = last ? nA : cA + (size_t)(t + 2) * kstep; const char* b2 = last ? nB : cB + (size_t)(t + 2) * kstep;
;             const char* a3 = a2 + kstep; const char* b3 = b2 + kstep;
;             PG8_LDB(B0, 0, 0); PG8_LDB(B1, 0, 1); PG8_SCHED; PG8_LDA(At, 0, 0); PG8_STAGE(PG8_SA(1, 1), a1 + hstepA, voffA);
;             PG8_WAIT_V(8); PG8_WAIT_L(0); PG8_BAR; PG8_MMA(0, 0, At, B0); PG8_MMA(0, 1, At, B1); PG8_BAR; PG8_SCHED;
;             PG8_LDA(At, 0, 1); PG8_STAGE(PG8_SB(0, 0), b2, voffB); PG8_STAGE(PG8_SB(0, 1), b2 + hstepB, voffB); PG8_STAGE(PG8_SA(0, 0), a2, voffA);
;             PG8_WAIT_V(8); PG8_WAIT_L(0); PG8_BAR; PG8_MMA(1, 0, At, B0); PG8_MMA(1, 1, At, B1); PG8_BAR; PG8_SCHED;
.LBB0_959:
	s_ashr_i32 s17, s16, 31
	s_lshl_b64 s[18:19], s[16:17], 19
	s_add_u32 s18, s31, s18
	s_addc_u32 s19, s34, s19
	s_and_b64 s[20:21], s[4:5], exec
	s_cselect_b32 s17, s19, s25
	s_cselect_b32 s49, s18, s24
	s_ashr_i32 s15, s14, 31
	s_lshl_b64 s[20:21], s[14:15], 19
	s_add_u32 s20, s35, s20
	s_addc_u32 s21, s36, s21
	s_and_b64 s[28:29], s[4:5], exec
	s_cselect_b32 s15, s21, s27
	s_cselect_b32 s50, s20, s26
	s_add_u32 s24, s24, 0x40080
	s_addc_u32 s25, s25, 0
	s_add_u32 s51, s26, 0x100
	s_addc_u32 s52, s27, 0
	s_mov_b32 s53, -2
	ds_read_b128 v[156:159], v151
	ds_read_b128 v[160:163], v151 offset:1024
	ds_read_b128 v[164:167], v151 offset:2048
	ds_read_b128 v[168:171], v151 offset:3072
	ds_read_b128 v[172:175], v152
	ds_read_b128 v[176:179], v152 offset:1024
	ds_read_b128 v[180:183], v152 offset:2048
	ds_read_b128 v[184:187], v152 offset:3072
	s_add_u32 s26, s24, 0xfffc0080
	s_addc_u32 s27, s25, -1
	s_cmp_eq_u32 s53, 12
	s_cselect_b32 s29, s17, s27
	s_cselect_b32 s28, s49, s26
	s_cselect_b32 s27, s15, s52
	s_cselect_b32 s26, s50, s51
	v_lshl_add_u64 v[220:221], s[24:25], 0, v[142:143]
	s_add_i32 m0, s37, 0xc000
	ds_read_b128 v[188:191], v153
	ds_read_b128 v[192:195], v153 offset:1024
	ds_read_b128 v[196:199], v153 offset:2048
	ds_read_b128 v[200:203], v153 offset:3072
	ds_read_b128 v[204:207], v153 offset:4096
	ds_read_b128 v[208:211], v153 offset:5120
	ds_read_b128 v[212:215], v153 offset:6144
	ds_read_b128 v[216:219], v153 offset:7168
	global_load_lds_dwordx4 v[220:221], off
	v_lshl_add_u64 v[220:221], s[24:25], 0, v[144:145]
	s_add_i32 m0, s37, 0xe000
	s_nop 0
	global_load_lds_dwordx4 v[220:221], off
	s_waitcnt vmcnt(24)
	s_waitcnt lgkmcnt(0)
	s_barrier
	s_setprio 1
	s_waitcnt lgkmcnt(0)
	v_mfma_f32_16x16x32_bf16 v[124:127], v[156:159], v[188:191], 0
	v_mfma_f32_16x16x32_bf16 v[120:123], v[164:167], v[188:191], 0
	v_mfma_f32_16x16x32_bf16 v[108:111], v[156:159], v[196:199], 0
	v_mfma_f32_16x16x32_bf16 v[104:107], v[164:167], v[196:199], 0
	v_mfma_f32_16x16x32_bf16 v[92:95], v[156:159], v[204:207], 0
	v_mfma_f32_16x16x32_bf16 v[88:91], v[164:167], v[204:207], 0
	v_mfma_f32_16x16x32_bf16 v[76:79], v[156:159], v[212:215], 0
	v_mfma_f32_16x16x32_bf16 v[72:75], v[164:167], v[212:215], 0
	v_mfma_f32_16x16x32_bf16 v[124:127], v[160:163], v[192:195], v[124:127]
	v_mfma_f32_16x16x32_bf16 v[120:123], v[168:171], v[192:195], v[120:123]
	v_mfma_f32_16x16x32_bf16 v[108:111], v[160:163], v[200:203], v[108:111]
	v_mfma_f32_16x16x32_bf16 v[104:107], v[168:171], v[200:203], v[104:107]
	v_mfma_f32_16x16x32_bf16 v[92:95], v[160:163], v[208:211], v[92:95]
	v_mfma_f32_16x16x32_bf16 v[88:91], v[168:171], v[208:211], v[88:91]
	v_mfma_f32_16x16x32_bf16 v[76:79], v[160:163], v[216:219], v[76:79]
	v_mfma_f32_16x16x32_bf16 v[72:75], v[168:171], v[216:219], v[72:75]
	s_setprio 0
	s_setprio 1
	v_mfma_f32_16x16x32_bf16 v[116:119], v[172:175], v[188:191], 0
	v_mfma_f32_16x16x32_bf16 v[112:115], v[180:183], v[188:191], 0
	v_mfma_f32_16x16x32_bf16 v[100:103], v[172:175], v[196:199], 0
	v_mfma_f32_16x16x32_bf16 v[96:99], v[180:183], v[196:199], 0
	v_mfma_f32_16x16x32_bf16 v[84:87], v[172:175], v[204:207], 0
	v_mfma_f32_16x16x32_bf16 v[80:83], v[180:183], v[204:207], 0
	v_mfma_f32_16x16x32_bf16 v[68:71], v[172:175], v[212:215], 0
	v_mfma_f32_16x16x32_bf16 v[64:67], v[180:183], v[212:215], 0
	v_mfma_f32_16x16x32_bf16 v[116:119], v[176:179], v[192:195], v[116:119]
	v_mfma_f32_16x16x32_bf16 v[112:115], v[184:187], v[192:195], v[112:115]
	v_mfma_f32_16x16x32_bf16 v[100:103], v[176:179], v[200:203], v[100:103]
	v_mfma_f32_16x16x32_bf16 v[96:99], v[184:187], v[200:203], v[96:99]
	v_mfma_f32_16x16x32_bf16 v[84:87], v[176:179], v[208:211], v[84:87]
	v_mfma_f32_16x16x32_bf16 v[80:83], v[184:187], v[208:211], v[80:83]
	v_mfma_f32_16x16x32_bf16 v[68:71], v[176:179], v[216:219], v[68:71]
	v_mfma_f32_16x16x32_bf16 v[64:67], v[184:187], v[216:219], v[64:67]
	s_setprio 0
	s_barrier
	s_add_i32 s54, s47, s2
	v_lshl_add_u64 v[220:221], s[26:27], 0, v[130:131]
	s_mov_b32 m0, s54
	ds_read_b128 v[188:191], v153 offset:16384
	ds_read_b128 v[192:195], v153 offset:17408
	ds_read_b128 v[196:199], v153 offset:18432
	ds_read_b128 v[200:203], v153 offset:19456
	ds_read_b128 v[204:207], v153 offset:20480
	ds_read_b128 v[208:211], v153 offset:21504
	ds_read_b128 v[212:215], v153 offset:22528
	ds_read_b128 v[216:219], v153 offset:23552
	global_load_lds_dwordx4 v[220:221], off
	s_add_i32 m0, s54, 0x2000
	s_add_u32 s54, s26, 0x40000
	v_lshl_add_u64 v[222:223], s[26:27], 0, v[134:135]
	s_addc_u32 s55, s27, 0
	s_add_i32 s58, s48, s2
	global_load_lds_dwordx4 v[222:223], off
	v_lshl_add_u64 v[224:225], s[54:55], 0, v[130:131]
	s_mov_b32 m0, s58
	v_lshl_add_u64 v[226:227], s[28:29], 0, v[132:133]
	global_load_lds_dwordx4 v[224:225], off
	v_lshl_add_u64 v[224:225], s[54:55], 0, v[134:135]
	s_add_i32 m0, s58, 0x2000
	s_nop 0
	global_load_lds_dwordx4 v[224:225], off
	v_lshl_add_u64 v[224:225], s[28:29], 0, v[128:129]
	s_mov_b32 m0, s37
	s_nop 0
	global_load_lds_dwordx4 v[224:225], off
	s_mov_b32 m0, s38
	s_nop 0
	global_load_lds_dwordx4 v[226:227], off
	s_waitcnt vmcnt(8)
	s_waitcnt lgkmcnt(0)
	s_barrier
; #define PG8_STAGE(bufoff, gbase, voff) do { _Pragma("unroll") for (int _i = 0; _i < 2; ++_i) \
;         __builtin_amdgcn_global_load_lds((const unsigned*)((const char*)(gbase) + (voff)[_i]), (LAS unsigned*)(lds + (bufoff) + ldsw + _i * 8192), 16, 0, 0); } while (0)
; #define PG8_LDA(dst, b, h) do { _Pragma("unroll") for (int m = 0; m < 4; ++m) _Pragma("unroll") for (int k = 0; k < 2; ++k) dst[m][k] = *(const LAS bf16x8*)(lds + PG8_SA(b, h) + aoff + m * 2048 + k * 1024); } while (0)
; #define PG8_LDB(dst, b, h) do { _Pragma("unroll") for (int n = 0; n < 2; ++n) _Pragma("unroll") for (int k = 0; k < 2; ++k) dst[n][k] = *(const LAS bf16x8*)(lds + PG8_SB(b, h) + boff + n * 2048 + k * 1024); } while (0)
; #define PG8_MMA(ai, bj, At, Bt) do { __builtin_amdgcn_s_setprio(1); _Pragma("unroll") for (int m = 0; m < 4; ++m) _Pragma("unroll") for (int n = 0; n < 2; ++n) _Pragma("unroll") for (int k = 0; k < 2; ++k) \
;         acc[ai][bj][m][n] = __builtin_amdgcn_mfma_f32_16x16x32_bf16(Bt[n][k], At[m][k], acc[ai][bj][m][n], 0, 0, 0); __builtin_amdgcn_s_setprio(0); } while (0)
; #define PG8_WAIT_V(n) asm volatile("s_waitcnt vmcnt(" #n ")" ::: "memory")
; #define PG8_WAIT_L(n) asm volatile("s_waitcnt lgkmcnt(" #n ")" ::: "memory")
; #define PG8_BAR __builtin_amdgcn_s_barrier()
; #define PG8_SCHED __builtin_amdgcn_sched_barrier(0)
; template <class Epi, class Sched>
; __device__ __forceinline__ void gemm_phase(LAS unsigned char* lds, const Gemm g, const Sched& S, const Epi& E, int wave_id) {
;     ...
;             PG8_WAIT_V(8); PG8_WAIT_L(0); PG8_BAR; PG8_MMA(1, 0, At, B0); PG8_MMA(1, 1, At, B1); PG8_BAR; PG8_SCHED;
;             PG8_LDB(B0, 1, 0); PG8_LDB(B1, 1, 1); PG8_SCHED; PG8_LDA(At, 1, 0); PG8_STAGE(PG8_SA(0, 1), a2 + hstepA, voffA);
;             PG8_WAIT_V(8); PG8_WAIT_L(0); PG8_BAR; PG8_MMA(0, 0, At, B0); PG8_MMA(0, 1, At, B1); PG8_BAR; PG8_SCHED;
	s_setprio 1
	s_waitcnt lgkmcnt(0)
	v_mfma_f32_16x16x32_bf16 v[60:63], v[156:159], v[188:191], 0
	v_mfma_f32_16x16x32_bf16 v[56:59], v[164:167], v[188:191], 0
	v_mfma_f32_16x16x32_bf16 v[44:47], v[156:159], v[196:199], 0
	v_mfma_f32_16x16x32_bf16 v[40:43], v[164:167], v[196:199], 0
	v_mfma_f32_16x16x32_bf16 v[28:31], v[156:159], v[204:207], 0
	v_mfma_f32_16x16x32_bf16 v[24:27], v[164:167], v[204:207], 0
	v_mfma_f32_16x16x32_bf16 v[12:15], v[156:159], v[212:215], 0
	v_mfma_f32_16x16x32_bf16 v[8:11], v[164:167], v[212:215], 0
	v_mfma_f32_16x16x32_bf16 v[60:63], v[160:163], v[192:195], v[60:63]
	v_mfma_f32_16x16x32_bf16 v[56:59], v[168:171], v[192:195], v[56:59]
	v_mfma_f32_16x16x32_bf16 v[44:47], v[160:163], v[200:203], v[44:47]
	v_mfma_f32_16x16x32_bf16 v[40:43], v[168:171], v[200:203], v[40:43]
	v_mfma_f32_16x16x32_bf16 v[28:31], v[160:163], v[208:211], v[28:31]
	v_mfma_f32_16x16x32_bf16 v[24:27], v[168:171], v[208:211], v[24:27]
	v_mfma_f32_16x16x32_bf16 v[12:15], v[160:163], v[216:219], v[12:15]
	v_mfma_f32_16x16x32_bf16 v[8:11], v[168:171], v[216:219], v[8:11]
	s_setprio 0
	s_setprio 1
	v_mfma_f32_16x16x32_bf16 v[52:55], v[172:175], v[188:191], 0
	v_mfma_f32_16x16x32_bf16 v[48:51], v[180:183], v[188:191], 0
	v_mfma_f32_16x16x32_bf16 v[36:39], v[172:175], v[196:199], 0
	v_mfma_f32_16x16x32_bf16 v[32:35], v[180:183], v[196:199], 0
	v_mfma_f32_16x16x32_bf16 v[20:23], v[172:175], v[204:207], 0
	v_mfma_f32_16x16x32_bf16 v[16:19], v[180:183], v[204:207], 0
	v_mfma_f32_16x16x32_bf16 v[4:7], v[172:175], v[212:215], 0
	v_mfma_f32_16x16x32_bf16 v[0:3], v[180:183], v[212:215], 0
	v_mfma_f32_16x16x32_bf16 v[52:55], v[176:179], v[192:195], v[52:55]
	v_mfma_f32_16x16x32_bf16 v[48:51], v[184:187], v[192:195], v[48:51]
	v_mfma_f32_16x16x32_bf16 v[36:39], v[176:179], v[200:203], v[36:39]
	v_mfma_f32_16x16x32_bf16 v[32:35], v[184:187], v[200:203], v[32:35]
	v_mfma_f32_16x16x32_bf16 v[20:23], v[176:179], v[208:211], v[20:23]
	v_mfma_f32_16x16x32_bf16 v[16:19], v[184:187], v[208:211], v[16:19]
	v_mfma_f32_16x16x32_bf16 v[4:7], v[176:179], v[216:219], v[4:7]
	v_mfma_f32_16x16x32_bf16 v[0:3], v[184:187], v[216:219], v[0:3]
	s_setprio 0
	s_barrier
	s_add_i32 s54, 0, 0x18000
	s_add_i32 s55, 0, 0x1c000
	v_add_u32_e32 v168, s54, v150
	v_add_u32_e32 v184, s55, v150
	ds_read_b128 v[156:159], v168
	ds_read_b128 v[160:163], v168 offset:1024
	ds_read_b128 v[164:167], v168 offset:2048
	ds_read_b128 v[168:171], v168 offset:3072
	ds_read_b128 v[172:175], v184
	ds_read_b128 v[176:179], v184 offset:1024
	ds_read_b128 v[180:183], v184 offset:2048
	ds_read_b128 v[184:187], v184 offset:3072
	s_add_u32 s28, s28, 0x40000
	s_addc_u32 s29, s29, 0
	s_mov_b32 m0, s39
	v_lshl_add_u64 v[228:229], s[28:29], 0, v[128:129]
	ds_read_b128 v[188:191], v153 offset:32768
	ds_read_b128 v[192:195], v153 offset:33792
	ds_read_b128 v[196:199], v153 offset:34816
	ds_read_b128 v[200:203], v153 offset:35840
	ds_read_b128 v[204:207], v153 offset:36864
	ds_read_b128 v[208:211], v153 offset:37888
	ds_read_b128 v[212:215], v153 offset:38912
	ds_read_b128 v[216:219], v153 offset:39936
	global_load_lds_dwordx4 v[228:229], off
	v_lshl_add_u64 v[228:229], s[28:29], 0, v[132:133]
	s_mov_b32 m0, s40
	s_nop 0
	global_load_lds_dwordx4 v[228:229], off
	s_waitcnt vmcnt(8)
	s_waitcnt lgkmcnt(0)
	s_barrier
	s_setprio 1
	s_waitcnt lgkmcnt(0)
	v_mfma_f32_16x16x32_bf16 v[124:127], v[156:159], v[188:191], v[124:127]
	v_mfma_f32_16x16x32_bf16 v[120:123], v[164:167], v[188:191], v[120:123]
	v_mfma_f32_16x16x32_bf16 v[108:111], v[156:159], v[196:199], v[108:111]
	v_mfma_f32_16x16x32_bf16 v[104:107], v[164:167], v[196:199], v[104:107]
	v_mfma_f32_16x16x32_bf16 v[92:95], v[156:159], v[204:207], v[92:95]
	v_mfma_f32_16x16x32_bf16 v[88:91], v[164:167], v[204:207], v[88:91]
	v_mfma_f32_16x16x32_bf16 v[76:79], v[156:159], v[212:215], v[76:79]
	v_mfma_f32_16x16x32_bf16 v[72:75], v[164:167], v[212:215], v[72:75]
	v_mfma_f32_16x16x32_bf16 v[124:127], v[160:163], v[192:195], v[124:127]
	v_mfma_f32_16x16x32_bf16 v[120:123], v[168:171], v[192:195], v[120:123]
	v_mfma_f32_16x16x32_bf16 v[108:111], v[160:163], v[200:203], v[108:111]
	v_mfma_f32_16x16x32_bf16 v[104:107], v[168:171], v[200:203], v[104:107]
	v_mfma_f32_16x16x32_bf16 v[92:95], v[160:163], v[208:211], v[92:95]
	v_mfma_f32_16x16x32_bf16 v[88:91], v[168:171], v[208:211], v[88:91]
	v_mfma_f32_16x16x32_bf16 v[76:79], v[160:163], v[216:219], v[76:79]
	v_mfma_f32_16x16x32_bf16 v[72:75], v[168:171], v[216:219], v[72:75]
	s_setprio 0
	s_setprio 1
	v_mfma_f32_16x16x32_bf16 v[116:119], v[172:175], v[188:191], v[116:119]
	v_mfma_f32_16x16x32_bf16 v[112:115], v[180:183], v[188:191], v[112:115]
	v_mfma_f32_16x16x32_bf16 v[100:103], v[172:175], v[196:199], v[100:103]
	v_mfma_f32_16x16x32_bf16 v[96:99], v[180:183], v[196:199], v[96:99]
	v_mfma_f32_16x16x32_bf16 v[84:87], v[172:175], v[204:207], v[84:87]
	v_mfma_f32_16x16x32_bf16 v[80:83], v[180:183], v[204:207], v[80:83]
	v_mfma_f32_16x16x32_bf16 v[68:71], v[172:175], v[212:215], v[68:71]
	v_mfma_f32_16x16x32_bf16 v[64:67], v[180:183], v[212:215], v[64:67]
	v_mfma_f32_16x16x32_bf16 v[116:119], v[176:179], v[192:195], v[116:119]
	v_mfma_f32_16x16x32_bf16 v[112:115], v[184:187], v[192:195], v[112:115]
	v_mfma_f32_16x16x32_bf16 v[100:103], v[176:179], v[200:203], v[100:103]
	v_mfma_f32_16x16x32_bf16 v[96:99], v[184:187], v[200:203], v[96:99]
	v_mfma_f32_16x16x32_bf16 v[84:87], v[176:179], v[208:211], v[84:87]
	v_mfma_f32_16x16x32_bf16 v[80:83], v[184:187], v[208:211], v[80:83]
	v_mfma_f32_16x16x32_bf16 v[68:71], v[176:179], v[216:219], v[68:71]
	v_mfma_f32_16x16x32_bf16 v[64:67], v[184:187], v[216:219], v[64:67]
	s_setprio 0
	s_barrier
; #define PG8_STAGE(bufoff, gbase, voff) do { _Pragma("unroll") for (int _i = 0; _i < 2; ++_i) \
;         __builtin_amdgcn_global_load_lds((const unsigned*)((const char*)(gbase) + (voff)[_i]), (LAS unsigned*)(lds + (bufoff) + ldsw + _i * 8192), 16, 0, 0); } while (0)
; #define PG8_LDA(dst, b, h) do { _Pragma("unroll") for (int m = 0; m < 4; ++m) _Pragma("unroll") for (int k = 0; k < 2; ++k) dst[m][k] = *(const LAS bf16x8*)(lds + PG8_SA(b, h) + aoff + m * 2048 + k * 1024); } while (0)
; #define PG8_MMA(ai, bj, At, Bt) do { __builtin_amdgcn_s_setprio(1); _Pragma("unroll") for (int m = 0; m < 4; ++m) _Pragma("unroll") for (int n = 0; n < 2; ++n) _Pragma("unroll") for (int k = 0; k < 2; ++k) \
;         acc[ai][bj][m][n] = __builtin_amdgcn_mfma_f32_16x16x32_bf16(Bt[n][k], At[m][k], acc[ai][bj][m][n], 0, 0, 0); __builtin_amdgcn_s_setprio(0); } while (0)
; #define PG8_WAIT_V(n) asm volatile("s_waitcnt vmcnt(" #n ")" ::: "memory")
; #define PG8_WAIT_L(n) asm volatile("s_waitcnt lgkmcnt(" #n ")" ::: "memory")
; #define PG8_BAR __builtin_amdgcn_s_barrier()
; #define PG8_SCHED __builtin_amdgcn_sched_barrier(0)
; template <class Epi, class Sched>
; __device__ __forceinline__ void gemm_phase(LAS unsigned char* lds, const Gemm g, const Sched& S, const Epi& E, int wave_id) {
;     ...
;             PG8_LDA(At, 1, 1); PG8_STAGE(PG8_SB(1, 0), b3, voffB); PG8_STAGE(PG8_SB(1, 1), b3 + hstepB, voffB); PG8_STAGE(PG8_SA(1, 0), a3, voffA);
;             PG8_WAIT_V(8); PG8_WAIT_L(0); PG8_BAR; PG8_MMA(1, 0, At, B0); PG8_MMA(1, 1, At, B1); PG8_BAR; PG8_SCHED;
;         }
	s_add_i32 s28, s54, s2
	v_lshl_add_u64 v[220:221], v[220:221], 0, s[10:11]
	s_mov_b32 m0, s28
	ds_read_b128 v[188:191], v153 offset:49152
	ds_read_b128 v[192:195], v153 offset:50176
	ds_read_b128 v[196:199], v153 offset:51200
	ds_read_b128 v[200:203], v153 offset:52224
	ds_read_b128 v[204:207], v153 offset:53248
	ds_read_b128 v[208:211], v153 offset:54272
	ds_read_b128 v[212:215], v153 offset:55296
	ds_read_b128 v[216:219], v153 offset:56320
	global_load_lds_dwordx4 v[220:221], off
	s_add_i32 m0, s28, 0x2000
	s_add_u32 s26, s26, 0x40080
	v_lshl_add_u64 v[220:221], v[222:223], 0, s[10:11]
	s_addc_u32 s27, s27, 0
	s_add_i32 s28, s55, s2
	global_load_lds_dwordx4 v[220:221], off
	v_lshl_add_u64 v[220:221], s[26:27], 0, v[130:131]
	s_mov_b32 m0, s28
	s_nop 0
	global_load_lds_dwordx4 v[220:221], off
	v_lshl_add_u64 v[220:221], s[26:27], 0, v[134:135]
	s_add_i32 m0, s28, 0x2000
	s_nop 0
	global_load_lds_dwordx4 v[220:221], off
	v_lshl_add_u64 v[220:221], v[224:225], 0, s[10:11]
	s_mov_b32 m0, s45
	s_nop 0
	global_load_lds_dwordx4 v[220:221], off
	v_lshl_add_u64 v[220:221], v[226:227], 0, s[10:11]
	s_mov_b32 m0, s46
	s_nop 0
	global_load_lds_dwordx4 v[220:221], off
	s_waitcnt vmcnt(8)
	s_waitcnt lgkmcnt(0)
	s_barrier
	s_setprio 1
	s_waitcnt lgkmcnt(0)
	v_mfma_f32_16x16x32_bf16 v[60:63], v[156:159], v[188:191], v[60:63]
	v_mfma_f32_16x16x32_bf16 v[56:59], v[164:167], v[188:191], v[56:59]
	v_mfma_f32_16x16x32_bf16 v[44:47], v[156:159], v[196:199], v[44:47]
	v_mfma_f32_16x16x32_bf16 v[40:43], v[164:167], v[196:199], v[40:43]
	v_mfma_f32_16x16x32_bf16 v[28:31], v[156:159], v[204:207], v[28:31]
	v_mfma_f32_16x16x32_bf16 v[24:27], v[164:167], v[204:207], v[24:27]
	v_mfma_f32_16x16x32_bf16 v[12:15], v[156:159], v[212:215], v[12:15]
	v_mfma_f32_16x16x32_bf16 v[8:11], v[164:167], v[212:215], v[8:11]
	v_mfma_f32_16x16x32_bf16 v[60:63], v[160:163], v[192:195], v[60:63]
	v_mfma_f32_16x16x32_bf16 v[56:59], v[168:171], v[192:195], v[56:59]
	v_mfma_f32_16x16x32_bf16 v[44:47], v[160:163], v[200:203], v[44:47]
	v_mfma_f32_16x16x32_bf16 v[40:43], v[168:171], v[200:203], v[40:43]
	v_mfma_f32_16x16x32_bf16 v[28:31], v[160:163], v[208:211], v[28:31]
	v_mfma_f32_16x16x32_bf16 v[24:27], v[168:171], v[208:211], v[24:27]
	v_mfma_f32_16x16x32_bf16 v[12:15], v[160:163], v[216:219], v[12:15]
	v_mfma_f32_16x16x32_bf16 v[8:11], v[168:171], v[216:219], v[8:11]
	s_setprio 0
	s_setprio 1
	v_mfma_f32_16x16x32_bf16 v[52:55], v[172:175], v[188:191], v[52:55]
	v_mfma_f32_16x16x32_bf16 v[48:51], v[180:183], v[188:191], v[48:51]
	v_mfma_f32_16x16x32_bf16 v[36:39], v[172:175], v[196:199], v[36:39]
	v_mfma_f32_16x16x32_bf16 v[32:35], v[180:183], v[196:199], v[32:35]
	v_mfma_f32_16x16x32_bf16 v[20:23], v[172:175], v[204:207], v[20:23]
	v_mfma_f32_16x16x32_bf16 v[16:19], v[180:183], v[204:207], v[16:19]
	v_mfma_f32_16x16x32_bf16 v[4:7], v[172:175], v[212:215], v[4:7]
	v_mfma_f32_16x16x32_bf16 v[0:3], v[180:183], v[212:215], v[0:3]
	v_mfma_f32_16x16x32_bf16 v[52:55], v[176:179], v[192:195], v[52:55]
	v_mfma_f32_16x16x32_bf16 v[48:51], v[184:187], v[192:195], v[48:51]
	v_mfma_f32_16x16x32_bf16 v[36:39], v[176:179], v[200:203], v[36:39]
	v_mfma_f32_16x16x32_bf16 v[32:35], v[184:187], v[200:203], v[32:35]
	v_mfma_f32_16x16x32_bf16 v[20:23], v[176:179], v[208:211], v[20:23]
	v_mfma_f32_16x16x32_bf16 v[16:19], v[184:187], v[208:211], v[16:19]
	v_mfma_f32_16x16x32_bf16 v[4:7], v[176:179], v[216:219], v[4:7]
	v_mfma_f32_16x16x32_bf16 v[0:3], v[184:187], v[216:219], v[0:3]
	s_setprio 0
	s_barrier
	s_add_i32 s53, s53, 2
	s_add_u32 s24, s24, 0x100
	s_addc_u32 s25, s25, 0
	s_add_u32 s51, s51, 0x100
	s_addc_u32 s52, s52, 0
	s_cmp_gt_u32 s53, 13

;     __device__ bool next(int i, Unit& u) const { if (r0 + i >= r1) return false; return base.next(r0 + i, u); }
;     __device__ bool next(int i, Unit& u) const { const int L = i * G + c; if (L >= 256) return false; u.pm = L; u.pn = L >> 3; return true; }
; #define PG8_STAGE(bufoff, gbase, voff) do { _Pragma("unroll") for (int _i = 0; _i < 2; ++_i) \
;         __builtin_amdgcn_global_load_lds((const unsigned*)((const char*)(gbase) + (voff)[_i]), (LAS unsigned*)(lds + (bufoff) + ldsw + _i * 8192), 16, 0, 0); } while (0)
; #define PG8_LDA(dst, b, h) do { _Pragma("unroll") for (int m = 0; m < 4; ++m) _Pragma("unroll") for (int k = 0; k < 2; ++k) dst[m][k] = *(const LAS bf16x8*)(lds + PG8_SA(b, h) + aoff + m * 2048 + k * 1024); } while (0)
; #define PG8_LDB(dst, b, h) do { _Pragma("unroll") for (int n = 0; n < 2; ++n) _Pragma("unroll") for (int k = 0; k < 2; ++k) dst[n][k] = *(const LAS bf16x8*)(lds + PG8_SB(b, h) + boff + n * 2048 + k * 1024); } while (0)
; #define PG8_WAIT_V(n) asm volatile("s_waitcnt vmcnt(" #n ")" ::: "memory")
; #define PG8_WAIT_L(n) asm volatile("s_waitcnt lgkmcnt(" #n ")" ::: "memory")
; template <class Epi, class Sched>
; __device__ __forceinline__ void gemm_phase(LAS unsigned char* lds, const Gemm g, const Sched& S, const Epi& E, int wave_id) {
;     ...
;         const bool has_next = S.next(ui + 1, nxt);
;         const char* nA = has_next ? (const char*)g.A + (size_t)nxt.pm * tstepA : cA; const char* nB = has_next ? (const char*)g.Bt + (size_t)nxt.pn * tstepB : cB;
;         for (int t = 0; t < nt; t += 2) {
;             const bool last = (t == nt - 2);
;             const char* a1 = cA + (size_t)(t + 1) * kstep;
;             const char* a2 = last ? nA : cA + (size_t)(t + 2) * kstep; const char* b2 = last ? nB : cB + (size_t)(t + 2) * kstep;
;             const char* a3 = a2 + kstep; const char* b3 = b2 + kstep;
;             PG8_LDB(B0, 0, 0); PG8_LDB(B1, 0, 1); PG8_SCHED; PG8_LDA(At, 0, 0); PG8_STAGE(PG8_SA(1, 1), a1 + hstepA, voffA);
;             PG8_WAIT_V(8); PG8_WAIT_L(0); PG8_BAR; PG8_MMA(0, 0, At, B0); PG8_MMA(0, 1, At, B1); PG8_BAR; PG8_SCHED;
;             PG8_LDA(At, 0, 1); PG8_STAGE(PG8_SB(0, 0), b2, voffB); PG8_STAGE(PG8_SB(0, 1), b2 + hstepB, voffB); PG8_STAGE(PG8_SA(0, 0), a2, voffA);
;             PG8_WAIT_V(8); PG8_WAIT_L(0); PG8_BAR; PG8_MMA(1, 0, At, B0); PG8_MMA(1, 1, At, B1); PG8_BAR; PG8_SCHED;
.LBB0_1040:
	s_ashr_i32 s19, s18, 31
	s_lshl_b64 s[20:21], s[18:19], 18
	s_add_u32 s20, s3, s20
	s_addc_u32 s21, s33, s21
	s_and_b64 s[22:23], s[4:5], exec
	s_cselect_b32 s19, s21, s27
	s_cselect_b32 s48, s20, s26
	s_ashr_i32 s17, s16, 31
	s_lshl_b64 s[22:23], s[16:17], 18
	s_add_u32 s22, s34, s22
	s_addc_u32 s23, s35, s23
	s_and_b64 s[30:31], s[4:5], exec
	s_cselect_b32 s17, s23, s29
	s_cselect_b32 s49, s22, s28
	s_add_u32 s26, s26, 0x20080
	s_addc_u32 s27, s27, 0
	s_add_u32 s50, s28, 0x100
	s_addc_u32 s51, s29, 0
	s_mov_b32 s52, -2
	s_waitcnt vmcnt(0)
	ds_read_b128 v[116:119], v201
	ds_read_b128 v[120:123], v201 offset:1024
	ds_read_b128 v[124:127], v201 offset:2048
	ds_read_b128 v[136:139], v201 offset:3072
	ds_read_b128 v[140:143], v202
	ds_read_b128 v[148:151], v202 offset:1024
	ds_read_b128 v[152:155], v202 offset:2048
	ds_read_b128 v[156:159], v202 offset:3072
	s_add_u32 s28, s26, 0xfffe0080
	s_addc_u32 s29, s27, -1
	s_cmp_eq_u32 s52, 4
	s_cselect_b32 s31, s19, s29
	s_cselect_b32 s30, s48, s28
	s_cselect_b32 s29, s17, s51
	s_cselect_b32 s28, s49, s50
	v_lshl_add_u64 v[216:217], s[26:27], 0, v[178:179]
	s_add_i32 m0, s25, 0xc000
	ds_read_b128 v[160:163], v203
	ds_read_b128 v[164:167], v203 offset:1024
	ds_read_b128 v[186:189], v203 offset:2048
	ds_read_b128 v[190:193], v203 offset:3072
	ds_read_b128 v[194:197], v203 offset:4096
	ds_read_b128 v[204:207], v203 offset:5120
	ds_read_b128 v[208:211], v203 offset:6144
	ds_read_b128 v[212:215], v203 offset:7168
	global_load_lds_dwordx4 v[216:217], off
	v_lshl_add_u64 v[216:217], s[26:27], 0, v[180:181]
	s_add_i32 m0, s25, 0xe000
	s_nop 0
	global_load_lds_dwordx4 v[216:217], off
	s_waitcnt vmcnt(16)
	s_waitcnt lgkmcnt(0)
	s_barrier
	s_setprio 1
	s_waitcnt lgkmcnt(0)
	v_mfma_f32_16x16x32_bf16 v[144:147], v[116:119], v[160:163], 0
	v_mfma_f32_16x16x32_bf16 v[128:131], v[124:127], v[160:163], 0
	v_mfma_f32_16x16x32_bf16 v[108:111], v[116:119], v[186:189], 0
	v_mfma_f32_16x16x32_bf16 v[100:103], v[124:127], v[186:189], 0
	v_mfma_f32_16x16x32_bf16 v[92:95], v[116:119], v[194:197], 0
	v_mfma_f32_16x16x32_bf16 v[84:87], v[124:127], v[194:197], 0
	v_mfma_f32_16x16x32_bf16 v[76:79], v[116:119], v[208:211], 0
	v_mfma_f32_16x16x32_bf16 v[68:71], v[124:127], v[208:211], 0
	v_mfma_f32_16x16x32_bf16 v[144:147], v[120:123], v[164:167], v[144:147]
	v_mfma_f32_16x16x32_bf16 v[128:131], v[136:139], v[164:167], v[128:131]
	v_mfma_f32_16x16x32_bf16 v[108:111], v[120:123], v[190:193], v[108:111]
	v_mfma_f32_16x16x32_bf16 v[100:103], v[136:139], v[190:193], v[100:103]
	v_mfma_f32_16x16x32_bf16 v[92:95], v[120:123], v[204:207], v[92:95]
	v_mfma_f32_16x16x32_bf16 v[84:87], v[136:139], v[204:207], v[84:87]
	v_mfma_f32_16x16x32_bf16 v[76:79], v[120:123], v[212:215], v[76:79]
	v_mfma_f32_16x16x32_bf16 v[68:71], v[136:139], v[212:215], v[68:71]
	s_setprio 0
	s_setprio 1
	v_mfma_f32_16x16x32_bf16 v[132:135], v[140:143], v[160:163], 0
	v_mfma_f32_16x16x32_bf16 v[112:115], v[152:155], v[160:163], 0
	v_mfma_f32_16x16x32_bf16 v[104:107], v[140:143], v[186:189], 0
	v_mfma_f32_16x16x32_bf16 v[96:99], v[152:155], v[186:189], 0
	v_mfma_f32_16x16x32_bf16 v[88:91], v[140:143], v[194:197], 0
	v_mfma_f32_16x16x32_bf16 v[80:83], v[152:155], v[194:197], 0
	v_mfma_f32_16x16x32_bf16 v[72:75], v[140:143], v[208:211], 0
	v_mfma_f32_16x16x32_bf16 v[64:67], v[152:155], v[208:211], 0
	v_mfma_f32_16x16x32_bf16 v[132:135], v[148:151], v[164:167], v[132:135]
	v_mfma_f32_16x16x32_bf16 v[112:115], v[156:159], v[164:167], v[112:115]
	v_mfma_f32_16x16x32_bf16 v[104:107], v[148:151], v[190:193], v[104:107]
	v_mfma_f32_16x16x32_bf16 v[96:99], v[156:159], v[190:193], v[96:99]
	v_mfma_f32_16x16x32_bf16 v[88:91], v[148:151], v[204:207], v[88:91]
	v_mfma_f32_16x16x32_bf16 v[80:83], v[156:159], v[204:207], v[80:83]
	v_mfma_f32_16x16x32_bf16 v[72:75], v[148:151], v[212:215], v[72:75]
	v_mfma_f32_16x16x32_bf16 v[64:67], v[156:159], v[212:215], v[64:67]
	s_setprio 0
	s_barrier
	s_add_i32 s53, s45, s36
	v_lshl_add_u64 v[216:217], s[28:29], 0, v[170:171]
	s_mov_b32 m0, s53
	ds_read_b128 v[160:163], v203 offset:16384
	ds_read_b128 v[164:167], v203 offset:17408
	ds_read_b128 v[186:189], v203 offset:18432
	ds_read_b128 v[190:193], v203 offset:19456
	ds_read_b128 v[194:197], v203 offset:20480
	ds_read_b128 v[204:207], v203 offset:21504
	ds_read_b128 v[208:211], v203 offset:22528
	ds_read_b128 v[212:215], v203 offset:23552
	global_load_lds_dwordx4 v[216:217], off
	s_add_i32 m0, s53, 0x2000
	s_add_u32 s54, s28, 0x20000
	v_lshl_add_u64 v[218:219], s[28:29], 0, v[174:175]
	s_addc_u32 s55, s29, 0
	s_add_i32 s53, s46, s36
	global_load_lds_dwordx4 v[218:219], off
	v_lshl_add_u64 v[220:221], s[54:55], 0, v[170:171]
	s_mov_b32 m0, s53
	v_lshl_add_u64 v[222:223], s[30:31], 0, v[172:173]
	global_load_lds_dwordx4 v[220:221], off
	v_lshl_add_u64 v[220:221], s[54:55], 0, v[174:175]
	s_add_i32 m0, s53, 0x2000
	s_nop 0
	global_load_lds_dwordx4 v[220:221], off
	v_lshl_add_u64 v[220:221], s[30:31], 0, v[168:169]
	s_mov_b32 m0, s25
	s_nop 0
	global_load_lds_dwordx4 v[220:221], off
	s_mov_b32 m0, s37
	s_nop 0
	global_load_lds_dwordx4 v[222:223], off
	s_waitcnt vmcnt(8)
	s_waitcnt lgkmcnt(0)
	s_barrier
; #define PG8_STAGE(bufoff, gbase, voff) do { _Pragma("unroll") for (int _i = 0; _i < 2; ++_i) \
;         __builtin_amdgcn_global_load_lds((const unsigned*)((const char*)(gbase) + (voff)[_i]), (LAS unsigned*)(lds + (bufoff) + ldsw + _i * 8192), 16, 0, 0); } while (0)
; #define PG8_LDA(dst, b, h) do { _Pragma("unroll") for (int m = 0; m < 4; ++m) _Pragma("unroll") for (int k = 0; k < 2; ++k) dst[m][k] = *(const LAS bf16x8*)(lds + PG8_SA(b, h) + aoff + m * 2048 + k * 1024); } while (0)
; #define PG8_LDB(dst, b, h) do { _Pragma("unroll") for (int n = 0; n < 2; ++n) _Pragma("unroll") for (int k = 0; k < 2; ++k) dst[n][k] = *(const LAS bf16x8*)(lds + PG8_SB(b, h) + boff + n * 2048 + k * 1024); } while (0)
; #define PG8_MMA(ai, bj, At, Bt) do { __builtin_amdgcn_s_setprio(1); _Pragma("unroll") for (int m = 0; m < 4; ++m) _Pragma("unroll") for (int n = 0; n < 2; ++n) _Pragma("unroll") for (int k = 0; k < 2; ++k) \
;         acc[ai][bj][m][n] = __builtin_amdgcn_mfma_f32_16x16x32_bf16(Bt[n][k], At[m][k], acc[ai][bj][m][n], 0, 0, 0); __builtin_amdgcn_s_setprio(0); } while (0)
; #define PG8_WAIT_V(n) asm volatile("s_waitcnt vmcnt(" #n ")" ::: "memory")
; #define PG8_WAIT_L(n) asm volatile("s_waitcnt lgkmcnt(" #n ")" ::: "memory")
; #define PG8_BAR __builtin_amdgcn_s_barrier()
; #define PG8_SCHED __builtin_amdgcn_sched_barrier(0)
; template <class Epi, class Sched>
; __device__ __forceinline__ void gemm_phase(LAS unsigned char* lds, const Gemm g, const Sched& S, const Epi& E, int wave_id) {
;     ...
;             PG8_WAIT_V(8); PG8_WAIT_L(0); PG8_BAR; PG8_MMA(1, 0, At, B0); PG8_MMA(1, 1, At, B1); PG8_BAR; PG8_SCHED;
;             PG8_LDB(B0, 1, 0); PG8_LDB(B1, 1, 1); PG8_SCHED; PG8_LDA(At, 1, 0); PG8_STAGE(PG8_SA(0, 1), a2 + hstepA, voffA);
;             PG8_WAIT_V(8); PG8_WAIT_L(0); PG8_BAR; PG8_MMA(0, 0, At, B0); PG8_MMA(0, 1, At, B1); PG8_BAR; PG8_SCHED;
	s_setprio 1
	s_waitcnt lgkmcnt(0)
	v_mfma_f32_16x16x32_bf16 v[60:63], v[116:119], v[160:163], 0
	v_mfma_f32_16x16x32_bf16 v[52:55], v[124:127], v[160:163], 0
	v_mfma_f32_16x16x32_bf16 v[44:47], v[116:119], v[186:189], 0
	v_mfma_f32_16x16x32_bf16 v[36:39], v[124:127], v[186:189], 0
	v_mfma_f32_16x16x32_bf16 v[28:31], v[116:119], v[194:197], 0
	v_mfma_f32_16x16x32_bf16 v[20:23], v[124:127], v[194:197], 0
	v_mfma_f32_16x16x32_bf16 v[12:15], v[116:119], v[208:211], 0
	v_mfma_f32_16x16x32_bf16 v[4:7], v[124:127], v[208:211], 0
	v_mfma_f32_16x16x32_bf16 v[60:63], v[120:123], v[164:167], v[60:63]
	v_mfma_f32_16x16x32_bf16 v[52:55], v[136:139], v[164:167], v[52:55]
	v_mfma_f32_16x16x32_bf16 v[44:47], v[120:123], v[190:193], v[44:47]
	v_mfma_f32_16x16x32_bf16 v[36:39], v[136:139], v[190:193], v[36:39]
	v_mfma_f32_16x16x32_bf16 v[28:31], v[120:123], v[204:207], v[28:31]
	v_mfma_f32_16x16x32_bf16 v[20:23], v[136:139], v[204:207], v[20:23]
	v_mfma_f32_16x16x32_bf16 v[12:15], v[120:123], v[212:215], v[12:15]
	v_mfma_f32_16x16x32_bf16 v[4:7], v[136:139], v[212:215], v[4:7]
	s_setprio 0
	s_setprio 1
	v_mfma_f32_16x16x32_bf16 v[56:59], v[140:143], v[160:163], 0
	v_mfma_f32_16x16x32_bf16 v[48:51], v[152:155], v[160:163], 0
	v_mfma_f32_16x16x32_bf16 v[40:43], v[140:143], v[186:189], 0
	v_mfma_f32_16x16x32_bf16 v[32:35], v[152:155], v[186:189], 0
	v_mfma_f32_16x16x32_bf16 v[24:27], v[140:143], v[194:197], 0
	v_mfma_f32_16x16x32_bf16 v[16:19], v[152:155], v[194:197], 0
	v_mfma_f32_16x16x32_bf16 v[8:11], v[140:143], v[208:211], 0
	v_mfma_f32_16x16x32_bf16 v[0:3], v[152:155], v[208:211], 0
	v_mfma_f32_16x16x32_bf16 v[56:59], v[148:151], v[164:167], v[56:59]
	v_mfma_f32_16x16x32_bf16 v[48:51], v[156:159], v[164:167], v[48:51]
	v_mfma_f32_16x16x32_bf16 v[40:43], v[148:151], v[190:193], v[40:43]
	v_mfma_f32_16x16x32_bf16 v[32:35], v[156:159], v[190:193], v[32:35]
	v_mfma_f32_16x16x32_bf16 v[24:27], v[148:151], v[204:207], v[24:27]
	v_mfma_f32_16x16x32_bf16 v[16:19], v[156:159], v[204:207], v[16:19]
	v_mfma_f32_16x16x32_bf16 v[8:11], v[148:151], v[212:215], v[8:11]
	v_mfma_f32_16x16x32_bf16 v[0:3], v[156:159], v[212:215], v[0:3]
	s_setprio 0
	s_barrier
	s_add_i32 s53, 0, 0x18000
	s_add_i32 s54, 0, 0x1c000
	v_add_u32_e32 v136, s53, v199
	v_add_u32_e32 v156, s54, v199
	ds_read_b128 v[116:119], v136
	ds_read_b128 v[120:123], v136 offset:1024
	ds_read_b128 v[124:127], v136 offset:2048
	ds_read_b128 v[136:139], v136 offset:3072
	ds_read_b128 v[140:143], v156
	ds_read_b128 v[148:151], v156 offset:1024
	ds_read_b128 v[152:155], v156 offset:2048
	ds_read_b128 v[156:159], v156 offset:3072
	s_add_u32 s30, s30, 0x20000
	s_addc_u32 s31, s31, 0
	s_mov_b32 m0, s38
	v_lshl_add_u64 v[224:225], s[30:31], 0, v[168:169]
	ds_read_b128 v[160:163], v203 offset:32768
	ds_read_b128 v[164:167], v203 offset:33792
	ds_read_b128 v[186:189], v203 offset:34816
	ds_read_b128 v[190:193], v203 offset:35840
	ds_read_b128 v[194:197], v203 offset:36864
	ds_read_b128 v[204:207], v203 offset:37888
	ds_read_b128 v[208:211], v203 offset:38912
	ds_read_b128 v[212:215], v203 offset:39936
	global_load_lds_dwordx4 v[224:225], off
	v_lshl_add_u64 v[224:225], s[30:31], 0, v[172:173]
	s_mov_b32 m0, s39
	s_nop 0
	global_load_lds_dwordx4 v[224:225], off
	s_waitcnt vmcnt(8)
	s_waitcnt lgkmcnt(0)
	s_barrier
	s_setprio 1
	s_waitcnt lgkmcnt(0)
	v_mfma_f32_16x16x32_bf16 v[144:147], v[116:119], v[160:163], v[144:147]
	v_mfma_f32_16x16x32_bf16 v[128:131], v[124:127], v[160:163], v[128:131]
	v_mfma_f32_16x16x32_bf16 v[108:111], v[116:119], v[186:189], v[108:111]
	v_mfma_f32_16x16x32_bf16 v[100:103], v[124:127], v[186:189], v[100:103]
	v_mfma_f32_16x16x32_bf16 v[92:95], v[116:119], v[194:197], v[92:95]
	v_mfma_f32_16x16x32_bf16 v[84:87], v[124:127], v[194:197], v[84:87]
	v_mfma_f32_16x16x32_bf16 v[76:79], v[116:119], v[208:211], v[76:79]
	v_mfma_f32_16x16x32_bf16 v[68:71], v[124:127], v[208:211], v[68:71]
	v_mfma_f32_16x16x32_bf16 v[144:147], v[120:123], v[164:167], v[144:147]
	v_mfma_f32_16x16x32_bf16 v[128:131], v[136:139], v[164:167], v[128:131]
	v_mfma_f32_16x16x32_bf16 v[108:111], v[120:123], v[190:193], v[108:111]
	v_mfma_f32_16x16x32_bf16 v[100:103], v[136:139], v[190:193], v[100:103]
	v_mfma_f32_16x16x32_bf16 v[92:95], v[120:123], v[204:207], v[92:95]
	v_mfma_f32_16x16x32_bf16 v[84:87], v[136:139], v[204:207], v[84:87]
	v_mfma_f32_16x16x32_bf16 v[76:79], v[120:123], v[212:215], v[76:79]
	v_mfma_f32_16x16x32_bf16 v[68:71], v[136:139], v[212:215], v[68:71]
	s_setprio 0
	s_setprio 1
	v_mfma_f32_16x16x32_bf16 v[132:135], v[140:143], v[160:163], v[132:135]
	v_mfma_f32_16x16x32_bf16 v[112:115], v[152:155], v[160:163], v[112:115]
	v_mfma_f32_16x16x32_bf16 v[104:107], v[140:143], v[186:189], v[104:107]
	v_mfma_f32_16x16x32_bf16 v[96:99], v[152:155], v[186:189], v[96:99]
	v_mfma_f32_16x16x32_bf16 v[88:91], v[140:143], v[194:197], v[88:91]
	v_mfma_f32_16x16x32_bf16 v[80:83], v[152:155], v[194:197], v[80:83]
	v_mfma_f32_16x16x32_bf16 v[72:75], v[140:143], v[208:211], v[72:75]
	v_mfma_f32_16x16x32_bf16 v[64:67], v[152:155], v[208:211], v[64:67]
	v_mfma_f32_16x16x32_bf16 v[132:135], v[148:151], v[164:167], v[132:135]
	v_mfma_f32_16x16x32_bf16 v[112:115], v[156:159], v[164:167], v[112:115]
	v_mfma_f32_16x16x32_bf16 v[104:107], v[148:151], v[190:193], v[104:107]
	v_mfma_f32_16x16x32_bf16 v[96:99], v[156:159], v[190:193], v[96:99]
	v_mfma_f32_16x16x32_bf16 v[88:91], v[148:151], v[204:207], v[88:91]
	v_mfma_f32_16x16x32_bf16 v[80:83], v[156:159], v[204:207], v[80:83]
	v_mfma_f32_16x16x32_bf16 v[72:75], v[148:151], v[212:215], v[72:75]
	v_mfma_f32_16x16x32_bf16 v[64:67], v[156:159], v[212:215], v[64:67]
	s_setprio 0
	s_barrier
; #define PG8_STAGE(bufoff, gbase, voff) do { _Pragma("unroll") for (int _i = 0; _i < 2; ++_i) \
;         __builtin_amdgcn_global_load_lds((const unsigned*)((const char*)(gbase) + (voff)[_i]), (LAS unsigned*)(lds + (bufoff) + ldsw + _i * 8192), 16, 0, 0); } while (0)
; #define PG8_LDA(dst, b, h) do { _Pragma("unroll") for (int m = 0; m < 4; ++m) _Pragma("unroll") for (int k = 0; k < 2; ++k) dst[m][k] = *(const LAS bf16x8*)(lds + PG8_SA(b, h) + aoff + m * 2048 + k * 1024); } while (0)
; #define PG8_MMA(ai, bj, At, Bt) do { __builtin_amdgcn_s_setprio(1); _Pragma("unroll") for (int m = 0; m < 4; ++m) _Pragma("unroll") for (int n = 0; n < 2; ++n) _Pragma("unroll") for (int k = 0; k < 2; ++k) \
;         acc[ai][bj][m][n] = __builtin_amdgcn_mfma_f32_16x16x32_bf16(Bt[n][k], At[m][k], acc[ai][bj][m][n], 0, 0, 0); __builtin_amdgcn_s_setprio(0); } while (0)
; #define PG8_WAIT_V(n) asm volatile("s_waitcnt vmcnt(" #n ")" ::: "memory")
; #define PG8_WAIT_L(n) asm volatile("s_waitcnt lgkmcnt(" #n ")" ::: "memory")
; #define PG8_BAR __builtin_amdgcn_s_barrier()
; #define PG8_SCHED __builtin_amdgcn_sched_barrier(0)
; template <class Epi, class Sched>
; __device__ __forceinline__ void gemm_phase(LAS unsigned char* lds, const Gemm g, const Sched& S, const Epi& E, int wave_id) {
;     ...
;             PG8_LDA(At, 1, 1); PG8_STAGE(PG8_SB(1, 0), b3, voffB); PG8_STAGE(PG8_SB(1, 1), b3 + hstepB, voffB); PG8_STAGE(PG8_SA(1, 0), a3, voffA);
;             PG8_WAIT_V(8); PG8_WAIT_L(0); PG8_BAR; PG8_MMA(1, 0, At, B0); PG8_MMA(1, 1, At, B1); PG8_BAR; PG8_SCHED;
;         }
	s_add_i32 s30, s53, s36
	v_lshl_add_u64 v[216:217], v[216:217], 0, s[10:11]
	s_mov_b32 m0, s30
	ds_read_b128 v[160:163], v203 offset:49152
	ds_read_b128 v[164:167], v203 offset:50176
	ds_read_b128 v[186:189], v203 offset:51200
	ds_read_b128 v[190:193], v203 offset:52224
	ds_read_b128 v[194:197], v203 offset:53248
	ds_read_b128 v[204:207], v203 offset:54272
	ds_read_b128 v[208:211], v203 offset:55296
	ds_read_b128 v[212:215], v203 offset:56320
	global_load_lds_dwordx4 v[216:217], off
	s_add_i32 m0, s30, 0x2000
	s_add_u32 s28, s28, 0x20080
	v_lshl_add_u64 v[216:217], v[218:219], 0, s[10:11]
	s_addc_u32 s29, s29, 0
	s_add_i32 s30, s54, s36
	global_load_lds_dwordx4 v[216:217], off
	v_lshl_add_u64 v[216:217], s[28:29], 0, v[170:171]
	s_mov_b32 m0, s30
	s_nop 0
	global_load_lds_dwordx4 v[216:217], off
	v_lshl_add_u64 v[216:217], s[28:29], 0, v[174:175]
	s_add_i32 m0, s30, 0x2000
	s_nop 0
	global_load_lds_dwordx4 v[216:217], off
	v_lshl_add_u64 v[216:217], v[220:221], 0, s[10:11]
	s_mov_b32 m0, s41
	s_nop 0
	global_load_lds_dwordx4 v[216:217], off
	v_lshl_add_u64 v[216:217], v[222:223], 0, s[10:11]
	s_mov_b32 m0, s42
	s_nop 0
	global_load_lds_dwordx4 v[216:217], off
	s_waitcnt vmcnt(8)
	s_waitcnt lgkmcnt(0)
	s_barrier
	s_setprio 1
	s_waitcnt lgkmcnt(0)
	v_mfma_f32_16x16x32_bf16 v[60:63], v[116:119], v[160:163], v[60:63]
	v_mfma_f32_16x16x32_bf16 v[52:55], v[124:127], v[160:163], v[52:55]
	v_mfma_f32_16x16x32_bf16 v[44:47], v[116:119], v[186:189], v[44:47]
	v_mfma_f32_16x16x32_bf16 v[36:39], v[124:127], v[186:189], v[36:39]
	v_mfma_f32_16x16x32_bf16 v[28:31], v[116:119], v[194:197], v[28:31]
	v_mfma_f32_16x16x32_bf16 v[20:23], v[124:127], v[194:197], v[20:23]
	v_mfma_f32_16x16x32_bf16 v[12:15], v[116:119], v[208:211], v[12:15]
	v_mfma_f32_16x16x32_bf16 v[4:7], v[124:127], v[208:211], v[4:7]
	v_mfma_f32_16x16x32_bf16 v[60:63], v[120:123], v[164:167], v[60:63]
	v_mfma_f32_16x16x32_bf16 v[52:55], v[136:139], v[164:167], v[52:55]
	v_mfma_f32_16x16x32_bf16 v[44:47], v[120:123], v[190:193], v[44:47]
	v_mfma_f32_16x16x32_bf16 v[36:39], v[136:139], v[190:193], v[36:39]
	v_mfma_f32_16x16x32_bf16 v[28:31], v[120:123], v[204:207], v[28:31]
	v_mfma_f32_16x16x32_bf16 v[20:23], v[136:139], v[204:207], v[20:23]
	v_mfma_f32_16x16x32_bf16 v[12:15], v[120:123], v[212:215], v[12:15]
	v_mfma_f32_16x16x32_bf16 v[4:7], v[136:139], v[212:215], v[4:7]
	s_setprio 0
	s_setprio 1
	v_mfma_f32_16x16x32_bf16 v[56:59], v[140:143], v[160:163], v[56:59]
	v_mfma_f32_16x16x32_bf16 v[48:51], v[152:155], v[160:163], v[48:51]
	v_mfma_f32_16x16x32_bf16 v[40:43], v[140:143], v[186:189], v[40:43]
	v_mfma_f32_16x16x32_bf16 v[32:35], v[152:155], v[186:189], v[32:35]
	v_mfma_f32_16x16x32_bf16 v[24:27], v[140:143], v[194:197], v[24:27]
	v_mfma_f32_16x16x32_bf16 v[16:19], v[152:155], v[194:197], v[16:19]
	v_mfma_f32_16x16x32_bf16 v[8:11], v[140:143], v[208:211], v[8:11]
	v_mfma_f32_16x16x32_bf16 v[0:3], v[152:155], v[208:211], v[0:3]
	v_mfma_f32_16x16x32_bf16 v[56:59], v[148:151], v[164:167], v[56:59]
	v_mfma_f32_16x16x32_bf16 v[48:51], v[156:159], v[164:167], v[48:51]
	v_mfma_f32_16x16x32_bf16 v[40:43], v[148:151], v[190:193], v[40:43]
	v_mfma_f32_16x16x32_bf16 v[32:35], v[156:159], v[190:193], v[32:35]
	v_mfma_f32_16x16x32_bf16 v[24:27], v[148:151], v[204:207], v[24:27]
	v_mfma_f32_16x16x32_bf16 v[16:19], v[156:159], v[204:207], v[16:19]
	v_mfma_f32_16x16x32_bf16 v[8:11], v[148:151], v[212:215], v[8:11]
	v_mfma_f32_16x16x32_bf16 v[0:3], v[156:159], v[212:215], v[0:3]
	s_setprio 0
	s_barrier
	s_add_i32 s52, s52, 2
	s_add_u32 s26, s26, 0x100
	s_addc_u32 s27, s27, 0
	s_add_u32 s50, s50, 0x100
	s_addc_u32 s51, s51, 0
	s_cmp_gt_u32 s52, 5

;     __device__ bool next(int i, Unit& u) const { if (r0 + i >= r1) return false; return base.next(r0 + i, u); }
;     __device__ bool next(int i, Unit& u) const { const int L = i * G + c; if (L >= 256) return false; u.pm = L; u.pn = L >> 3; return true; }
; #define PG8_STAGE(bufoff, gbase, voff) do { _Pragma("unroll") for (int _i = 0; _i < 2; ++_i) \
;         __builtin_amdgcn_global_load_lds((const unsigned*)((const char*)(gbase) + (voff)[_i]), (LAS unsigned*)(lds + (bufoff) + ldsw + _i * 8192), 16, 0, 0); } while (0)
; #define PG8_LDA(dst, b, h) do { _Pragma("unroll") for (int m = 0; m < 4; ++m) _Pragma("unroll") for (int k = 0; k < 2; ++k) dst[m][k] = *(const LAS bf16x8*)(lds + PG8_SA(b, h) + aoff + m * 2048 + k * 1024); } while (0)
; #define PG8_LDB(dst, b, h) do { _Pragma("unroll") for (int n = 0; n < 2; ++n) _Pragma("unroll") for (int k = 0; k < 2; ++k) dst[n][k] = *(const LAS bf16x8*)(lds + PG8_SB(b, h) + boff + n * 2048 + k * 1024); } while (0)
; #define PG8_WAIT_V(n) asm volatile("s_waitcnt vmcnt(" #n ")" ::: "memory")
; #define PG8_WAIT_L(n) asm volatile("s_waitcnt lgkmcnt(" #n ")" ::: "memory")
; template <class Epi, class Sched>
; __device__ __forceinline__ void gemm_phase(LAS unsigned char* lds, const Gemm g, const Sched& S, const Epi& E, int wave_id) {
;     ...
;         const bool has_next = S.next(ui + 1, nxt);
;         const char* nA = has_next ? (const char*)g.A + (size_t)nxt.pm * tstepA : cA; const char* nB = has_next ? (const char*)g.Bt + (size_t)nxt.pn * tstepB : cB;
;         for (int t = 0; t < nt; t += 2) {
;             const bool last = (t == nt - 2);
;             const char* a1 = cA + (size_t)(t + 1) * kstep;
;             const char* a2 = last ? nA : cA + (size_t)(t + 2) * kstep; const char* b2 = last ? nB : cB + (size_t)(t + 2) * kstep;
;             const char* a3 = a2 + kstep; const char* b3 = b2 + kstep;
;             PG8_LDB(B0, 0, 0); PG8_LDB(B1, 0, 1); PG8_SCHED; PG8_LDA(At, 0, 0); PG8_STAGE(PG8_SA(1, 1), a1 + hstepA, voffA);
;             PG8_WAIT_V(8); PG8_WAIT_L(0); PG8_BAR; PG8_MMA(0, 0, At, B0); PG8_MMA(0, 1, At, B1); PG8_BAR; PG8_SCHED;
;             PG8_LDA(At, 0, 1); PG8_STAGE(PG8_SB(0, 0), b2, voffB); PG8_STAGE(PG8_SB(0, 1), b2 + hstepB, voffB); PG8_STAGE(PG8_SA(0, 0), a2, voffA);
;             PG8_WAIT_V(8); PG8_WAIT_L(0); PG8_BAR; PG8_MMA(1, 0, At, B0); PG8_MMA(1, 1, At, B1); PG8_BAR; PG8_SCHED;
.LBB0_1145:
	s_ashr_i32 s21, s20, 31
	s_lshl_b64 s[22:23], s[20:21], 18
	s_add_u32 s22, s3, s22
	s_addc_u32 s23, s17, s23
	s_and_b64 s[24:25], s[4:5], exec
	s_cselect_b32 s21, s23, s29
	s_cselect_b32 s56, s22, s28
	s_ashr_i32 s19, s18, 31
	s_lshl_b64 s[24:25], s[18:19], 18
	s_add_u32 s24, s33, s24
	s_addc_u32 s25, s36, s25
	s_and_b64 s[34:35], s[4:5], exec
	s_cselect_b32 s19, s25, s31
	s_cselect_b32 s57, s24, s30
	s_add_u32 s28, s28, 0x20080
	s_addc_u32 s29, s29, 0
	s_add_u32 s58, s30, 0x100
	s_addc_u32 s59, s31, 0
	s_mov_b32 s60, -2
	s_waitcnt vmcnt(0)
	ds_read_b128 v[128:131], v206
	ds_read_b128 v[132:135], v206 offset:1024
	ds_read_b128 v[136:139], v206 offset:2048
	ds_read_b128 v[140:143], v206 offset:3072
	ds_read_b128 v[144:147], v207
	ds_read_b128 v[148:151], v207 offset:1024
	ds_read_b128 v[178:181], v207 offset:2048
	ds_read_b128 v[182:185], v207 offset:3072
	s_add_u32 s30, s28, 0xfffe0080
	s_addc_u32 s31, s29, -1
	s_cmp_eq_u32 s60, 4
	s_cselect_b32 s35, s21, s31
	s_cselect_b32 s34, s56, s30
	s_cselect_b32 s31, s19, s59
	s_cselect_b32 s30, s57, s58
	v_lshl_add_u64 v[202:203], s[28:29], 0, v[170:171]
	s_add_i32 m0, s38, 0xc000
	ds_read_b128 v[186:189], v208
	ds_read_b128 v[190:193], v208 offset:1024
	ds_read_b128 v[194:197], v208 offset:2048
	ds_read_b128 v[198:201], v208 offset:3072
	ds_read_b128 v[212:215], v208 offset:4096
	ds_read_b128 v[216:219], v208 offset:5120
	ds_read_b128 v[220:223], v208 offset:6144
	ds_read_b128 v[224:227], v208 offset:7168
	global_load_lds_dwordx4 v[202:203], off
	v_lshl_add_u64 v[202:203], s[28:29], 0, v[172:173]
	s_add_i32 m0, s38, 0xe000
	s_nop 0
	global_load_lds_dwordx4 v[202:203], off
	s_waitcnt vmcnt(24)
	s_waitcnt lgkmcnt(0)
	s_barrier
	s_setprio 1
	s_waitcnt lgkmcnt(0)
	v_mfma_f32_16x16x32_bf16 v[124:127], v[128:131], v[186:189], 0
	v_mfma_f32_16x16x32_bf16 v[120:123], v[136:139], v[186:189], 0
	v_mfma_f32_16x16x32_bf16 v[108:111], v[128:131], v[194:197], 0
	v_mfma_f32_16x16x32_bf16 v[104:107], v[136:139], v[194:197], 0
	v_mfma_f32_16x16x32_bf16 v[92:95], v[128:131], v[212:215], 0
	v_mfma_f32_16x16x32_bf16 v[88:91], v[136:139], v[212:215], 0
	v_mfma_f32_16x16x32_bf16 v[76:79], v[128:131], v[220:223], 0
	v_mfma_f32_16x16x32_bf16 v[72:75], v[136:139], v[220:223], 0
	v_mfma_f32_16x16x32_bf16 v[124:127], v[132:135], v[190:193], v[124:127]
	v_mfma_f32_16x16x32_bf16 v[120:123], v[140:143], v[190:193], v[120:123]
	v_mfma_f32_16x16x32_bf16 v[108:111], v[132:135], v[198:201], v[108:111]
	v_mfma_f32_16x16x32_bf16 v[104:107], v[140:143], v[198:201], v[104:107]
	v_mfma_f32_16x16x32_bf16 v[92:95], v[132:135], v[216:219], v[92:95]
	v_mfma_f32_16x16x32_bf16 v[88:91], v[140:143], v[216:219], v[88:91]
	v_mfma_f32_16x16x32_bf16 v[76:79], v[132:135], v[224:227], v[76:79]
	v_mfma_f32_16x16x32_bf16 v[72:75], v[140:143], v[224:227], v[72:75]
	s_setprio 0
	s_setprio 1
	v_mfma_f32_16x16x32_bf16 v[116:119], v[144:147], v[186:189], 0
	v_mfma_f32_16x16x32_bf16 v[112:115], v[178:181], v[186:189], 0
	v_mfma_f32_16x16x32_bf16 v[100:103], v[144:147], v[194:197], 0
	v_mfma_f32_16x16x32_bf16 v[96:99], v[178:181], v[194:197], 0
	v_mfma_f32_16x16x32_bf16 v[84:87], v[144:147], v[212:215], 0
	v_mfma_f32_16x16x32_bf16 v[80:83], v[178:181], v[212:215], 0
	v_mfma_f32_16x16x32_bf16 v[68:71], v[144:147], v[220:223], 0
	v_mfma_f32_16x16x32_bf16 v[64:67], v[178:181], v[220:223], 0
	v_mfma_f32_16x16x32_bf16 v[116:119], v[148:151], v[190:193], v[116:119]
	v_mfma_f32_16x16x32_bf16 v[112:115], v[182:185], v[190:193], v[112:115]
	v_mfma_f32_16x16x32_bf16 v[100:103], v[148:151], v[198:201], v[100:103]
	v_mfma_f32_16x16x32_bf16 v[96:99], v[182:185], v[198:201], v[96:99]
	v_mfma_f32_16x16x32_bf16 v[84:87], v[148:151], v[216:219], v[84:87]
	v_mfma_f32_16x16x32_bf16 v[80:83], v[182:185], v[216:219], v[80:83]
	v_mfma_f32_16x16x32_bf16 v[68:71], v[148:151], v[224:227], v[68:71]
	v_mfma_f32_16x16x32_bf16 v[64:67], v[182:185], v[224:227], v[64:67]
	s_setprio 0
	s_barrier
	s_add_i32 s61, s54, s37
	v_lshl_add_u64 v[202:203], s[30:31], 0, v[154:155]
	s_mov_b32 m0, s61
	ds_read_b128 v[186:189], v208 offset:16384
	ds_read_b128 v[190:193], v208 offset:17408
	ds_read_b128 v[194:197], v208 offset:18432
	ds_read_b128 v[198:201], v208 offset:19456
	ds_read_b128 v[212:215], v208 offset:20480
	ds_read_b128 v[216:219], v208 offset:21504
	ds_read_b128 v[220:223], v208 offset:22528
	ds_read_b128 v[224:227], v208 offset:23552
	global_load_lds_dwordx4 v[202:203], off
	s_add_i32 m0, s61, 0x2000
	s_add_u32 s62, s30, 0x20000
	v_lshl_add_u64 v[228:229], s[30:31], 0, v[158:159]
	s_addc_u32 s63, s31, 0
	s_add_i32 s61, s55, s37
	global_load_lds_dwordx4 v[228:229], off
	v_lshl_add_u64 v[230:231], s[62:63], 0, v[154:155]
	s_mov_b32 m0, s61
	v_lshl_add_u64 v[232:233], s[34:35], 0, v[156:157]
	global_load_lds_dwordx4 v[230:231], off
	v_lshl_add_u64 v[230:231], s[62:63], 0, v[158:159]
	s_add_i32 m0, s61, 0x2000
	s_nop 0
	global_load_lds_dwordx4 v[230:231], off
	v_lshl_add_u64 v[230:231], s[34:35], 0, v[152:153]
	s_mov_b32 m0, s38
	s_nop 0
	global_load_lds_dwordx4 v[230:231], off
	s_mov_b32 m0, s39
	s_nop 0
	global_load_lds_dwordx4 v[232:233], off
	s_waitcnt vmcnt(8)
	s_waitcnt lgkmcnt(0)
	s_barrier
; #define PG8_STAGE(bufoff, gbase, voff) do { _Pragma("unroll") for (int _i = 0; _i < 2; ++_i) \
;         __builtin_amdgcn_global_load_lds((const unsigned*)((const char*)(gbase) + (voff)[_i]), (LAS unsigned*)(lds + (bufoff) + ldsw + _i * 8192), 16, 0, 0); } while (0)
; #define PG8_LDA(dst, b, h) do { _Pragma("unroll") for (int m = 0; m < 4; ++m) _Pragma("unroll") for (int k = 0; k < 2; ++k) dst[m][k] = *(const LAS bf16x8*)(lds + PG8_SA(b, h) + aoff + m * 2048 + k * 1024); } while (0)
; #define PG8_LDB(dst, b, h) do { _Pragma("unroll") for (int n = 0; n < 2; ++n) _Pragma("unroll") for (int k = 0; k < 2; ++k) dst[n][k] = *(const LAS bf16x8*)(lds + PG8_SB(b, h) + boff + n * 2048 + k * 1024); } while (0)
; #define PG8_MMA(ai, bj, At, Bt) do { __builtin_amdgcn_s_setprio(1); _Pragma("unroll") for (int m = 0; m < 4; ++m) _Pragma("unroll") for (int n = 0; n < 2; ++n) _Pragma("unroll") for (int k = 0; k < 2; ++k) \
;         acc[ai][bj][m][n] = __builtin_amdgcn_mfma_f32_16x16x32_bf16(Bt[n][k], At[m][k], acc[ai][bj][m][n], 0, 0, 0); __builtin_amdgcn_s_setprio(0); } while (0)
; #define PG8_WAIT_V(n) asm volatile("s_waitcnt vmcnt(" #n ")" ::: "memory")
; #define PG8_WAIT_L(n) asm volatile("s_waitcnt lgkmcnt(" #n ")" ::: "memory")
; #define PG8_BAR __builtin_amdgcn_s_barrier()
; #define PG8_SCHED __builtin_amdgcn_sched_barrier(0)
; template <class Epi, class Sched>
; __device__ __forceinline__ void gemm_phase(LAS unsigned char* lds, const Gemm g, const Sched& S, const Epi& E, int wave_id) {
;     ...
;             PG8_WAIT_V(8); PG8_WAIT_L(0); PG8_BAR; PG8_MMA(1, 0, At, B0); PG8_MMA(1, 1, At, B1); PG8_BAR; PG8_SCHED;
;             PG8_LDB(B0, 1, 0); PG8_LDB(B1, 1, 1); PG8_SCHED; PG8_LDA(At, 1, 0); PG8_STAGE(PG8_SA(0, 1), a2 + hstepA, voffA);
;             PG8_WAIT_V(8); PG8_WAIT_L(0); PG8_BAR; PG8_MMA(0, 0, At, B0); PG8_MMA(0, 1, At, B1); PG8_BAR; PG8_SCHED;
	s_setprio 1
	s_waitcnt lgkmcnt(0)
	v_mfma_f32_16x16x32_bf16 v[60:63], v[128:131], v[186:189], 0
	v_mfma_f32_16x16x32_bf16 v[56:59], v[136:139], v[186:189], 0
	v_mfma_f32_16x16x32_bf16 v[44:47], v[128:131], v[194:197], 0
	v_mfma_f32_16x16x32_bf16 v[40:43], v[136:139], v[194:197], 0
	v_mfma_f32_16x16x32_bf16 v[28:31], v[128:131], v[212:215], 0
	v_mfma_f32_16x16x32_bf16 v[24:27], v[136:139], v[212:215], 0
	v_mfma_f32_16x16x32_bf16 v[12:15], v[128:131], v[220:223], 0
	v_mfma_f32_16x16x32_bf16 v[8:11], v[136:139], v[220:223], 0
	v_mfma_f32_16x16x32_bf16 v[60:63], v[132:135], v[190:193], v[60:63]
	v_mfma_f32_16x16x32_bf16 v[56:59], v[140:143], v[190:193], v[56:59]
	v_mfma_f32_16x16x32_bf16 v[44:47], v[132:135], v[198:201], v[44:47]
	v_mfma_f32_16x16x32_bf16 v[40:43], v[140:143], v[198:201], v[40:43]
	v_mfma_f32_16x16x32_bf16 v[28:31], v[132:135], v[216:219], v[28:31]
	v_mfma_f32_16x16x32_bf16 v[24:27], v[140:143], v[216:219], v[24:27]
	v_mfma_f32_16x16x32_bf16 v[12:15], v[132:135], v[224:227], v[12:15]
	v_mfma_f32_16x16x32_bf16 v[8:11], v[140:143], v[224:227], v[8:11]
	s_setprio 0
	s_setprio 1
	v_mfma_f32_16x16x32_bf16 v[52:55], v[144:147], v[186:189], 0
	v_mfma_f32_16x16x32_bf16 v[48:51], v[178:181], v[186:189], 0
	v_mfma_f32_16x16x32_bf16 v[36:39], v[144:147], v[194:197], 0
	v_mfma_f32_16x16x32_bf16 v[32:35], v[178:181], v[194:197], 0
	v_mfma_f32_16x16x32_bf16 v[20:23], v[144:147], v[212:215], 0
	v_mfma_f32_16x16x32_bf16 v[16:19], v[178:181], v[212:215], 0
	v_mfma_f32_16x16x32_bf16 v[4:7], v[144:147], v[220:223], 0
	v_mfma_f32_16x16x32_bf16 v[0:3], v[178:181], v[220:223], 0
	v_mfma_f32_16x16x32_bf16 v[52:55], v[148:151], v[190:193], v[52:55]
	v_mfma_f32_16x16x32_bf16 v[48:51], v[182:185], v[190:193], v[48:51]
	v_mfma_f32_16x16x32_bf16 v[36:39], v[148:151], v[198:201], v[36:39]
	v_mfma_f32_16x16x32_bf16 v[32:35], v[182:185], v[198:201], v[32:35]
	v_mfma_f32_16x16x32_bf16 v[20:23], v[148:151], v[216:219], v[20:23]
	v_mfma_f32_16x16x32_bf16 v[16:19], v[182:185], v[216:219], v[16:19]
	v_mfma_f32_16x16x32_bf16 v[4:7], v[148:151], v[224:227], v[4:7]
	v_mfma_f32_16x16x32_bf16 v[0:3], v[182:185], v[224:227], v[0:3]
	s_setprio 0
	s_barrier
	s_add_i32 s61, 0, 0x18000
	s_add_i32 s62, 0, 0x1c000
	v_add_u32_e32 v140, s61, v205
	v_add_u32_e32 v182, s62, v205
	ds_read_b128 v[128:131], v140
	ds_read_b128 v[132:135], v140 offset:1024
	ds_read_b128 v[136:139], v140 offset:2048
	ds_read_b128 v[140:143], v140 offset:3072
	ds_read_b128 v[144:147], v182
	ds_read_b128 v[148:151], v182 offset:1024
	ds_read_b128 v[178:181], v182 offset:2048
	ds_read_b128 v[182:185], v182 offset:3072
	s_add_u32 s34, s34, 0x20000
	s_addc_u32 s35, s35, 0
	s_mov_b32 m0, s40
	v_lshl_add_u64 v[234:235], s[34:35], 0, v[152:153]
	ds_read_b128 v[186:189], v208 offset:32768
	ds_read_b128 v[190:193], v208 offset:33792
	ds_read_b128 v[194:197], v208 offset:34816
	ds_read_b128 v[198:201], v208 offset:35840
	ds_read_b128 v[212:215], v208 offset:36864
	ds_read_b128 v[216:219], v208 offset:37888
	ds_read_b128 v[220:223], v208 offset:38912
	ds_read_b128 v[224:227], v208 offset:39936
	global_load_lds_dwordx4 v[234:235], off
	v_lshl_add_u64 v[234:235], s[34:35], 0, v[156:157]
	s_mov_b32 m0, s41
	s_nop 0
	global_load_lds_dwordx4 v[234:235], off
	s_waitcnt vmcnt(8)
	s_waitcnt lgkmcnt(0)
	s_barrier
	s_setprio 1
	s_waitcnt lgkmcnt(0)
	v_mfma_f32_16x16x32_bf16 v[124:127], v[128:131], v[186:189], v[124:127]
	v_mfma_f32_16x16x32_bf16 v[120:123], v[136:139], v[186:189], v[120:123]
	v_mfma_f32_16x16x32_bf16 v[108:111], v[128:131], v[194:197], v[108:111]
	v_mfma_f32_16x16x32_bf16 v[104:107], v[136:139], v[194:197], v[104:107]
	v_mfma_f32_16x16x32_bf16 v[92:95], v[128:131], v[212:215], v[92:95]
	v_mfma_f32_16x16x32_bf16 v[88:91], v[136:139], v[212:215], v[88:91]
	v_mfma_f32_16x16x32_bf16 v[76:79], v[128:131], v[220:223], v[76:79]
	v_mfma_f32_16x16x32_bf16 v[72:75], v[136:139], v[220:223], v[72:75]
	v_mfma_f32_16x16x32_bf16 v[124:127], v[132:135], v[190:193], v[124:127]
	v_mfma_f32_16x16x32_bf16 v[120:123], v[140:143], v[190:193], v[120:123]
	v_mfma_f32_16x16x32_bf16 v[108:111], v[132:135], v[198:201], v[108:111]
	v_mfma_f32_16x16x32_bf16 v[104:107], v[140:143], v[198:201], v[104:107]
	v_mfma_f32_16x16x32_bf16 v[92:95], v[132:135], v[216:219], v[92:95]
	v_mfma_f32_16x16x32_bf16 v[88:91], v[140:143], v[216:219], v[88:91]
	v_mfma_f32_16x16x32_bf16 v[76:79], v[132:135], v[224:227], v[76:79]
	v_mfma_f32_16x16x32_bf16 v[72:75], v[140:143], v[224:227], v[72:75]
	s_setprio 0
	s_setprio 1
	v_mfma_f32_16x16x32_bf16 v[116:119], v[144:147], v[186:189], v[116:119]
	v_mfma_f32_16x16x32_bf16 v[112:115], v[178:181], v[186:189], v[112:115]
	v_mfma_f32_16x16x32_bf16 v[100:103], v[144:147], v[194:197], v[100:103]
	v_mfma_f32_16x16x32_bf16 v[96:99], v[178:181], v[194:197], v[96:99]
	v_mfma_f32_16x16x32_bf16 v[84:87], v[144:147], v[212:215], v[84:87]
	v_mfma_f32_16x16x32_bf16 v[80:83], v[178:181], v[212:215], v[80:83]
	v_mfma_f32_16x16x32_bf16 v[68:71], v[144:147], v[220:223], v[68:71]
	v_mfma_f32_16x16x32_bf16 v[64:67], v[178:181], v[220:223], v[64:67]
	v_mfma_f32_16x16x32_bf16 v[116:119], v[148:151], v[190:193], v[116:119]
	v_mfma_f32_16x16x32_bf16 v[112:115], v[182:185], v[190:193], v[112:115]
	v_mfma_f32_16x16x32_bf16 v[100:103], v[148:151], v[198:201], v[100:103]
	v_mfma_f32_16x16x32_bf16 v[96:99], v[182:185], v[198:201], v[96:99]
	v_mfma_f32_16x16x32_bf16 v[84:87], v[148:151], v[216:219], v[84:87]
	v_mfma_f32_16x16x32_bf16 v[80:83], v[182:185], v[216:219], v[80:83]
	v_mfma_f32_16x16x32_bf16 v[68:71], v[148:151], v[224:227], v[68:71]
	v_mfma_f32_16x16x32_bf16 v[64:67], v[182:185], v[224:227], v[64:67]
	s_setprio 0
	s_barrier
; #define PG8_STAGE(bufoff, gbase, voff) do { _Pragma("unroll") for (int _i = 0; _i < 2; ++_i) \
;         __builtin_amdgcn_global_load_lds((const unsigned*)((const char*)(gbase) + (voff)[_i]), (LAS unsigned*)(lds + (bufoff) + ldsw + _i * 8192), 16, 0, 0); } while (0)
; #define PG8_LDA(dst, b, h) do { _Pragma("unroll") for (int m = 0; m < 4; ++m) _Pragma("unroll") for (int k = 0; k < 2; ++k) dst[m][k] = *(const LAS bf16x8*)(lds + PG8_SA(b, h) + aoff + m * 2048 + k * 1024); } while (0)
; #define PG8_MMA(ai, bj, At, Bt) do { __builtin_amdgcn_s_setprio(1); _Pragma("unroll") for (int m = 0; m < 4; ++m) _Pragma("unroll") for (int n = 0; n < 2; ++n) _Pragma("unroll") for (int k = 0; k < 2; ++k) \
;         acc[ai][bj][m][n] = __builtin_amdgcn_mfma_f32_16x16x32_bf16(Bt[n][k], At[m][k], acc[ai][bj][m][n], 0, 0, 0); __builtin_amdgcn_s_setprio(0); } while (0)
; #define PG8_WAIT_V(n) asm volatile("s_waitcnt vmcnt(" #n ")" ::: "memory")
; #define PG8_WAIT_L(n) asm volatile("s_waitcnt lgkmcnt(" #n ")" ::: "memory")
; #define PG8_BAR __builtin_amdgcn_s_barrier()
; #define PG8_SCHED __builtin_amdgcn_sched_barrier(0)
; template <class Epi, class Sched>
; __device__ __forceinline__ void gemm_phase(LAS unsigned char* lds, const Gemm g, const Sched& S, const Epi& E, int wave_id) {
;     ...
;             PG8_LDA(At, 1, 1); PG8_STAGE(PG8_SB(1, 0), b3, voffB); PG8_STAGE(PG8_SB(1, 1), b3 + hstepB, voffB); PG8_STAGE(PG8_SA(1, 0), a3, voffA);
;             PG8_WAIT_V(8); PG8_WAIT_L(0); PG8_BAR; PG8_MMA(1, 0, At, B0); PG8_MMA(1, 1, At, B1); PG8_BAR; PG8_SCHED;
;         }
	s_add_i32 s34, s61, s37
	v_lshl_add_u64 v[202:203], v[202:203], 0, s[12:13]
	s_mov_b32 m0, s34
	ds_read_b128 v[186:189], v208 offset:49152
	ds_read_b128 v[190:193], v208 offset:50176
	ds_read_b128 v[194:197], v208 offset:51200
	ds_read_b128 v[198:201], v208 offset:52224
	ds_read_b128 v[212:215], v208 offset:53248
	ds_read_b128 v[216:219], v208 offset:54272
	ds_read_b128 v[220:223], v208 offset:55296
	ds_read_b128 v[224:227], v208 offset:56320
	global_load_lds_dwordx4 v[202:203], off
	s_add_i32 m0, s34, 0x2000
	s_add_u32 s30, s30, 0x20080
	v_lshl_add_u64 v[202:203], v[228:229], 0, s[12:13]
	s_addc_u32 s31, s31, 0
	s_add_i32 s34, s62, s37
	global_load_lds_dwordx4 v[202:203], off
	v_lshl_add_u64 v[202:203], s[30:31], 0, v[154:155]
	s_mov_b32 m0, s34
	s_nop 0
	global_load_lds_dwordx4 v[202:203], off
	v_lshl_add_u64 v[202:203], s[30:31], 0, v[158:159]
	s_add_i32 m0, s34, 0x2000
	s_nop 0
	global_load_lds_dwordx4 v[202:203], off
	v_lshl_add_u64 v[202:203], v[230:231], 0, s[12:13]
	s_mov_b32 m0, s44
	s_nop 0
	global_load_lds_dwordx4 v[202:203], off
	v_lshl_add_u64 v[202:203], v[232:233], 0, s[12:13]
	s_mov_b32 m0, s45
	s_nop 0
	global_load_lds_dwordx4 v[202:203], off
	s_waitcnt vmcnt(8)
	s_waitcnt lgkmcnt(0)
	s_barrier
	s_setprio 1
	s_waitcnt lgkmcnt(0)
	v_mfma_f32_16x16x32_bf16 v[60:63], v[128:131], v[186:189], v[60:63]
	v_mfma_f32_16x16x32_bf16 v[56:59], v[136:139], v[186:189], v[56:59]
	v_mfma_f32_16x16x32_bf16 v[44:47], v[128:131], v[194:197], v[44:47]
	v_mfma_f32_16x16x32_bf16 v[40:43], v[136:139], v[194:197], v[40:43]
	v_mfma_f32_16x16x32_bf16 v[28:31], v[128:131], v[212:215], v[28:31]
	v_mfma_f32_16x16x32_bf16 v[24:27], v[136:139], v[212:215], v[24:27]
	v_mfma_f32_16x16x32_bf16 v[12:15], v[128:131], v[220:223], v[12:15]
	v_mfma_f32_16x16x32_bf16 v[8:11], v[136:139], v[220:223], v[8:11]
	v_mfma_f32_16x16x32_bf16 v[60:63], v[132:135], v[190:193], v[60:63]
	v_mfma_f32_16x16x32_bf16 v[56:59], v[140:143], v[190:193], v[56:59]
	v_mfma_f32_16x16x32_bf16 v[44:47], v[132:135], v[198:201], v[44:47]
	v_mfma_f32_16x16x32_bf16 v[40:43], v[140:143], v[198:201], v[40:43]
	v_mfma_f32_16x16x32_bf16 v[28:31], v[132:135], v[216:219], v[28:31]
	v_mfma_f32_16x16x32_bf16 v[24:27], v[140:143], v[216:219], v[24:27]
	v_mfma_f32_16x16x32_bf16 v[12:15], v[132:135], v[224:227], v[12:15]
	v_mfma_f32_16x16x32_bf16 v[8:11], v[140:143], v[224:227], v[8:11]
	s_setprio 0
	s_setprio 1
	v_mfma_f32_16x16x32_bf16 v[52:55], v[144:147], v[186:189], v[52:55]
	v_mfma_f32_16x16x32_bf16 v[48:51], v[178:181], v[186:189], v[48:51]
	v_mfma_f32_16x16x32_bf16 v[36:39], v[144:147], v[194:197], v[36:39]
	v_mfma_f32_16x16x32_bf16 v[32:35], v[178:181], v[194:197], v[32:35]
	v_mfma_f32_16x16x32_bf16 v[20:23], v[144:147], v[212:215], v[20:23]
	v_mfma_f32_16x16x32_bf16 v[16:19], v[178:181], v[212:215], v[16:19]
	v_mfma_f32_16x16x32_bf16 v[4:7], v[144:147], v[220:223], v[4:7]
	v_mfma_f32_16x16x32_bf16 v[0:3], v[178:181], v[220:223], v[0:3]
	v_mfma_f32_16x16x32_bf16 v[52:55], v[148:151], v[190:193], v[52:55]
	v_mfma_f32_16x16x32_bf16 v[48:51], v[182:185], v[190:193], v[48:51]
	v_mfma_f32_16x16x32_bf16 v[36:39], v[148:151], v[198:201], v[36:39]
	v_mfma_f32_16x16x32_bf16 v[32:35], v[182:185], v[198:201], v[32:35]
	v_mfma_f32_16x16x32_bf16 v[20:23], v[148:151], v[216:219], v[20:23]
	v_mfma_f32_16x16x32_bf16 v[16:19], v[182:185], v[216:219], v[16:19]
	v_mfma_f32_16x16x32_bf16 v[4:7], v[148:151], v[224:227], v[4:7]
	v_mfma_f32_16x16x32_bf16 v[0:3], v[182:185], v[224:227], v[0:3]
	s_setprio 0
	s_barrier
	s_add_i32 s60, s60, 2
	s_add_u32 s28, s28, 0x100
	s_addc_u32 s29, s29, 0
	s_add_u32 s58, s58, 0x100
	s_addc_u32 s59, s59, 0
	s_cmp_gt_u32 s60, 5

;     __device__ bool next(int i, Unit& u) const { if (r0 + i >= r1) return false; return base.next(r0 + i, u); }
;     __device__ bool next(int i, Unit& u) const { const int L = i * G + c; if (L >= 256) return false; u.pm = L; u.pn = L >> 3; return true; }
; #define PG8_STAGE(bufoff, gbase, voff) do { _Pragma("unroll") for (int _i = 0; _i < 2; ++_i) \
;         __builtin_amdgcn_global_load_lds((const unsigned*)((const char*)(gbase) + (voff)[_i]), (LAS unsigned*)(lds + (bufoff) + ldsw + _i * 8192), 16, 0, 0); } while (0)
; #define PG8_LDA(dst, b, h) do { _Pragma("unroll") for (int m = 0; m < 4; ++m) _Pragma("unroll") for (int k = 0; k < 2; ++k) dst[m][k] = *(const LAS bf16x8*)(lds + PG8_SA(b, h) + aoff + m * 2048 + k * 1024); } while (0)
; #define PG8_LDB(dst, b, h) do { _Pragma("unroll") for (int n = 0; n < 2; ++n) _Pragma("unroll") for (int k = 0; k < 2; ++k) dst[n][k] = *(const LAS bf16x8*)(lds + PG8_SB(b, h) + boff + n * 2048 + k * 1024); } while (0)
; #define PG8_WAIT_V(n) asm volatile("s_waitcnt vmcnt(" #n ")" ::: "memory")
; #define PG8_WAIT_L(n) asm volatile("s_waitcnt lgkmcnt(" #n ")" ::: "memory")
; template <class Epi, class Sched>
; __device__ __forceinline__ void gemm_phase(LAS unsigned char* lds, const Gemm g, const Sched& S, const Epi& E, int wave_id) {
;     ...
;         const bool has_next = S.next(ui + 1, nxt);
;         const char* nA = has_next ? (const char*)g.A + (size_t)nxt.pm * tstepA : cA; const char* nB = has_next ? (const char*)g.Bt + (size_t)nxt.pn * tstepB : cB;
;         for (int t = 0; t < nt; t += 2) {
;             const bool last = (t == nt - 2);
;             const char* a1 = cA + (size_t)(t + 1) * kstep;
;             const char* a2 = last ? nA : cA + (size_t)(t + 2) * kstep; const char* b2 = last ? nB : cB + (size_t)(t + 2) * kstep;
;             const char* a3 = a2 + kstep; const char* b3 = b2 + kstep;
;             PG8_LDB(B0, 0, 0); PG8_LDB(B1, 0, 1); PG8_SCHED; PG8_LDA(At, 0, 0); PG8_STAGE(PG8_SA(1, 1), a1 + hstepA, voffA);
;             PG8_WAIT_V(8); PG8_WAIT_L(0); PG8_BAR; PG8_MMA(0, 0, At, B0); PG8_MMA(0, 1, At, B1); PG8_BAR; PG8_SCHED;
;             PG8_LDA(At, 0, 1); PG8_STAGE(PG8_SB(0, 0), b2, voffB); PG8_STAGE(PG8_SB(0, 1), b2 + hstepB, voffB); PG8_STAGE(PG8_SA(0, 0), a2, voffA);
;             PG8_WAIT_V(8); PG8_WAIT_L(0); PG8_BAR; PG8_MMA(1, 0, At, B0); PG8_MMA(1, 1, At, B1); PG8_BAR; PG8_SCHED;
.LBB0_1250:
	s_ashr_i32 s25, s24, 31
	s_lshl_b64 s[26:27], s[24:25], 19
	s_add_u32 s26, s45, s26
	s_addc_u32 s27, s46, s27
	s_and_b64 s[28:29], s[6:7], exec
	s_cselect_b32 s25, s27, s35
	s_cselect_b32 s63, s26, s34
	s_ashr_i32 s23, s22, 31
	s_lshl_b64 s[28:29], s[22:23], 19
	s_add_u32 s28, s47, s28
	s_addc_u32 s29, s48, s29
	s_and_b64 s[38:39], s[6:7], exec
	s_cselect_b32 s23, s29, s37
	s_cselect_b32 s64, s28, s36
	s_add_u32 s34, s34, 0x40080
	s_addc_u32 s35, s35, 0
	s_add_u32 s65, s36, 0x100
	s_addc_u32 s66, s37, 0
	s_mov_b32 s67, -2
	s_waitcnt lgkmcnt(0)
	s_waitcnt vmcnt(0)
	ds_read_b128 v[128:131], v178
	ds_read_b128 v[132:135], v178 offset:1024
	ds_read_b128 v[136:139], v178 offset:2048
	ds_read_b128 v[140:143], v178 offset:3072
	ds_read_b128 v[170:173], v179
	ds_read_b128 v[184:187], v179 offset:1024
	ds_read_b128 v[188:191], v179 offset:2048
	ds_read_b128 v[192:195], v179 offset:3072
	s_add_u32 s36, s34, 0xfffc0080
	s_addc_u32 s37, s35, -1
	s_cmp_eq_u32 s67, 12
	s_cselect_b32 s39, s25, s37
	s_cselect_b32 s38, s63, s36
	s_cselect_b32 s37, s23, s66
	s_cselect_b32 s36, s64, s65
	v_lshl_add_u64 v[174:175], s[34:35], 0, v[162:163]
	s_add_i32 m0, s49, 0xc000
	ds_read_b128 v[196:199], v180
	ds_read_b128 v[200:203], v180 offset:1024
	ds_read_b128 v[204:207], v180 offset:2048
	ds_read_b128 v[208:211], v180 offset:3072
	ds_read_b128 v[212:215], v180 offset:4096
	ds_read_b128 v[216:219], v180 offset:5120
	ds_read_b128 v[220:223], v180 offset:6144
	ds_read_b128 v[224:227], v180 offset:7168
	global_load_lds_dwordx4 v[174:175], off
	v_lshl_add_u64 v[174:175], s[34:35], 0, v[164:165]
	s_add_i32 m0, s49, 0xe000
	s_nop 0
	global_load_lds_dwordx4 v[174:175], off
	s_waitcnt vmcnt(24)
	s_waitcnt lgkmcnt(0)
	s_barrier
	s_setprio 1
	s_waitcnt lgkmcnt(0)
	v_mfma_f32_16x16x32_bf16 v[124:127], v[128:131], v[196:199], 0
	v_mfma_f32_16x16x32_bf16 v[120:123], v[136:139], v[196:199], 0
	v_mfma_f32_16x16x32_bf16 v[108:111], v[128:131], v[204:207], 0
	v_mfma_f32_16x16x32_bf16 v[104:107], v[136:139], v[204:207], 0
	v_mfma_f32_16x16x32_bf16 v[92:95], v[128:131], v[212:215], 0
	v_mfma_f32_16x16x32_bf16 v[88:91], v[136:139], v[212:215], 0
	v_mfma_f32_16x16x32_bf16 v[76:79], v[128:131], v[220:223], 0
	v_mfma_f32_16x16x32_bf16 v[72:75], v[136:139], v[220:223], 0
	v_mfma_f32_16x16x32_bf16 v[124:127], v[132:135], v[200:203], v[124:127]
	v_mfma_f32_16x16x32_bf16 v[120:123], v[140:143], v[200:203], v[120:123]
	v_mfma_f32_16x16x32_bf16 v[108:111], v[132:135], v[208:211], v[108:111]
	v_mfma_f32_16x16x32_bf16 v[104:107], v[140:143], v[208:211], v[104:107]
	v_mfma_f32_16x16x32_bf16 v[92:95], v[132:135], v[216:219], v[92:95]
	v_mfma_f32_16x16x32_bf16 v[88:91], v[140:143], v[216:219], v[88:91]
	v_mfma_f32_16x16x32_bf16 v[76:79], v[132:135], v[224:227], v[76:79]
	v_mfma_f32_16x16x32_bf16 v[72:75], v[140:143], v[224:227], v[72:75]
	s_setprio 0
	s_setprio 1
	v_mfma_f32_16x16x32_bf16 v[116:119], v[170:173], v[196:199], 0
	v_mfma_f32_16x16x32_bf16 v[112:115], v[188:191], v[196:199], 0
	v_mfma_f32_16x16x32_bf16 v[100:103], v[170:173], v[204:207], 0
	v_mfma_f32_16x16x32_bf16 v[96:99], v[188:191], v[204:207], 0
	v_mfma_f32_16x16x32_bf16 v[84:87], v[170:173], v[212:215], 0
	v_mfma_f32_16x16x32_bf16 v[80:83], v[188:191], v[212:215], 0
	v_mfma_f32_16x16x32_bf16 v[68:71], v[170:173], v[220:223], 0
	v_mfma_f32_16x16x32_bf16 v[64:67], v[188:191], v[220:223], 0
	v_mfma_f32_16x16x32_bf16 v[116:119], v[184:187], v[200:203], v[116:119]
	v_mfma_f32_16x16x32_bf16 v[112:115], v[192:195], v[200:203], v[112:115]
	v_mfma_f32_16x16x32_bf16 v[100:103], v[184:187], v[208:211], v[100:103]
	v_mfma_f32_16x16x32_bf16 v[96:99], v[192:195], v[208:211], v[96:99]
	v_mfma_f32_16x16x32_bf16 v[84:87], v[184:187], v[216:219], v[84:87]
	v_mfma_f32_16x16x32_bf16 v[80:83], v[192:195], v[216:219], v[80:83]
	v_mfma_f32_16x16x32_bf16 v[68:71], v[184:187], v[224:227], v[68:71]
	v_mfma_f32_16x16x32_bf16 v[64:67], v[192:195], v[224:227], v[64:67]
	s_setprio 0
	s_barrier
	s_add_i32 s72, s60, s2
	v_lshl_add_u64 v[174:175], s[36:37], 0, v[146:147]
	s_mov_b32 m0, s72
	ds_read_b128 v[196:199], v180 offset:16384
	ds_read_b128 v[200:203], v180 offset:17408
	ds_read_b128 v[204:207], v180 offset:18432
	ds_read_b128 v[208:211], v180 offset:19456
	ds_read_b128 v[212:215], v180 offset:20480
	ds_read_b128 v[216:219], v180 offset:21504
	ds_read_b128 v[220:223], v180 offset:22528
	ds_read_b128 v[224:227], v180 offset:23552
	global_load_lds_dwordx4 v[174:175], off
	s_add_i32 m0, s72, 0x2000
	s_add_u32 s72, s36, 0x40000
	v_lshl_add_u64 v[228:229], s[36:37], 0, v[150:151]
	s_addc_u32 s73, s37, 0
	s_add_i32 s74, s61, s2
	global_load_lds_dwordx4 v[228:229], off
	v_lshl_add_u64 v[230:231], s[72:73], 0, v[146:147]
	s_mov_b32 m0, s74
	v_lshl_add_u64 v[232:233], s[38:39], 0, v[148:149]
	global_load_lds_dwordx4 v[230:231], off
	v_lshl_add_u64 v[230:231], s[72:73], 0, v[150:151]
	s_add_i32 m0, s74, 0x2000
	s_nop 0
	global_load_lds_dwordx4 v[230:231], off
	v_lshl_add_u64 v[230:231], s[38:39], 0, v[144:145]
	s_mov_b32 m0, s49
	s_nop 0
	global_load_lds_dwordx4 v[230:231], off
	s_mov_b32 m0, s50
	s_nop 0
	global_load_lds_dwordx4 v[232:233], off
	s_waitcnt vmcnt(8)
	s_waitcnt lgkmcnt(0)
	s_barrier
; #define PG8_STAGE(bufoff, gbase, voff) do { _Pragma("unroll") for (int _i = 0; _i < 2; ++_i) \
;         __builtin_amdgcn_global_load_lds((const unsigned*)((const char*)(gbase) + (voff)[_i]), (LAS unsigned*)(lds + (bufoff) + ldsw + _i * 8192), 16, 0, 0); } while (0)
; #define PG8_LDA(dst, b, h) do { _Pragma("unroll") for (int m = 0; m < 4; ++m) _Pragma("unroll") for (int k = 0; k < 2; ++k) dst[m][k] = *(const LAS bf16x8*)(lds + PG8_SA(b, h) + aoff + m * 2048 + k * 1024); } while (0)
; #define PG8_LDB(dst, b, h) do { _Pragma("unroll") for (int n = 0; n < 2; ++n) _Pragma("unroll") for (int k = 0; k < 2; ++k) dst[n][k] = *(const LAS bf16x8*)(lds + PG8_SB(b, h) + boff + n * 2048 + k * 1024); } while (0)
; #define PG8_MMA(ai, bj, At, Bt) do { __builtin_amdgcn_s_setprio(1); _Pragma("unroll") for (int m = 0; m < 4; ++m) _Pragma("unroll") for (int n = 0; n < 2; ++n) _Pragma("unroll") for (int k = 0; k < 2; ++k) \
;         acc[ai][bj][m][n] = __builtin_amdgcn_mfma_f32_16x16x32_bf16(Bt[n][k], At[m][k], acc[ai][bj][m][n], 0, 0, 0); __builtin_amdgcn_s_setprio(0); } while (0)
; #define PG8_WAIT_V(n) asm volatile("s_waitcnt vmcnt(" #n ")" ::: "memory")
; #define PG8_WAIT_L(n) asm volatile("s_waitcnt lgkmcnt(" #n ")" ::: "memory")
; #define PG8_BAR __builtin_amdgcn_s_barrier()
; #define PG8_SCHED __builtin_amdgcn_sched_barrier(0)
; template <class Epi, class Sched>
; __device__ __forceinline__ void gemm_phase(LAS unsigned char* lds, const Gemm g, const Sched& S, const Epi& E, int wave_id) {
;     ...
;             PG8_WAIT_V(8); PG8_WAIT_L(0); PG8_BAR; PG8_MMA(1, 0, At, B0); PG8_MMA(1, 1, At, B1); PG8_BAR; PG8_SCHED;
;             PG8_LDB(B0, 1, 0); PG8_LDB(B1, 1, 1); PG8_SCHED; PG8_LDA(At, 1, 0); PG8_STAGE(PG8_SA(0, 1), a2 + hstepA, voffA);
;             PG8_WAIT_V(8); PG8_WAIT_L(0); PG8_BAR; PG8_MMA(0, 0, At, B0); PG8_MMA(0, 1, At, B1); PG8_BAR; PG8_SCHED;
	s_setprio 1
	s_waitcnt lgkmcnt(0)
	v_mfma_f32_16x16x32_bf16 v[60:63], v[128:131], v[196:199], 0
	v_mfma_f32_16x16x32_bf16 v[56:59], v[136:139], v[196:199], 0
	v_mfma_f32_16x16x32_bf16 v[44:47], v[128:131], v[204:207], 0
	v_mfma_f32_16x16x32_bf16 v[40:43], v[136:139], v[204:207], 0
	v_mfma_f32_16x16x32_bf16 v[28:31], v[128:131], v[212:215], 0
	v_mfma_f32_16x16x32_bf16 v[24:27], v[136:139], v[212:215], 0
	v_mfma_f32_16x16x32_bf16 v[12:15], v[128:131], v[220:223], 0
	v_mfma_f32_16x16x32_bf16 v[8:11], v[136:139], v[220:223], 0
	v_mfma_f32_16x16x32_bf16 v[60:63], v[132:135], v[200:203], v[60:63]
	v_mfma_f32_16x16x32_bf16 v[56:59], v[140:143], v[200:203], v[56:59]
	v_mfma_f32_16x16x32_bf16 v[44:47], v[132:135], v[208:211], v[44:47]
	v_mfma_f32_16x16x32_bf16 v[40:43], v[140:143], v[208:211], v[40:43]
	v_mfma_f32_16x16x32_bf16 v[28:31], v[132:135], v[216:219], v[28:31]
	v_mfma_f32_16x16x32_bf16 v[24:27], v[140:143], v[216:219], v[24:27]
	v_mfma_f32_16x16x32_bf16 v[12:15], v[132:135], v[224:227], v[12:15]
	v_mfma_f32_16x16x32_bf16 v[8:11], v[140:143], v[224:227], v[8:11]
	s_setprio 0
	s_setprio 1
	v_mfma_f32_16x16x32_bf16 v[52:55], v[170:173], v[196:199], 0
	v_mfma_f32_16x16x32_bf16 v[48:51], v[188:191], v[196:199], 0
	v_mfma_f32_16x16x32_bf16 v[36:39], v[170:173], v[204:207], 0
	v_mfma_f32_16x16x32_bf16 v[32:35], v[188:191], v[204:207], 0
	v_mfma_f32_16x16x32_bf16 v[20:23], v[170:173], v[212:215], 0
	v_mfma_f32_16x16x32_bf16 v[16:19], v[188:191], v[212:215], 0
	v_mfma_f32_16x16x32_bf16 v[4:7], v[170:173], v[220:223], 0
	v_mfma_f32_16x16x32_bf16 v[0:3], v[188:191], v[220:223], 0
	v_mfma_f32_16x16x32_bf16 v[52:55], v[184:187], v[200:203], v[52:55]
	v_mfma_f32_16x16x32_bf16 v[48:51], v[192:195], v[200:203], v[48:51]
	v_mfma_f32_16x16x32_bf16 v[36:39], v[184:187], v[208:211], v[36:39]
	v_mfma_f32_16x16x32_bf16 v[32:35], v[192:195], v[208:211], v[32:35]
	v_mfma_f32_16x16x32_bf16 v[20:23], v[184:187], v[216:219], v[20:23]
	v_mfma_f32_16x16x32_bf16 v[16:19], v[192:195], v[216:219], v[16:19]
	v_mfma_f32_16x16x32_bf16 v[4:7], v[184:187], v[224:227], v[4:7]
	v_mfma_f32_16x16x32_bf16 v[0:3], v[192:195], v[224:227], v[0:3]
	s_setprio 0
	s_barrier
	s_add_i32 s72, 0, 0x18000
	s_add_i32 s73, 0, 0x1c000
	v_add_u32_e32 v140, s72, v177
	v_add_u32_e32 v192, s73, v177
	ds_read_b128 v[128:131], v140
	ds_read_b128 v[132:135], v140 offset:1024
	ds_read_b128 v[136:139], v140 offset:2048
	ds_read_b128 v[140:143], v140 offset:3072
	ds_read_b128 v[170:173], v192
	ds_read_b128 v[184:187], v192 offset:1024
	ds_read_b128 v[188:191], v192 offset:2048
	ds_read_b128 v[192:195], v192 offset:3072
	s_add_u32 s38, s38, 0x40000
	s_addc_u32 s39, s39, 0
	s_mov_b32 m0, s51
	v_lshl_add_u64 v[234:235], s[38:39], 0, v[144:145]
	ds_read_b128 v[196:199], v180 offset:32768
	ds_read_b128 v[200:203], v180 offset:33792
	ds_read_b128 v[204:207], v180 offset:34816
	ds_read_b128 v[208:211], v180 offset:35840
	ds_read_b128 v[212:215], v180 offset:36864
	ds_read_b128 v[216:219], v180 offset:37888
	ds_read_b128 v[220:223], v180 offset:38912
	ds_read_b128 v[224:227], v180 offset:39936
	global_load_lds_dwordx4 v[234:235], off
	v_lshl_add_u64 v[234:235], s[38:39], 0, v[148:149]
	s_mov_b32 m0, s52
	s_nop 0
	global_load_lds_dwordx4 v[234:235], off
	s_waitcnt vmcnt(8)
	s_waitcnt lgkmcnt(0)
	s_barrier
	s_setprio 1
	s_waitcnt lgkmcnt(0)
	v_mfma_f32_16x16x32_bf16 v[124:127], v[128:131], v[196:199], v[124:127]
	v_mfma_f32_16x16x32_bf16 v[120:123], v[136:139], v[196:199], v[120:123]
	v_mfma_f32_16x16x32_bf16 v[108:111], v[128:131], v[204:207], v[108:111]
	v_mfma_f32_16x16x32_bf16 v[104:107], v[136:139], v[204:207], v[104:107]
	v_mfma_f32_16x16x32_bf16 v[92:95], v[128:131], v[212:215], v[92:95]
	v_mfma_f32_16x16x32_bf16 v[88:91], v[136:139], v[212:215], v[88:91]
	v_mfma_f32_16x16x32_bf16 v[76:79], v[128:131], v[220:223], v[76:79]
	v_mfma_f32_16x16x32_bf16 v[72:75], v[136:139], v[220:223], v[72:75]
	v_mfma_f32_16x16x32_bf16 v[124:127], v[132:135], v[200:203], v[124:127]
	v_mfma_f32_16x16x32_bf16 v[120:123], v[140:143], v[200:203], v[120:123]
	v_mfma_f32_16x16x32_bf16 v[108:111], v[132:135], v[208:211], v[108:111]
	v_mfma_f32_16x16x32_bf16 v[104:107], v[140:143], v[208:211], v[104:107]
	v_mfma_f32_16x16x32_bf16 v[92:95], v[132:135], v[216:219], v[92:95]
	v_mfma_f32_16x16x32_bf16 v[88:91], v[140:143], v[216:219], v[88:91]
	v_mfma_f32_16x16x32_bf16 v[76:79], v[132:135], v[224:227], v[76:79]
	v_mfma_f32_16x16x32_bf16 v[72:75], v[140:143], v[224:227], v[72:75]
	s_setprio 0
	s_setprio 1
	v_mfma_f32_16x16x32_bf16 v[116:119], v[170:173], v[196:199], v[116:119]
	v_mfma_f32_16x16x32_bf16 v[112:115], v[188:191], v[196:199], v[112:115]
	v_mfma_f32_16x16x32_bf16 v[100:103], v[170:173], v[204:207], v[100:103]
	v_mfma_f32_16x16x32_bf16 v[96:99], v[188:191], v[204:207], v[96:99]
	v_mfma_f32_16x16x32_bf16 v[84:87], v[170:173], v[212:215], v[84:87]
	v_mfma_f32_16x16x32_bf16 v[80:83], v[188:191], v[212:215], v[80:83]
	v_mfma_f32_16x16x32_bf16 v[68:71], v[170:173], v[220:223], v[68:71]
	v_mfma_f32_16x16x32_bf16 v[64:67], v[188:191], v[220:223], v[64:67]
	v_mfma_f32_16x16x32_bf16 v[116:119], v[184:187], v[200:203], v[116:119]
	v_mfma_f32_16x16x32_bf16 v[112:115], v[192:195], v[200:203], v[112:115]
	v_mfma_f32_16x16x32_bf16 v[100:103], v[184:187], v[208:211], v[100:103]
	v_mfma_f32_16x16x32_bf16 v[96:99], v[192:195], v[208:211], v[96:99]
	v_mfma_f32_16x16x32_bf16 v[84:87], v[184:187], v[216:219], v[84:87]
	v_mfma_f32_16x16x32_bf16 v[80:83], v[192:195], v[216:219], v[80:83]
	v_mfma_f32_16x16x32_bf16 v[68:71], v[184:187], v[224:227], v[68:71]
	v_mfma_f32_16x16x32_bf16 v[64:67], v[192:195], v[224:227], v[64:67]
	s_setprio 0
	s_barrier
; #define PG8_STAGE(bufoff, gbase, voff) do { _Pragma("unroll") for (int _i = 0; _i < 2; ++_i) \
;         __builtin_amdgcn_global_load_lds((const unsigned*)((const char*)(gbase) + (voff)[_i]), (LAS unsigned*)(lds + (bufoff) + ldsw + _i * 8192), 16, 0, 0); } while (0)
; #define PG8_LDA(dst, b, h) do { _Pragma("unroll") for (int m = 0; m < 4; ++m) _Pragma("unroll") for (int k = 0; k < 2; ++k) dst[m][k] = *(const LAS bf16x8*)(lds + PG8_SA(b, h) + aoff + m * 2048 + k * 1024); } while (0)
; #define PG8_MMA(ai, bj, At, Bt) do { __builtin_amdgcn_s_setprio(1); _Pragma("unroll") for (int m = 0; m < 4; ++m) _Pragma("unroll") for (int n = 0; n < 2; ++n) _Pragma("unroll") for (int k = 0; k < 2; ++k) \
;         acc[ai][bj][m][n] = __builtin_amdgcn_mfma_f32_16x16x32_bf16(Bt[n][k], At[m][k], acc[ai][bj][m][n], 0, 0, 0); __builtin_amdgcn_s_setprio(0); } while (0)
; #define PG8_WAIT_V(n) asm volatile("s_waitcnt vmcnt(" #n ")" ::: "memory")
; #define PG8_WAIT_L(n) asm volatile("s_waitcnt lgkmcnt(" #n ")" ::: "memory")
; #define PG8_BAR __builtin_amdgcn_s_barrier()
; #define PG8_SCHED __builtin_amdgcn_sched_barrier(0)
; template <class Epi, class Sched>
; __device__ __forceinline__ void gemm_phase(LAS unsigned char* lds, const Gemm g, const Sched& S, const Epi& E, int wave_id) {
;     ...
;             PG8_LDA(At, 1, 1); PG8_STAGE(PG8_SB(1, 0), b3, voffB); PG8_STAGE(PG8_SB(1, 1), b3 + hstepB, voffB); PG8_STAGE(PG8_SA(1, 0), a3, voffA);
;             PG8_WAIT_V(8); PG8_WAIT_L(0); PG8_BAR; PG8_MMA(1, 0, At, B0); PG8_MMA(1, 1, At, B1); PG8_BAR; PG8_SCHED;
;         }
	s_add_i32 s38, s72, s2
	v_lshl_add_u64 v[174:175], v[174:175], 0, s[16:17]
	s_mov_b32 m0, s38
	ds_read_b128 v[196:199], v180 offset:49152
	ds_read_b128 v[200:203], v180 offset:50176
	ds_read_b128 v[204:207], v180 offset:51200
	ds_read_b128 v[208:211], v180 offset:52224
	ds_read_b128 v[212:215], v180 offset:53248
	ds_read_b128 v[216:219], v180 offset:54272
	ds_read_b128 v[220:223], v180 offset:55296
	ds_read_b128 v[224:227], v180 offset:56320
	global_load_lds_dwordx4 v[174:175], off
	s_add_i32 m0, s38, 0x2000
	s_add_u32 s36, s36, 0x40080
	v_lshl_add_u64 v[174:175], v[228:229], 0, s[16:17]
	s_addc_u32 s37, s37, 0
	s_add_i32 s38, s73, s2
	global_load_lds_dwordx4 v[174:175], off
	v_lshl_add_u64 v[174:175], s[36:37], 0, v[146:147]
	s_mov_b32 m0, s38
	s_nop 0
	global_load_lds_dwordx4 v[174:175], off
	v_lshl_add_u64 v[174:175], s[36:37], 0, v[150:151]
	s_add_i32 m0, s38, 0x2000
	s_nop 0
	global_load_lds_dwordx4 v[174:175], off
	v_lshl_add_u64 v[174:175], v[230:231], 0, s[16:17]
	s_mov_b32 m0, s54
	s_nop 0
	global_load_lds_dwordx4 v[174:175], off
	v_lshl_add_u64 v[174:175], v[232:233], 0, s[16:17]
	s_mov_b32 m0, s55
	s_nop 0
	global_load_lds_dwordx4 v[174:175], off
	s_waitcnt vmcnt(8)
	s_waitcnt lgkmcnt(0)
	s_barrier
	s_setprio 1
	s_waitcnt lgkmcnt(0)
	v_mfma_f32_16x16x32_bf16 v[60:63], v[128:131], v[196:199], v[60:63]
	v_mfma_f32_16x16x32_bf16 v[56:59], v[136:139], v[196:199], v[56:59]
	v_mfma_f32_16x16x32_bf16 v[44:47], v[128:131], v[204:207], v[44:47]
	v_mfma_f32_16x16x32_bf16 v[40:43], v[136:139], v[204:207], v[40:43]
	v_mfma_f32_16x16x32_bf16 v[28:31], v[128:131], v[212:215], v[28:31]
	v_mfma_f32_16x16x32_bf16 v[24:27], v[136:139], v[212:215], v[24:27]
	v_mfma_f32_16x16x32_bf16 v[12:15], v[128:131], v[220:223], v[12:15]
	v_mfma_f32_16x16x32_bf16 v[8:11], v[136:139], v[220:223], v[8:11]
	v_mfma_f32_16x16x32_bf16 v[60:63], v[132:135], v[200:203], v[60:63]
	v_mfma_f32_16x16x32_bf16 v[56:59], v[140:143], v[200:203], v[56:59]
	v_mfma_f32_16x16x32_bf16 v[44:47], v[132:135], v[208:211], v[44:47]
	v_mfma_f32_16x16x32_bf16 v[40:43], v[140:143], v[208:211], v[40:43]
	v_mfma_f32_16x16x32_bf16 v[28:31], v[132:135], v[216:219], v[28:31]
	v_mfma_f32_16x16x32_bf16 v[24:27], v[140:143], v[216:219], v[24:27]
	v_mfma_f32_16x16x32_bf16 v[12:15], v[132:135], v[224:227], v[12:15]
	v_mfma_f32_16x16x32_bf16 v[8:11], v[140:143], v[224:227], v[8:11]
	s_setprio 0
	s_setprio 1
	v_mfma_f32_16x16x32_bf16 v[52:55], v[170:173], v[196:199], v[52:55]
	v_mfma_f32_16x16x32_bf16 v[48:51], v[188:191], v[196:199], v[48:51]
	v_mfma_f32_16x16x32_bf16 v[36:39], v[170:173], v[204:207], v[36:39]
	v_mfma_f32_16x16x32_bf16 v[32:35], v[188:191], v[204:207], v[32:35]
	v_mfma_f32_16x16x32_bf16 v[20:23], v[170:173], v[212:215], v[20:23]
	v_mfma_f32_16x16x32_bf16 v[16:19], v[188:191], v[212:215], v[16:19]
	v_mfma_f32_16x16x32_bf16 v[4:7], v[170:173], v[220:223], v[4:7]
	v_mfma_f32_16x16x32_bf16 v[0:3], v[188:191], v[220:223], v[0:3]
	v_mfma_f32_16x16x32_bf16 v[52:55], v[184:187], v[200:203], v[52:55]
	v_mfma_f32_16x16x32_bf16 v[48:51], v[192:195], v[200:203], v[48:51]
	v_mfma_f32_16x16x32_bf16 v[36:39], v[184:187], v[208:211], v[36:39]
	v_mfma_f32_16x16x32_bf16 v[32:35], v[192:195], v[208:211], v[32:35]
	v_mfma_f32_16x16x32_bf16 v[20:23], v[184:187], v[216:219], v[20:23]
	v_mfma_f32_16x16x32_bf16 v[16:19], v[192:195], v[216:219], v[16:19]
	v_mfma_f32_16x16x32_bf16 v[4:7], v[184:187], v[224:227], v[4:7]
	v_mfma_f32_16x16x32_bf16 v[0:3], v[192:195], v[224:227], v[0:3]
	s_setprio 0
	s_barrier
	s_add_i32 s67, s67, 2
	s_add_u32 s34, s34, 0x100
	s_addc_u32 s35, s35, 0
	s_add_u32 s65, s65, 0x100
	s_addc_u32 s66, s66, 0
	s_cmp_gt_u32 s67, 13

;     __device__ bool next(int i, Unit& u) const { if (r0 + i >= r1) return false; return base.next(r0 + i, u); }
;     __device__ bool next(int i, Unit& u) const { const int L = i * G + c; if (L >= 256) return false; u.pm = L; u.pn = L >> 3; return true; }
; #define PG8_STAGE(bufoff, gbase, voff) do { _Pragma("unroll") for (int _i = 0; _i < 2; ++_i) \
;         __builtin_amdgcn_global_load_lds((const unsigned*)((const char*)(gbase) + (voff)[_i]), (LAS unsigned*)(lds + (bufoff) + ldsw + _i * 8192), 16, 0, 0); } while (0)
; #define PG8_LDA(dst, b, h) do { _Pragma("unroll") for (int m = 0; m < 4; ++m) _Pragma("unroll") for (int k = 0; k < 2; ++k) dst[m][k] = *(const LAS bf16x8*)(lds + PG8_SA(b, h) + aoff + m * 2048 + k * 1024); } while (0)
; #define PG8_LDB(dst, b, h) do { _Pragma("unroll") for (int n = 0; n < 2; ++n) _Pragma("unroll") for (int k = 0; k < 2; ++k) dst[n][k] = *(const LAS bf16x8*)(lds + PG8_SB(b, h) + boff + n * 2048 + k * 1024); } while (0)
; #define PG8_WAIT_V(n) asm volatile("s_waitcnt vmcnt(" #n ")" ::: "memory")
; #define PG8_WAIT_L(n) asm volatile("s_waitcnt lgkmcnt(" #n ")" ::: "memory")
; template <class Epi, class Sched>
; __device__ __forceinline__ void gemm_phase(LAS unsigned char* lds, const Gemm g, const Sched& S, const Epi& E, int wave_id) {
;     ...
;         const bool has_next = S.next(ui + 1, nxt);
;         const char* nA = has_next ? (const char*)g.A + (size_t)nxt.pm * tstepA : cA; const char* nB = has_next ? (const char*)g.Bt + (size_t)nxt.pn * tstepB : cB;
;         for (int t = 0; t < nt; t += 2) {
;             const bool last = (t == nt - 2);
;             const char* a1 = cA + (size_t)(t + 1) * kstep;
;             const char* a2 = last ? nA : cA + (size_t)(t + 2) * kstep; const char* b2 = last ? nB : cB + (size_t)(t + 2) * kstep;
;             const char* a3 = a2 + kstep; const char* b3 = b2 + kstep;
;             PG8_LDB(B0, 0, 0); PG8_LDB(B1, 0, 1); PG8_SCHED; PG8_LDA(At, 0, 0); PG8_STAGE(PG8_SA(1, 1), a1 + hstepA, voffA);
;             PG8_WAIT_V(8); PG8_WAIT_L(0); PG8_BAR; PG8_MMA(0, 0, At, B0); PG8_MMA(0, 1, At, B1); PG8_BAR; PG8_SCHED;
;             PG8_LDA(At, 0, 1); PG8_STAGE(PG8_SB(0, 0), b2, voffB); PG8_STAGE(PG8_SB(0, 1), b2 + hstepB, voffB); PG8_STAGE(PG8_SA(0, 0), a2, voffA);
;             PG8_WAIT_V(8); PG8_WAIT_L(0); PG8_BAR; PG8_MMA(1, 0, At, B0); PG8_MMA(1, 1, At, B1); PG8_BAR; PG8_SCHED;
.LBB0_1276:
	s_ashr_i32 s19, s18, 31
	s_lshl_b64 s[20:21], s[18:19], 17
	s_add_u32 s20, s47, s20
	s_addc_u32 s21, s48, s21
	s_and_b64 s[22:23], s[4:5], exec
	s_cselect_b32 s19, s21, s29
	s_cselect_b32 s63, s20, s28
	s_ashr_i32 s17, s16, 31
	s_lshl_b64 s[22:23], s[16:17], 17
	s_add_u32 s22, s49, s22
	s_addc_u32 s23, s50, s23
	s_and_b64 s[30:31], s[4:5], exec
	s_cselect_b32 s17, s23, s27
	s_cselect_b32 s64, s22, s26
	s_mov_b32 s36, 0
	s_mov_b64 s[30:31], -1
	s_mov_b64 s[34:35], 0
	s_add_u32 s37, s28, s36
	s_addc_u32 s42, s29, 0
	s_add_u32 s40, s37, 0x100
	s_addc_u32 s41, s42, 0
	s_and_b64 s[38:39], s[34:35], exec
	s_cselect_b32 s39, s19, s41
	s_cselect_b32 s38, s63, s40
	s_add_u32 s36, s26, s36
	s_addc_u32 s40, s27, 0
	s_add_u32 s36, s36, 0x100
	s_addc_u32 s40, s40, 0
	s_and_b64 s[34:35], s[34:35], exec
	s_cselect_b32 s41, s17, s40
	s_cselect_b32 s40, s64, s36
	s_add_u32 s44, s37, 0x10080
	ds_read_b128 v[152:155], v147
	ds_read_b128 v[156:159], v147 offset:1024
	ds_read_b128 v[160:163], v147 offset:2048
	ds_read_b128 v[164:167], v147 offset:3072
	ds_read_b128 v[168:171], v148
	ds_read_b128 v[172:175], v148 offset:1024
	ds_read_b128 v[176:179], v148 offset:2048
	ds_read_b128 v[180:183], v148 offset:3072
	s_addc_u32 s45, s42, 0
	s_add_i32 s76, s61, s2
	s_add_i32 m0, s51, 0xc000
	s_add_i32 s79, s51, 0xe000
	s_add_i32 s73, s76, 0x2000
	s_add_u32 s42, s40, 0x10000
	s_addc_u32 s43, s41, 0
	s_add_i32 s75, s62, s2
	s_add_i32 s74, s75, 0x2000
	s_add_i32 s72, 0, 0x18000
	s_add_i32 s67, 0, 0x1c000
	s_add_u32 s36, s38, 0x10000
	s_addc_u32 s37, s39, 0
	s_add_i32 s66, s72, s2
	s_add_i32 s65, s66, 0x2000
	s_add_u32 s34, s40, 0x10080
	s_addc_u32 s35, s41, 0
	s_add_i32 s78, s67, s2
	s_add_i32 s77, s78, 0x2000
	v_lshl_add_u64 v[216:217], s[44:45], 0, v[128:129]
	ds_read_b128 v[184:187], v149
	ds_read_b128 v[188:191], v149 offset:1024
	ds_read_b128 v[192:195], v149 offset:2048
	ds_read_b128 v[196:199], v149 offset:3072
	ds_read_b128 v[200:203], v149 offset:4096
	ds_read_b128 v[204:207], v149 offset:5120
	ds_read_b128 v[208:211], v149 offset:6144
	ds_read_b128 v[212:215], v149 offset:7168
	global_load_lds_dwordx4 v[216:217], off
	v_lshl_add_u64 v[216:217], s[44:45], 0, v[132:133]
	s_mov_b32 m0, s79
	s_nop 0
	global_load_lds_dwordx4 v[216:217], off
	s_waitcnt vmcnt(24)
	s_waitcnt lgkmcnt(0)
	s_barrier
	s_setprio 1
	s_waitcnt lgkmcnt(0)
	v_mfma_f32_16x16x32_bf16 v[124:127], v[152:155], v[184:187], 0
	v_mfma_f32_16x16x32_bf16 v[120:123], v[160:163], v[184:187], 0
	v_mfma_f32_16x16x32_bf16 v[108:111], v[152:155], v[192:195], 0
	v_mfma_f32_16x16x32_bf16 v[104:107], v[160:163], v[192:195], 0
	v_mfma_f32_16x16x32_bf16 v[92:95], v[152:155], v[200:203], 0
	v_mfma_f32_16x16x32_bf16 v[88:91], v[160:163], v[200:203], 0
	v_mfma_f32_16x16x32_bf16 v[76:79], v[152:155], v[208:211], 0
	v_mfma_f32_16x16x32_bf16 v[72:75], v[160:163], v[208:211], 0
	v_mfma_f32_16x16x32_bf16 v[124:127], v[156:159], v[188:191], v[124:127]
	v_mfma_f32_16x16x32_bf16 v[120:123], v[164:167], v[188:191], v[120:123]
	v_mfma_f32_16x16x32_bf16 v[108:111], v[156:159], v[196:199], v[108:111]
	v_mfma_f32_16x16x32_bf16 v[104:107], v[164:167], v[196:199], v[104:107]
	v_mfma_f32_16x16x32_bf16 v[92:95], v[156:159], v[204:207], v[92:95]
	v_mfma_f32_16x16x32_bf16 v[88:91], v[164:167], v[204:207], v[88:91]
	v_mfma_f32_16x16x32_bf16 v[76:79], v[156:159], v[212:215], v[76:79]
	v_mfma_f32_16x16x32_bf16 v[72:75], v[164:167], v[212:215], v[72:75]
	s_setprio 0
	s_setprio 1
	v_mfma_f32_16x16x32_bf16 v[116:119], v[168:171], v[184:187], 0
	v_mfma_f32_16x16x32_bf16 v[112:115], v[176:179], v[184:187], 0
	v_mfma_f32_16x16x32_bf16 v[100:103], v[168:171], v[192:195], 0
	v_mfma_f32_16x16x32_bf16 v[96:99], v[176:179], v[192:195], 0
	v_mfma_f32_16x16x32_bf16 v[84:87], v[168:171], v[200:203], 0
	v_mfma_f32_16x16x32_bf16 v[80:83], v[176:179], v[200:203], 0
	v_mfma_f32_16x16x32_bf16 v[68:71], v[168:171], v[208:211], 0
	v_mfma_f32_16x16x32_bf16 v[64:67], v[176:179], v[208:211], 0
	v_mfma_f32_16x16x32_bf16 v[116:119], v[172:175], v[188:191], v[116:119]
	v_mfma_f32_16x16x32_bf16 v[112:115], v[180:183], v[188:191], v[112:115]
	v_mfma_f32_16x16x32_bf16 v[100:103], v[172:175], v[196:199], v[100:103]
	v_mfma_f32_16x16x32_bf16 v[96:99], v[180:183], v[196:199], v[96:99]
	v_mfma_f32_16x16x32_bf16 v[84:87], v[172:175], v[204:207], v[84:87]
	v_mfma_f32_16x16x32_bf16 v[80:83], v[180:183], v[204:207], v[80:83]
	v_mfma_f32_16x16x32_bf16 v[68:71], v[172:175], v[212:215], v[68:71]
	v_mfma_f32_16x16x32_bf16 v[64:67], v[180:183], v[212:215], v[64:67]
	s_setprio 0
	s_barrier
	s_mov_b32 m0, s76
	v_lshl_add_u64 v[216:217], s[40:41], 0, v[130:131]
	ds_read_b128 v[184:187], v149 offset:16384
	ds_read_b128 v[188:191], v149 offset:17408
	ds_read_b128 v[192:195], v149 offset:18432
	ds_read_b128 v[196:199], v149 offset:19456
	ds_read_b128 v[200:203], v149 offset:20480
	ds_read_b128 v[204:207], v149 offset:21504
	ds_read_b128 v[208:211], v149 offset:22528
	ds_read_b128 v[212:215], v149 offset:23552
	global_load_lds_dwordx4 v[216:217], off
	v_lshl_add_u64 v[218:219], s[40:41], 0, v[134:135]
	s_mov_b32 m0, s73
	v_lshl_add_u64 v[220:221], s[42:43], 0, v[130:131]
	global_load_lds_dwordx4 v[218:219], off
	s_mov_b32 m0, s75
	v_lshl_add_u64 v[222:223], s[38:39], 0, v[132:133]
	global_load_lds_dwordx4 v[220:221], off
	v_lshl_add_u64 v[220:221], s[42:43], 0, v[134:135]
	s_mov_b32 m0, s74
	s_nop 0
	global_load_lds_dwordx4 v[220:221], off
	v_lshl_add_u64 v[220:221], s[38:39], 0, v[128:129]
	s_mov_b32 m0, s51
	s_nop 0
	global_load_lds_dwordx4 v[220:221], off
	s_mov_b32 m0, s52
	s_nop 0
	global_load_lds_dwordx4 v[222:223], off
	s_waitcnt vmcnt(8)
	s_waitcnt lgkmcnt(0)
	s_barrier
; #define PG8_STAGE(bufoff, gbase, voff) do { _Pragma("unroll") for (int _i = 0; _i < 2; ++_i) \
;         __builtin_amdgcn_global_load_lds((const unsigned*)((const char*)(gbase) + (voff)[_i]), (LAS unsigned*)(lds + (bufoff) + ldsw + _i * 8192), 16, 0, 0); } while (0)
; #define PG8_LDA(dst, b, h) do { _Pragma("unroll") for (int m = 0; m < 4; ++m) _Pragma("unroll") for (int k = 0; k < 2; ++k) dst[m][k] = *(const LAS bf16x8*)(lds + PG8_SA(b, h) + aoff + m * 2048 + k * 1024); } while (0)
; #define PG8_LDB(dst, b, h) do { _Pragma("unroll") for (int n = 0; n < 2; ++n) _Pragma("unroll") for (int k = 0; k < 2; ++k) dst[n][k] = *(const LAS bf16x8*)(lds + PG8_SB(b, h) + boff + n * 2048 + k * 1024); } while (0)
; #define PG8_MMA(ai, bj, At, Bt) do { __builtin_amdgcn_s_setprio(1); _Pragma("unroll") for (int m = 0; m < 4; ++m) _Pragma("unroll") for (int n = 0; n < 2; ++n) _Pragma("unroll") for (int k = 0; k < 2; ++k) \
;         acc[ai][bj][m][n] = __builtin_amdgcn_mfma_f32_16x16x32_bf16(Bt[n][k], At[m][k], acc[ai][bj][m][n], 0, 0, 0); __builtin_amdgcn_s_setprio(0); } while (0)
; #define PG8_WAIT_V(n) asm volatile("s_waitcnt vmcnt(" #n ")" ::: "memory")
; #define PG8_WAIT_L(n) asm volatile("s_waitcnt lgkmcnt(" #n ")" ::: "memory")
; #define PG8_BAR __builtin_amdgcn_s_barrier()
; #define PG8_SCHED __builtin_amdgcn_sched_barrier(0)
; template <class Epi, class Sched>
; __device__ __forceinline__ void gemm_phase(LAS unsigned char* lds, const Gemm g, const Sched& S, const Epi& E, int wave_id) {
;     ...
;             PG8_WAIT_V(8); PG8_WAIT_L(0); PG8_BAR; PG8_MMA(1, 0, At, B0); PG8_MMA(1, 1, At, B1); PG8_BAR; PG8_SCHED;
;             PG8_LDB(B0, 1, 0); PG8_LDB(B1, 1, 1); PG8_SCHED; PG8_LDA(At, 1, 0); PG8_STAGE(PG8_SA(0, 1), a2 + hstepA, voffA);
;             PG8_WAIT_V(8); PG8_WAIT_L(0); PG8_BAR; PG8_MMA(0, 0, At, B0); PG8_MMA(0, 1, At, B1); PG8_BAR; PG8_SCHED;
	s_setprio 1
	s_waitcnt lgkmcnt(0)
	v_mfma_f32_16x16x32_bf16 v[60:63], v[152:155], v[184:187], 0
	v_mfma_f32_16x16x32_bf16 v[56:59], v[160:163], v[184:187], 0
	v_mfma_f32_16x16x32_bf16 v[44:47], v[152:155], v[192:195], 0
	v_mfma_f32_16x16x32_bf16 v[40:43], v[160:163], v[192:195], 0
	v_mfma_f32_16x16x32_bf16 v[28:31], v[152:155], v[200:203], 0
	v_mfma_f32_16x16x32_bf16 v[24:27], v[160:163], v[200:203], 0
	v_mfma_f32_16x16x32_bf16 v[12:15], v[152:155], v[208:211], 0
	v_mfma_f32_16x16x32_bf16 v[8:11], v[160:163], v[208:211], 0
	v_mfma_f32_16x16x32_bf16 v[60:63], v[156:159], v[188:191], v[60:63]
	v_mfma_f32_16x16x32_bf16 v[56:59], v[164:167], v[188:191], v[56:59]
	v_mfma_f32_16x16x32_bf16 v[44:47], v[156:159], v[196:199], v[44:47]
	v_mfma_f32_16x16x32_bf16 v[40:43], v[164:167], v[196:199], v[40:43]
	v_mfma_f32_16x16x32_bf16 v[28:31], v[156:159], v[204:207], v[28:31]
	v_mfma_f32_16x16x32_bf16 v[24:27], v[164:167], v[204:207], v[24:27]
	v_mfma_f32_16x16x32_bf16 v[12:15], v[156:159], v[212:215], v[12:15]
	v_mfma_f32_16x16x32_bf16 v[8:11], v[164:167], v[212:215], v[8:11]
	s_setprio 0
	s_setprio 1
	v_mfma_f32_16x16x32_bf16 v[52:55], v[168:171], v[184:187], 0
	v_mfma_f32_16x16x32_bf16 v[48:51], v[176:179], v[184:187], 0
	v_mfma_f32_16x16x32_bf16 v[36:39], v[168:171], v[192:195], 0
	v_mfma_f32_16x16x32_bf16 v[32:35], v[176:179], v[192:195], 0
	v_mfma_f32_16x16x32_bf16 v[20:23], v[168:171], v[200:203], 0
	v_mfma_f32_16x16x32_bf16 v[16:19], v[176:179], v[200:203], 0
	v_mfma_f32_16x16x32_bf16 v[4:7], v[168:171], v[208:211], 0
	v_mfma_f32_16x16x32_bf16 v[0:3], v[176:179], v[208:211], 0
	v_mfma_f32_16x16x32_bf16 v[52:55], v[172:175], v[188:191], v[52:55]
	v_mfma_f32_16x16x32_bf16 v[48:51], v[180:183], v[188:191], v[48:51]
	v_mfma_f32_16x16x32_bf16 v[36:39], v[172:175], v[196:199], v[36:39]
	v_mfma_f32_16x16x32_bf16 v[32:35], v[180:183], v[196:199], v[32:35]
	v_mfma_f32_16x16x32_bf16 v[20:23], v[172:175], v[204:207], v[20:23]
	v_mfma_f32_16x16x32_bf16 v[16:19], v[180:183], v[204:207], v[16:19]
	v_mfma_f32_16x16x32_bf16 v[4:7], v[172:175], v[212:215], v[4:7]
	v_mfma_f32_16x16x32_bf16 v[0:3], v[180:183], v[212:215], v[0:3]
	s_setprio 0
	s_barrier
	v_add_u32_e32 v164, s72, v146
	v_add_u32_e32 v180, s67, v146
	ds_read_b128 v[152:155], v164
	ds_read_b128 v[156:159], v164 offset:1024
	ds_read_b128 v[160:163], v164 offset:2048
	ds_read_b128 v[164:167], v164 offset:3072
	ds_read_b128 v[168:171], v180
	ds_read_b128 v[172:175], v180 offset:1024
	ds_read_b128 v[176:179], v180 offset:2048
	ds_read_b128 v[180:183], v180 offset:3072
	s_mov_b32 m0, s53
	v_lshl_add_u64 v[224:225], s[36:37], 0, v[128:129]
	ds_read_b128 v[184:187], v149 offset:32768
	ds_read_b128 v[188:191], v149 offset:33792
	ds_read_b128 v[192:195], v149 offset:34816
	ds_read_b128 v[196:199], v149 offset:35840
	ds_read_b128 v[200:203], v149 offset:36864
	ds_read_b128 v[204:207], v149 offset:37888
	ds_read_b128 v[208:211], v149 offset:38912
	ds_read_b128 v[212:215], v149 offset:39936
	global_load_lds_dwordx4 v[224:225], off
	v_lshl_add_u64 v[224:225], s[36:37], 0, v[132:133]
	s_mov_b32 m0, s54
	s_nop 0
	global_load_lds_dwordx4 v[224:225], off
	s_waitcnt vmcnt(8)
	s_waitcnt lgkmcnt(0)
	s_barrier
	s_setprio 1
	s_waitcnt lgkmcnt(0)
	v_mfma_f32_16x16x32_bf16 v[124:127], v[152:155], v[184:187], v[124:127]
	v_mfma_f32_16x16x32_bf16 v[120:123], v[160:163], v[184:187], v[120:123]
	v_mfma_f32_16x16x32_bf16 v[108:111], v[152:155], v[192:195], v[108:111]
	v_mfma_f32_16x16x32_bf16 v[104:107], v[160:163], v[192:195], v[104:107]
	v_mfma_f32_16x16x32_bf16 v[92:95], v[152:155], v[200:203], v[92:95]
	v_mfma_f32_16x16x32_bf16 v[88:91], v[160:163], v[200:203], v[88:91]
	v_mfma_f32_16x16x32_bf16 v[76:79], v[152:155], v[208:211], v[76:79]
	v_mfma_f32_16x16x32_bf16 v[72:75], v[160:163], v[208:211], v[72:75]
	v_mfma_f32_16x16x32_bf16 v[124:127], v[156:159], v[188:191], v[124:127]
	v_mfma_f32_16x16x32_bf16 v[120:123], v[164:167], v[188:191], v[120:123]
	v_mfma_f32_16x16x32_bf16 v[108:111], v[156:159], v[196:199], v[108:111]
	v_mfma_f32_16x16x32_bf16 v[104:107], v[164:167], v[196:199], v[104:107]
	v_mfma_f32_16x16x32_bf16 v[92:95], v[156:159], v[204:207], v[92:95]
	v_mfma_f32_16x16x32_bf16 v[88:91], v[164:167], v[204:207], v[88:91]
	v_mfma_f32_16x16x32_bf16 v[76:79], v[156:159], v[212:215], v[76:79]
	v_mfma_f32_16x16x32_bf16 v[72:75], v[164:167], v[212:215], v[72:75]
	s_setprio 0
	s_setprio 1
	v_mfma_f32_16x16x32_bf16 v[116:119], v[168:171], v[184:187], v[116:119]
	v_mfma_f32_16x16x32_bf16 v[112:115], v[176:179], v[184:187], v[112:115]
	v_mfma_f32_16x16x32_bf16 v[100:103], v[168:171], v[192:195], v[100:103]
	v_mfma_f32_16x16x32_bf16 v[96:99], v[176:179], v[192:195], v[96:99]
	v_mfma_f32_16x16x32_bf16 v[84:87], v[168:171], v[200:203], v[84:87]
	v_mfma_f32_16x16x32_bf16 v[80:83], v[176:179], v[200:203], v[80:83]
	v_mfma_f32_16x16x32_bf16 v[68:71], v[168:171], v[208:211], v[68:71]
	v_mfma_f32_16x16x32_bf16 v[64:67], v[176:179], v[208:211], v[64:67]
	v_mfma_f32_16x16x32_bf16 v[116:119], v[172:175], v[188:191], v[116:119]
	v_mfma_f32_16x16x32_bf16 v[112:115], v[180:183], v[188:191], v[112:115]
	v_mfma_f32_16x16x32_bf16 v[100:103], v[172:175], v[196:199], v[100:103]
	v_mfma_f32_16x16x32_bf16 v[96:99], v[180:183], v[196:199], v[96:99]
	v_mfma_f32_16x16x32_bf16 v[84:87], v[172:175], v[204:207], v[84:87]
	v_mfma_f32_16x16x32_bf16 v[80:83], v[180:183], v[204:207], v[80:83]
	v_mfma_f32_16x16x32_bf16 v[68:71], v[172:175], v[212:215], v[68:71]
	v_mfma_f32_16x16x32_bf16 v[64:67], v[180:183], v[212:215], v[64:67]
	s_setprio 0
	s_barrier
; #define PG8_STAGE(bufoff, gbase, voff) do { _Pragma("unroll") for (int _i = 0; _i < 2; ++_i) \
;         __builtin_amdgcn_global_load_lds((const unsigned*)((const char*)(gbase) + (voff)[_i]), (LAS unsigned*)(lds + (bufoff) + ldsw + _i * 8192), 16, 0, 0); } while (0)
; #define PG8_LDA(dst, b, h) do { _Pragma("unroll") for (int m = 0; m < 4; ++m) _Pragma("unroll") for (int k = 0; k < 2; ++k) dst[m][k] = *(const LAS bf16x8*)(lds + PG8_SA(b, h) + aoff + m * 2048 + k * 1024); } while (0)
; #define PG8_MMA(ai, bj, At, Bt) do { __builtin_amdgcn_s_setprio(1); _Pragma("unroll") for (int m = 0; m < 4; ++m) _Pragma("unroll") for (int n = 0; n < 2; ++n) _Pragma("unroll") for (int k = 0; k < 2; ++k) \
;         acc[ai][bj][m][n] = __builtin_amdgcn_mfma_f32_16x16x32_bf16(Bt[n][k], At[m][k], acc[ai][bj][m][n], 0, 0, 0); __builtin_amdgcn_s_setprio(0); } while (0)
; #define PG8_WAIT_V(n) asm volatile("s_waitcnt vmcnt(" #n ")" ::: "memory")
; #define PG8_WAIT_L(n) asm volatile("s_waitcnt lgkmcnt(" #n ")" ::: "memory")
; #define PG8_BAR __builtin_amdgcn_s_barrier()
; #define PG8_SCHED __builtin_amdgcn_sched_barrier(0)
; template <class Epi, class Sched>
; __device__ __forceinline__ void gemm_phase(LAS unsigned char* lds, const Gemm g, const Sched& S, const Epi& E, int wave_id) {
;     ...
;             PG8_LDA(At, 1, 1); PG8_STAGE(PG8_SB(1, 0), b3, voffB); PG8_STAGE(PG8_SB(1, 1), b3 + hstepB, voffB); PG8_STAGE(PG8_SA(1, 0), a3, voffA);
;             PG8_WAIT_V(8); PG8_WAIT_L(0); PG8_BAR; PG8_MMA(1, 0, At, B0); PG8_MMA(1, 1, At, B1); PG8_BAR; PG8_SCHED;
;         }
	s_mov_b32 m0, s66
	v_lshl_add_u64 v[216:217], v[216:217], 0, s[12:13]
	ds_read_b128 v[184:187], v149 offset:49152
	ds_read_b128 v[188:191], v149 offset:50176
	ds_read_b128 v[192:195], v149 offset:51200
	ds_read_b128 v[196:199], v149 offset:52224
	ds_read_b128 v[200:203], v149 offset:53248
	ds_read_b128 v[204:207], v149 offset:54272
	ds_read_b128 v[208:211], v149 offset:55296
	ds_read_b128 v[212:215], v149 offset:56320
	global_load_lds_dwordx4 v[216:217], off
	v_lshl_add_u64 v[216:217], v[218:219], 0, s[12:13]
	s_mov_b32 m0, s65
	s_nop 0
	global_load_lds_dwordx4 v[216:217], off
	v_lshl_add_u64 v[216:217], s[34:35], 0, v[130:131]
	s_mov_b32 m0, s78
	s_nop 0
	global_load_lds_dwordx4 v[216:217], off
	v_lshl_add_u64 v[216:217], s[34:35], 0, v[134:135]
	s_mov_b32 m0, s77
	s_nop 0
	global_load_lds_dwordx4 v[216:217], off
	v_lshl_add_u64 v[216:217], v[220:221], 0, s[12:13]
	s_mov_b32 m0, s58
	s_nop 0
	global_load_lds_dwordx4 v[216:217], off
	v_lshl_add_u64 v[216:217], v[222:223], 0, s[12:13]
	s_mov_b32 m0, s59
	s_nop 0
	global_load_lds_dwordx4 v[216:217], off
	s_waitcnt vmcnt(8)
	s_waitcnt lgkmcnt(0)
	s_barrier
	s_setprio 1
	s_waitcnt lgkmcnt(0)
	v_mfma_f32_16x16x32_bf16 v[60:63], v[152:155], v[184:187], v[60:63]
	v_mfma_f32_16x16x32_bf16 v[56:59], v[160:163], v[184:187], v[56:59]
	v_mfma_f32_16x16x32_bf16 v[44:47], v[152:155], v[192:195], v[44:47]
	v_mfma_f32_16x16x32_bf16 v[40:43], v[160:163], v[192:195], v[40:43]
	v_mfma_f32_16x16x32_bf16 v[28:31], v[152:155], v[200:203], v[28:31]
	v_mfma_f32_16x16x32_bf16 v[24:27], v[160:163], v[200:203], v[24:27]
	v_mfma_f32_16x16x32_bf16 v[12:15], v[152:155], v[208:211], v[12:15]
	v_mfma_f32_16x16x32_bf16 v[8:11], v[160:163], v[208:211], v[8:11]
	v_mfma_f32_16x16x32_bf16 v[60:63], v[156:159], v[188:191], v[60:63]
	v_mfma_f32_16x16x32_bf16 v[56:59], v[164:167], v[188:191], v[56:59]
	v_mfma_f32_16x16x32_bf16 v[44:47], v[156:159], v[196:199], v[44:47]
	v_mfma_f32_16x16x32_bf16 v[40:43], v[164:167], v[196:199], v[40:43]
	v_mfma_f32_16x16x32_bf16 v[28:31], v[156:159], v[204:207], v[28:31]
	v_mfma_f32_16x16x32_bf16 v[24:27], v[164:167], v[204:207], v[24:27]
	v_mfma_f32_16x16x32_bf16 v[12:15], v[156:159], v[212:215], v[12:15]
	v_mfma_f32_16x16x32_bf16 v[8:11], v[164:167], v[212:215], v[8:11]
	s_setprio 0
	s_setprio 1
	v_mfma_f32_16x16x32_bf16 v[52:55], v[168:171], v[184:187], v[52:55]
	v_mfma_f32_16x16x32_bf16 v[48:51], v[176:179], v[184:187], v[48:51]
	v_mfma_f32_16x16x32_bf16 v[36:39], v[168:171], v[192:195], v[36:39]
	v_mfma_f32_16x16x32_bf16 v[32:35], v[176:179], v[192:195], v[32:35]
	v_mfma_f32_16x16x32_bf16 v[20:23], v[168:171], v[200:203], v[20:23]
	v_mfma_f32_16x16x32_bf16 v[16:19], v[176:179], v[200:203], v[16:19]
	v_mfma_f32_16x16x32_bf16 v[4:7], v[168:171], v[208:211], v[4:7]
	v_mfma_f32_16x16x32_bf16 v[0:3], v[176:179], v[208:211], v[0:3]
	v_mfma_f32_16x16x32_bf16 v[52:55], v[172:175], v[188:191], v[52:55]
	v_mfma_f32_16x16x32_bf16 v[48:51], v[180:183], v[188:191], v[48:51]
	v_mfma_f32_16x16x32_bf16 v[36:39], v[172:175], v[196:199], v[36:39]
	v_mfma_f32_16x16x32_bf16 v[32:35], v[180:183], v[196:199], v[32:35]
	v_mfma_f32_16x16x32_bf16 v[20:23], v[172:175], v[204:207], v[20:23]
	v_mfma_f32_16x16x32_bf16 v[16:19], v[180:183], v[204:207], v[16:19]
	v_mfma_f32_16x16x32_bf16 v[4:7], v[172:175], v[212:215], v[4:7]
	v_mfma_f32_16x16x32_bf16 v[0:3], v[180:183], v[212:215], v[0:3]
	s_setprio 0
	s_barrier
	s_movk_i32 s36, 0x100
	s_andn2_b64 vcc, exec, s[30:31]
	s_mov_b64 s[34:35], -1
	s_mov_b64 s[30:31], 0

;     __device__ bool next(int i, Unit& u) const { if (r0 + i >= r1) return false; return base.next(r0 + i, u); }
;     __device__ bool next(int i, Unit& u) const { const int L = i * G + c; if (L >= 256) return false; u.pm = L; u.pn = L >> 3; return true; }
; #define PG8_STAGE(bufoff, gbase, voff) do { _Pragma("unroll") for (int _i = 0; _i < 2; ++_i) \
;         __builtin_amdgcn_global_load_lds((const unsigned*)((const char*)(gbase) + (voff)[_i]), (LAS unsigned*)(lds + (bufoff) + ldsw + _i * 8192), 16, 0, 0); } while (0)
; #define PG8_LDA(dst, b, h) do { _Pragma("unroll") for (int m = 0; m < 4; ++m) _Pragma("unroll") for (int k = 0; k < 2; ++k) dst[m][k] = *(const LAS bf16x8*)(lds + PG8_SA(b, h) + aoff + m * 2048 + k * 1024); } while (0)
; #define PG8_LDB(dst, b, h) do { _Pragma("unroll") for (int n = 0; n < 2; ++n) _Pragma("unroll") for (int k = 0; k < 2; ++k) dst[n][k] = *(const LAS bf16x8*)(lds + PG8_SB(b, h) + boff + n * 2048 + k * 1024); } while (0)
; #define PG8_WAIT_V(n) asm volatile("s_waitcnt vmcnt(" #n ")" ::: "memory")
; #define PG8_WAIT_L(n) asm volatile("s_waitcnt lgkmcnt(" #n ")" ::: "memory")
; template <class Epi, class Sched>
; __device__ __forceinline__ void gemm_phase(LAS unsigned char* lds, const Gemm g, const Sched& S, const Epi& E, int wave_id) {
;     ...
;         const bool has_next = S.next(ui + 1, nxt);
;         const char* nA = has_next ? (const char*)g.A + (size_t)nxt.pm * tstepA : cA; const char* nB = has_next ? (const char*)g.Bt + (size_t)nxt.pn * tstepB : cB;
;         for (int t = 0; t < nt; t += 2) {
;             const bool last = (t == nt - 2);
;             const char* a1 = cA + (size_t)(t + 1) * kstep;
;             const char* a2 = last ? nA : cA + (size_t)(t + 2) * kstep; const char* b2 = last ? nB : cB + (size_t)(t + 2) * kstep;
;             const char* a3 = a2 + kstep; const char* b3 = b2 + kstep;
;             PG8_LDB(B0, 0, 0); PG8_LDB(B1, 0, 1); PG8_SCHED; PG8_LDA(At, 0, 0); PG8_STAGE(PG8_SA(1, 1), a1 + hstepA, voffA);
;             PG8_WAIT_V(8); PG8_WAIT_L(0); PG8_BAR; PG8_MMA(0, 0, At, B0); PG8_MMA(0, 1, At, B1); PG8_BAR; PG8_SCHED;
;             PG8_LDA(At, 0, 1); PG8_STAGE(PG8_SB(0, 0), b2, voffB); PG8_STAGE(PG8_SB(0, 1), b2 + hstepB, voffB); PG8_STAGE(PG8_SA(0, 0), a2, voffA);
;             PG8_WAIT_V(8); PG8_WAIT_L(0); PG8_BAR; PG8_MMA(1, 0, At, B0); PG8_MMA(1, 1, At, B1); PG8_BAR; PG8_SCHED;
.LBB0_1381:
	s_ashr_i32 s41, s40, 31
	s_lshl_b64 s[42:43], s[40:41], 19
	s_add_u32 s42, s16, s42
	s_addc_u32 s43, s17, s43
	s_and_b64 s[44:45], s[8:9], exec
	s_cselect_b32 s41, s43, s13
	s_cselect_b32 s50, s42, s12
	s_ashr_i32 s39, s38, 31
	s_lshl_b64 s[44:45], s[38:39], 19
	s_add_u32 s44, s3, s44
	s_addc_u32 s45, s33, s45
	s_and_b64 s[48:49], s[8:9], exec
	s_cselect_b32 s39, s45, s47
	s_cselect_b32 s51, s44, s46
	s_add_u32 s12, s12, 0x40080
	s_addc_u32 s13, s13, 0
	s_add_u32 s65, s46, 0x100
	s_addc_u32 s66, s47, 0
	s_mov_b32 s67, -2
	s_waitcnt vmcnt(0)
	ds_read_b128 v[8:11], v200
	ds_read_b128 v[12:15], v200 offset:1024
	ds_read_b128 v[16:19], v200 offset:2048
	ds_read_b128 v[20:23], v200 offset:3072
	ds_read_b128 v[144:147], v201
	ds_read_b128 v[148:151], v201 offset:1024
	ds_read_b128 v[176:179], v201 offset:2048
	ds_read_b128 v[180:183], v201 offset:3072
	s_add_u32 s46, s12, 0xfffc0080
	s_addc_u32 s47, s13, -1
	s_cmp_eq_u32 s67, 12
	s_cselect_b32 s49, s41, s47
	s_cselect_b32 s48, s50, s46
	s_cselect_b32 s47, s39, s66
	s_cselect_b32 s46, s51, s65
	v_lshl_add_u64 v[222:223], s[12:13], 0, v[168:169]
	s_add_i32 m0, s37, 0xc000
	ds_read_b128 v[184:187], v202
	ds_read_b128 v[188:191], v202 offset:1024
	ds_read_b128 v[192:195], v202 offset:2048
	ds_read_b128 v[196:199], v202 offset:3072
	ds_read_b128 v[206:209], v202 offset:4096
	ds_read_b128 v[210:213], v202 offset:5120
	ds_read_b128 v[214:217], v202 offset:6144
	ds_read_b128 v[218:221], v202 offset:7168
	global_load_lds_dwordx4 v[222:223], off
	v_lshl_add_u64 v[222:223], s[12:13], 0, v[170:171]
	s_add_i32 m0, s37, 0xe000
	s_nop 0
	global_load_lds_dwordx4 v[222:223], off
	s_waitcnt vmcnt(24)
	s_waitcnt lgkmcnt(0)
	s_barrier
	s_setprio 1
	s_waitcnt lgkmcnt(0)
	v_mfma_f32_16x16x32_bf16 v[140:143], v[8:11], v[184:187], 0
	v_mfma_f32_16x16x32_bf16 v[136:139], v[16:19], v[184:187], 0
	v_mfma_f32_16x16x32_bf16 v[124:127], v[8:11], v[192:195], 0
	v_mfma_f32_16x16x32_bf16 v[120:123], v[16:19], v[192:195], 0
	v_mfma_f32_16x16x32_bf16 v[108:111], v[8:11], v[206:209], 0
	v_mfma_f32_16x16x32_bf16 v[104:107], v[16:19], v[206:209], 0
	v_mfma_f32_16x16x32_bf16 v[92:95], v[8:11], v[214:217], 0
	v_mfma_f32_16x16x32_bf16 v[88:91], v[16:19], v[214:217], 0
	v_mfma_f32_16x16x32_bf16 v[140:143], v[12:15], v[188:191], v[140:143]
	v_mfma_f32_16x16x32_bf16 v[136:139], v[20:23], v[188:191], v[136:139]
	v_mfma_f32_16x16x32_bf16 v[124:127], v[12:15], v[196:199], v[124:127]
	v_mfma_f32_16x16x32_bf16 v[120:123], v[20:23], v[196:199], v[120:123]
	v_mfma_f32_16x16x32_bf16 v[108:111], v[12:15], v[210:213], v[108:111]
	v_mfma_f32_16x16x32_bf16 v[104:107], v[20:23], v[210:213], v[104:107]
	v_mfma_f32_16x16x32_bf16 v[92:95], v[12:15], v[218:221], v[92:95]
	v_mfma_f32_16x16x32_bf16 v[88:91], v[20:23], v[218:221], v[88:91]
	s_setprio 0
	s_setprio 1
	v_mfma_f32_16x16x32_bf16 v[132:135], v[144:147], v[184:187], 0
	v_mfma_f32_16x16x32_bf16 v[128:131], v[176:179], v[184:187], 0
	v_mfma_f32_16x16x32_bf16 v[116:119], v[144:147], v[192:195], 0
	v_mfma_f32_16x16x32_bf16 v[112:115], v[176:179], v[192:195], 0
	v_mfma_f32_16x16x32_bf16 v[100:103], v[144:147], v[206:209], 0
	v_mfma_f32_16x16x32_bf16 v[96:99], v[176:179], v[206:209], 0
	v_mfma_f32_16x16x32_bf16 v[84:87], v[144:147], v[214:217], 0
	v_mfma_f32_16x16x32_bf16 v[80:83], v[176:179], v[214:217], 0
	v_mfma_f32_16x16x32_bf16 v[132:135], v[148:151], v[188:191], v[132:135]
	v_mfma_f32_16x16x32_bf16 v[128:131], v[180:183], v[188:191], v[128:131]
	v_mfma_f32_16x16x32_bf16 v[116:119], v[148:151], v[196:199], v[116:119]
	v_mfma_f32_16x16x32_bf16 v[112:115], v[180:183], v[196:199], v[112:115]
	v_mfma_f32_16x16x32_bf16 v[100:103], v[148:151], v[210:213], v[100:103]
	v_mfma_f32_16x16x32_bf16 v[96:99], v[180:183], v[210:213], v[96:99]
	v_mfma_f32_16x16x32_bf16 v[84:87], v[148:151], v[218:221], v[84:87]
	v_mfma_f32_16x16x32_bf16 v[80:83], v[180:183], v[218:221], v[80:83]
	s_setprio 0
	s_barrier
	s_add_i32 s72, s61, s35
	v_lshl_add_u64 v[222:223], s[46:47], 0, v[154:155]
	s_mov_b32 m0, s72
	ds_read_b128 v[184:187], v202 offset:16384
	ds_read_b128 v[188:191], v202 offset:17408
	ds_read_b128 v[192:195], v202 offset:18432
	ds_read_b128 v[196:199], v202 offset:19456
	ds_read_b128 v[206:209], v202 offset:20480
	ds_read_b128 v[210:213], v202 offset:21504
	ds_read_b128 v[214:217], v202 offset:22528
	ds_read_b128 v[218:221], v202 offset:23552
	global_load_lds_dwordx4 v[222:223], off
	s_add_i32 m0, s72, 0x2000
	s_add_u32 s72, s46, 0x40000
	v_lshl_add_u64 v[224:225], s[46:47], 0, v[158:159]
	s_addc_u32 s73, s47, 0
	s_add_i32 s74, s62, s35
	global_load_lds_dwordx4 v[224:225], off
	v_lshl_add_u64 v[226:227], s[72:73], 0, v[154:155]
	s_mov_b32 m0, s74
	v_lshl_add_u64 v[228:229], s[48:49], 0, v[156:157]
	global_load_lds_dwordx4 v[226:227], off
	v_lshl_add_u64 v[226:227], s[72:73], 0, v[158:159]
	s_add_i32 m0, s74, 0x2000
	s_nop 0
	global_load_lds_dwordx4 v[226:227], off
	v_lshl_add_u64 v[226:227], s[48:49], 0, v[152:153]
	s_mov_b32 m0, s37
	s_nop 0
	global_load_lds_dwordx4 v[226:227], off
	s_mov_b32 m0, s52
	s_nop 0
	global_load_lds_dwordx4 v[228:229], off
	s_waitcnt vmcnt(8)
	s_waitcnt lgkmcnt(0)
	s_barrier
; #define PG8_STAGE(bufoff, gbase, voff) do { _Pragma("unroll") for (int _i = 0; _i < 2; ++_i) \
;         __builtin_amdgcn_global_load_lds((const unsigned*)((const char*)(gbase) + (voff)[_i]), (LAS unsigned*)(lds + (bufoff) + ldsw + _i * 8192), 16, 0, 0); } while (0)
; #define PG8_LDA(dst, b, h) do { _Pragma("unroll") for (int m = 0; m < 4; ++m) _Pragma("unroll") for (int k = 0; k < 2; ++k) dst[m][k] = *(const LAS bf16x8*)(lds + PG8_SA(b, h) + aoff + m * 2048 + k * 1024); } while (0)
; #define PG8_LDB(dst, b, h) do { _Pragma("unroll") for (int n = 0; n < 2; ++n) _Pragma("unroll") for (int k = 0; k < 2; ++k) dst[n][k] = *(const LAS bf16x8*)(lds + PG8_SB(b, h) + boff + n * 2048 + k * 1024); } while (0)
; #define PG8_MMA(ai, bj, At, Bt) do { __builtin_amdgcn_s_setprio(1); _Pragma("unroll") for (int m = 0; m < 4; ++m) _Pragma("unroll") for (int n = 0; n < 2; ++n) _Pragma("unroll") for (int k = 0; k < 2; ++k) \
;         acc[ai][bj][m][n] = __builtin_amdgcn_mfma_f32_16x16x32_bf16(Bt[n][k], At[m][k], acc[ai][bj][m][n], 0, 0, 0); __builtin_amdgcn_s_setprio(0); } while (0)
; #define PG8_WAIT_V(n) asm volatile("s_waitcnt vmcnt(" #n ")" ::: "memory")
; #define PG8_WAIT_L(n) asm volatile("s_waitcnt lgkmcnt(" #n ")" ::: "memory")
; #define PG8_BAR __builtin_amdgcn_s_barrier()
; #define PG8_SCHED __builtin_amdgcn_sched_barrier(0)
; template <class Epi, class Sched>
; __device__ __forceinline__ void gemm_phase(LAS unsigned char* lds, const Gemm g, const Sched& S, const Epi& E, int wave_id) {
;     ...
;             PG8_WAIT_V(8); PG8_WAIT_L(0); PG8_BAR; PG8_MMA(1, 0, At, B0); PG8_MMA(1, 1, At, B1); PG8_BAR; PG8_SCHED;
;             PG8_LDB(B0, 1, 0); PG8_LDB(B1, 1, 1); PG8_SCHED; PG8_LDA(At, 1, 0); PG8_STAGE(PG8_SA(0, 1), a2 + hstepA, voffA);
;             PG8_WAIT_V(8); PG8_WAIT_L(0); PG8_BAR; PG8_MMA(0, 0, At, B0); PG8_MMA(0, 1, At, B1); PG8_BAR; PG8_SCHED;
	s_setprio 1
	s_waitcnt lgkmcnt(0)
	v_mfma_f32_16x16x32_bf16 v[76:79], v[8:11], v[184:187], 0
	v_mfma_f32_16x16x32_bf16 v[72:75], v[16:19], v[184:187], 0
	v_mfma_f32_16x16x32_bf16 v[60:63], v[8:11], v[192:195], 0
	v_mfma_f32_16x16x32_bf16 v[56:59], v[16:19], v[192:195], 0
	v_mfma_f32_16x16x32_bf16 v[44:47], v[8:11], v[206:209], 0
	v_mfma_f32_16x16x32_bf16 v[40:43], v[16:19], v[206:209], 0
	v_mfma_f32_16x16x32_bf16 v[8:11], v[8:11], v[214:217], 0
	v_mfma_f32_16x16x32_bf16 v[76:79], v[12:15], v[188:191], v[76:79]
	v_mfma_f32_16x16x32_bf16 v[72:75], v[20:23], v[188:191], v[72:75]
	v_mfma_f32_16x16x32_bf16 v[60:63], v[12:15], v[196:199], v[60:63]
	v_mfma_f32_16x16x32_bf16 v[56:59], v[20:23], v[196:199], v[56:59]
	v_mfma_f32_16x16x32_bf16 v[44:47], v[12:15], v[210:213], v[44:47]
	v_mfma_f32_16x16x32_bf16 v[40:43], v[20:23], v[210:213], v[40:43]
	v_mfma_f32_16x16x32_bf16 v[8:11], v[12:15], v[218:221], v[8:11]
	v_mfma_f32_16x16x32_bf16 v[12:15], v[16:19], v[214:217], 0
	v_mfma_f32_16x16x32_bf16 v[12:15], v[20:23], v[218:221], v[12:15]
	s_setprio 0
	s_setprio 1
	v_mfma_f32_16x16x32_bf16 v[24:27], v[144:147], v[192:195], 0
	v_mfma_f32_16x16x32_bf16 v[52:55], v[148:151], v[196:199], v[24:27]
	v_mfma_f32_16x16x32_bf16 v[24:27], v[176:179], v[192:195], 0
	v_mfma_f32_16x16x32_bf16 v[48:51], v[180:183], v[196:199], v[24:27]
	v_mfma_f32_16x16x32_bf16 v[24:27], v[144:147], v[206:209], 0
	v_mfma_f32_16x16x32_bf16 v[36:39], v[148:151], v[210:213], v[24:27]
	v_mfma_f32_16x16x32_bf16 v[24:27], v[176:179], v[206:209], 0
	v_mfma_f32_16x16x32_bf16 v[4:7], v[144:147], v[214:217], 0
	v_mfma_f32_16x16x32_bf16 v[0:3], v[176:179], v[214:217], 0
	v_mfma_f32_16x16x32_bf16 v[16:19], v[144:147], v[184:187], 0
	v_mfma_f32_16x16x32_bf16 v[20:23], v[176:179], v[184:187], 0
	v_mfma_f32_16x16x32_bf16 v[32:35], v[180:183], v[210:213], v[24:27]
	v_mfma_f32_16x16x32_bf16 v[4:7], v[148:151], v[218:221], v[4:7]
	v_mfma_f32_16x16x32_bf16 v[0:3], v[180:183], v[218:221], v[0:3]
	v_mfma_f32_16x16x32_bf16 v[16:19], v[148:151], v[188:191], v[16:19]
	v_mfma_f32_16x16x32_bf16 v[20:23], v[180:183], v[188:191], v[20:23]
	s_setprio 0
	s_barrier
	s_add_i32 s72, 0, 0x18000
	s_add_i32 s73, 0, 0x1c000
	v_add_u32_e32 v68, s72, v165
	v_add_u32_e32 v180, s73, v165
	ds_read_b128 v[24:27], v68
	ds_read_b128 v[28:31], v68 offset:1024
	ds_read_b128 v[64:67], v68 offset:2048
	ds_read_b128 v[68:71], v68 offset:3072
	ds_read_b128 v[144:147], v180
	ds_read_b128 v[148:151], v180 offset:1024
	ds_read_b128 v[176:179], v180 offset:2048
	ds_read_b128 v[180:183], v180 offset:3072
	s_add_u32 s48, s48, 0x40000
	s_addc_u32 s49, s49, 0
	s_mov_b32 m0, s53
	v_lshl_add_u64 v[230:231], s[48:49], 0, v[152:153]
	ds_read_b128 v[184:187], v202 offset:32768
	ds_read_b128 v[188:191], v202 offset:33792
	ds_read_b128 v[192:195], v202 offset:34816
	ds_read_b128 v[196:199], v202 offset:35840
	ds_read_b128 v[206:209], v202 offset:36864
	ds_read_b128 v[210:213], v202 offset:37888
	ds_read_b128 v[214:217], v202 offset:38912
	ds_read_b128 v[218:221], v202 offset:39936
	global_load_lds_dwordx4 v[230:231], off
	v_lshl_add_u64 v[230:231], s[48:49], 0, v[156:157]
	s_mov_b32 m0, s54
	s_nop 0
	global_load_lds_dwordx4 v[230:231], off
	s_waitcnt vmcnt(8)
	s_waitcnt lgkmcnt(0)
	s_barrier
	s_setprio 1
	s_waitcnt lgkmcnt(0)
	v_mfma_f32_16x16x32_bf16 v[140:143], v[24:27], v[184:187], v[140:143]
	v_mfma_f32_16x16x32_bf16 v[136:139], v[64:67], v[184:187], v[136:139]
	v_mfma_f32_16x16x32_bf16 v[124:127], v[24:27], v[192:195], v[124:127]
	v_mfma_f32_16x16x32_bf16 v[120:123], v[64:67], v[192:195], v[120:123]
	v_mfma_f32_16x16x32_bf16 v[108:111], v[24:27], v[206:209], v[108:111]
	v_mfma_f32_16x16x32_bf16 v[104:107], v[64:67], v[206:209], v[104:107]
	v_mfma_f32_16x16x32_bf16 v[92:95], v[24:27], v[214:217], v[92:95]
	v_mfma_f32_16x16x32_bf16 v[88:91], v[64:67], v[214:217], v[88:91]
	v_mfma_f32_16x16x32_bf16 v[140:143], v[28:31], v[188:191], v[140:143]
	v_mfma_f32_16x16x32_bf16 v[136:139], v[68:71], v[188:191], v[136:139]
	v_mfma_f32_16x16x32_bf16 v[124:127], v[28:31], v[196:199], v[124:127]
	v_mfma_f32_16x16x32_bf16 v[120:123], v[68:71], v[196:199], v[120:123]
	v_mfma_f32_16x16x32_bf16 v[108:111], v[28:31], v[210:213], v[108:111]
	v_mfma_f32_16x16x32_bf16 v[104:107], v[68:71], v[210:213], v[104:107]
	v_mfma_f32_16x16x32_bf16 v[92:95], v[28:31], v[218:221], v[92:95]
	v_mfma_f32_16x16x32_bf16 v[88:91], v[68:71], v[218:221], v[88:91]
	s_setprio 0
	s_setprio 1
	v_mfma_f32_16x16x32_bf16 v[132:135], v[144:147], v[184:187], v[132:135]
	v_mfma_f32_16x16x32_bf16 v[128:131], v[176:179], v[184:187], v[128:131]
	v_mfma_f32_16x16x32_bf16 v[116:119], v[144:147], v[192:195], v[116:119]
	v_mfma_f32_16x16x32_bf16 v[112:115], v[176:179], v[192:195], v[112:115]
	v_mfma_f32_16x16x32_bf16 v[100:103], v[144:147], v[206:209], v[100:103]
	v_mfma_f32_16x16x32_bf16 v[96:99], v[176:179], v[206:209], v[96:99]
	v_mfma_f32_16x16x32_bf16 v[84:87], v[144:147], v[214:217], v[84:87]
	v_mfma_f32_16x16x32_bf16 v[80:83], v[176:179], v[214:217], v[80:83]
	v_mfma_f32_16x16x32_bf16 v[132:135], v[148:151], v[188:191], v[132:135]
	v_mfma_f32_16x16x32_bf16 v[128:131], v[180:183], v[188:191], v[128:131]
	v_mfma_f32_16x16x32_bf16 v[116:119], v[148:151], v[196:199], v[116:119]
	v_mfma_f32_16x16x32_bf16 v[112:115], v[180:183], v[196:199], v[112:115]
	v_mfma_f32_16x16x32_bf16 v[100:103], v[148:151], v[210:213], v[100:103]
	v_mfma_f32_16x16x32_bf16 v[96:99], v[180:183], v[210:213], v[96:99]
	v_mfma_f32_16x16x32_bf16 v[84:87], v[148:151], v[218:221], v[84:87]
	v_mfma_f32_16x16x32_bf16 v[80:83], v[180:183], v[218:221], v[80:83]
	s_setprio 0
	s_barrier
; #define PG8_STAGE(bufoff, gbase, voff) do { _Pragma("unroll") for (int _i = 0; _i < 2; ++_i) \
;         __builtin_amdgcn_global_load_lds((const unsigned*)((const char*)(gbase) + (voff)[_i]), (LAS unsigned*)(lds + (bufoff) + ldsw + _i * 8192), 16, 0, 0); } while (0)
; #define PG8_LDA(dst, b, h) do { _Pragma("unroll") for (int m = 0; m < 4; ++m) _Pragma("unroll") for (int k = 0; k < 2; ++k) dst[m][k] = *(const LAS bf16x8*)(lds + PG8_SA(b, h) + aoff + m * 2048 + k * 1024); } while (0)
; #define PG8_MMA(ai, bj, At, Bt) do { __builtin_amdgcn_s_setprio(1); _Pragma("unroll") for (int m = 0; m < 4; ++m) _Pragma("unroll") for (int n = 0; n < 2; ++n) _Pragma("unroll") for (int k = 0; k < 2; ++k) \
;         acc[ai][bj][m][n] = __builtin_amdgcn_mfma_f32_16x16x32_bf16(Bt[n][k], At[m][k], acc[ai][bj][m][n], 0, 0, 0); __builtin_amdgcn_s_setprio(0); } while (0)
; #define PG8_WAIT_V(n) asm volatile("s_waitcnt vmcnt(" #n ")" ::: "memory")
; #define PG8_WAIT_L(n) asm volatile("s_waitcnt lgkmcnt(" #n ")" ::: "memory")
; #define PG8_BAR __builtin_amdgcn_s_barrier()
; #define PG8_SCHED __builtin_amdgcn_sched_barrier(0)
; template <class Epi, class Sched>
; __device__ __forceinline__ void gemm_phase(LAS unsigned char* lds, const Gemm g, const Sched& S, const Epi& E, int wave_id) {
;     ...
;             PG8_LDA(At, 1, 1); PG8_STAGE(PG8_SB(1, 0), b3, voffB); PG8_STAGE(PG8_SB(1, 1), b3 + hstepB, voffB); PG8_STAGE(PG8_SA(1, 0), a3, voffA);
;             PG8_WAIT_V(8); PG8_WAIT_L(0); PG8_BAR; PG8_MMA(1, 0, At, B0); PG8_MMA(1, 1, At, B1); PG8_BAR; PG8_SCHED;
;         }
	s_add_i32 s48, s72, s35
	v_lshl_add_u64 v[222:223], v[222:223], 0, s[22:23]
	s_mov_b32 m0, s48
	ds_read_b128 v[184:187], v202 offset:49152
	ds_read_b128 v[188:191], v202 offset:50176
	ds_read_b128 v[192:195], v202 offset:51200
	ds_read_b128 v[196:199], v202 offset:52224
	ds_read_b128 v[206:209], v202 offset:53248
	ds_read_b128 v[210:213], v202 offset:54272
	ds_read_b128 v[214:217], v202 offset:55296
	ds_read_b128 v[218:221], v202 offset:56320
	global_load_lds_dwordx4 v[222:223], off
	s_add_i32 m0, s48, 0x2000
	s_add_u32 s46, s46, 0x40080
	v_lshl_add_u64 v[222:223], v[224:225], 0, s[22:23]
	s_addc_u32 s47, s47, 0
	s_add_i32 s48, s73, s35
	global_load_lds_dwordx4 v[222:223], off
	v_lshl_add_u64 v[222:223], s[46:47], 0, v[154:155]
	s_mov_b32 m0, s48
	s_nop 0
	global_load_lds_dwordx4 v[222:223], off
	v_lshl_add_u64 v[222:223], s[46:47], 0, v[158:159]
	s_add_i32 m0, s48, 0x2000
	s_nop 0
	global_load_lds_dwordx4 v[222:223], off
	v_lshl_add_u64 v[222:223], v[226:227], 0, s[22:23]
	s_mov_b32 m0, s55
	s_nop 0
	global_load_lds_dwordx4 v[222:223], off
	v_lshl_add_u64 v[222:223], v[228:229], 0, s[22:23]
	s_mov_b32 m0, s56
	s_nop 0
	global_load_lds_dwordx4 v[222:223], off
	s_waitcnt vmcnt(8)
	s_waitcnt lgkmcnt(0)
	s_barrier
	s_setprio 1
	s_waitcnt lgkmcnt(0)
	v_mfma_f32_16x16x32_bf16 v[76:79], v[24:27], v[184:187], v[76:79]
	v_mfma_f32_16x16x32_bf16 v[60:63], v[24:27], v[192:195], v[60:63]
	v_mfma_f32_16x16x32_bf16 v[44:47], v[24:27], v[206:209], v[44:47]
	v_mfma_f32_16x16x32_bf16 v[8:11], v[24:27], v[214:217], v[8:11]
	v_mfma_f32_16x16x32_bf16 v[76:79], v[28:31], v[188:191], v[76:79]
	v_mfma_f32_16x16x32_bf16 v[72:75], v[64:67], v[184:187], v[72:75]
	v_mfma_f32_16x16x32_bf16 v[60:63], v[28:31], v[196:199], v[60:63]
	v_mfma_f32_16x16x32_bf16 v[56:59], v[64:67], v[192:195], v[56:59]
	v_mfma_f32_16x16x32_bf16 v[44:47], v[28:31], v[210:213], v[44:47]
	v_mfma_f32_16x16x32_bf16 v[40:43], v[64:67], v[206:209], v[40:43]
	v_mfma_f32_16x16x32_bf16 v[28:31], v[28:31], v[218:221], v[8:11]
	v_mfma_f32_16x16x32_bf16 v[8:11], v[64:67], v[214:217], v[12:15]
	v_mfma_f32_16x16x32_bf16 v[72:75], v[68:71], v[188:191], v[72:75]
	v_mfma_f32_16x16x32_bf16 v[56:59], v[68:71], v[196:199], v[56:59]
	v_mfma_f32_16x16x32_bf16 v[40:43], v[68:71], v[210:213], v[40:43]
	v_mfma_f32_16x16x32_bf16 v[24:27], v[68:71], v[218:221], v[8:11]
	s_setprio 0
	s_setprio 1
	v_mfma_f32_16x16x32_bf16 v[8:11], v[144:147], v[184:187], v[16:19]
	v_mfma_f32_16x16x32_bf16 v[68:71], v[148:151], v[188:191], v[8:11]
	v_mfma_f32_16x16x32_bf16 v[8:11], v[176:179], v[184:187], v[20:23]
	v_mfma_f32_16x16x32_bf16 v[64:67], v[180:183], v[188:191], v[8:11]
	v_mfma_f32_16x16x32_bf16 v[8:11], v[144:147], v[192:195], v[52:55]
	v_mfma_f32_16x16x32_bf16 v[52:55], v[148:151], v[196:199], v[8:11]
	v_mfma_f32_16x16x32_bf16 v[8:11], v[176:179], v[192:195], v[48:51]
	v_mfma_f32_16x16x32_bf16 v[48:51], v[180:183], v[196:199], v[8:11]
	v_mfma_f32_16x16x32_bf16 v[8:11], v[144:147], v[206:209], v[36:39]
	v_mfma_f32_16x16x32_bf16 v[36:39], v[148:151], v[210:213], v[8:11]
	v_mfma_f32_16x16x32_bf16 v[8:11], v[176:179], v[206:209], v[32:35]
	v_mfma_f32_16x16x32_bf16 v[4:7], v[144:147], v[214:217], v[4:7]
	v_mfma_f32_16x16x32_bf16 v[0:3], v[176:179], v[214:217], v[0:3]
	v_mfma_f32_16x16x32_bf16 v[32:35], v[180:183], v[210:213], v[8:11]
	v_mfma_f32_16x16x32_bf16 v[4:7], v[148:151], v[218:221], v[4:7]
	v_mfma_f32_16x16x32_bf16 v[0:3], v[180:183], v[218:221], v[0:3]
	s_setprio 0
	s_barrier
	s_add_i32 s67, s67, 2
	s_add_u32 s12, s12, 0x100
	s_addc_u32 s13, s13, 0
	s_add_u32 s65, s65, 0x100
	s_addc_u32 s66, s66, 0
	s_cmp_gt_u32 s67, 13
